# QK^T segments of FoX/diff/cross attention loops re-emitted with a 5-deep ring of K-fragment registers (v228-239, v248-255): LDS reads issued 5 MFMAs ahead with counted lgkmcnt waits
# baseline (speedup 1.0000x reference)
.LBB0_291:
	s_ashr_i32 s5, s4, 31
	s_lshl_b64 s[28:29], s[4:5], 20
	s_add_u32 s28, s14, s28
	s_addc_u32 s29, s15, s29
	s_and_b64 s[34:35], s[22:23], exec
	s_cselect_b32 s5, s29, s37
	s_cselect_b32 s8, s28, s36
	s_ashr_i32 s19, s18, 31
	s_lshl_b64 s[34:35], s[18:19], 20
	v_readlane_b32 s19, v245, 38
	s_add_u32 s34, s19, s34
	v_readlane_b32 s19, v245, 39
	s_addc_u32 s35, s19, s35
	s_and_b64 s[44:45], s[22:23], exec
	s_cselect_b32 s19, s35, s43
	s_cselect_b32 s21, s34, s42
	s_add_u32 s36, s36, 0x80080
	s_addc_u32 s37, s37, 0
	s_add_u32 s41, s42, 0x100
	v_mov_b32_e32 v2, 0
	s_addc_u32 s46, s43, 0
	s_mov_b32 s47, -2
	v_mov_b32_e32 v3, v2
	v_mov_b32_e32 v4, v2
	v_mov_b32_e32 v5, v2
	v_mov_b32_e32 v6, v2
	v_mov_b32_e32 v7, v2
	v_mov_b32_e32 v8, v2
	v_mov_b32_e32 v9, v2
	s_waitcnt vmcnt(0) lgkmcnt(0)
	v_mov_b32_e32 v18, v2
	v_mov_b32_e32 v19, v2
	v_mov_b32_e32 v20, v2
	v_mov_b32_e32 v21, v2
	v_mov_b32_e32 v22, v2
	v_mov_b32_e32 v23, v2
	v_mov_b32_e32 v24, v2
	v_mov_b32_e32 v25, v2
	v_mov_b32_e32 v34, v2
	v_mov_b32_e32 v35, v2
	v_mov_b32_e32 v36, v2
	v_mov_b32_e32 v37, v2
	v_mov_b32_e32 v38, v2
	v_mov_b32_e32 v39, v2
	v_mov_b32_e32 v40, v2
	v_mov_b32_e32 v41, v2
	v_mov_b32_e32 v50, v2
	v_mov_b32_e32 v51, v2
	v_mov_b32_e32 v52, v2
	v_mov_b32_e32 v53, v2
	v_mov_b32_e32 v54, v2
	v_mov_b32_e32 v55, v2
	v_mov_b32_e32 v56, v2
	v_mov_b32_e32 v57, v2
	v_mov_b32_e32 v10, v2
	v_mov_b32_e32 v11, v2
	v_mov_b32_e32 v12, v2
	v_mov_b32_e32 v13, v2
	v_mov_b32_e32 v14, v2
	v_mov_b32_e32 v15, v2
	v_mov_b32_e32 v16, v2
	v_mov_b32_e32 v17, v2
	v_mov_b32_e32 v26, v2
	v_mov_b32_e32 v27, v2
	v_mov_b32_e32 v28, v2
	v_mov_b32_e32 v29, v2
	v_mov_b32_e32 v30, v2
	v_mov_b32_e32 v31, v2
	v_mov_b32_e32 v32, v2
	v_mov_b32_e32 v33, v2
	v_mov_b32_e32 v42, v2
	v_mov_b32_e32 v43, v2
	v_mov_b32_e32 v44, v2
	v_mov_b32_e32 v45, v2
	v_mov_b32_e32 v46, v2
	v_mov_b32_e32 v47, v2
	v_mov_b32_e32 v48, v2
	v_mov_b32_e32 v49, v2
	v_mov_b32_e32 v58, v2
	v_mov_b32_e32 v59, v2
	v_mov_b32_e32 v60, v2
	v_mov_b32_e32 v61, v2
	v_mov_b32_e32 v62, v2
	v_mov_b32_e32 v63, v2
	v_mov_b32_e32 v64, v2
	v_mov_b32_e32 v65, v2
	v_mov_b32_e32 v66, v2
	v_mov_b32_e32 v67, v2
	v_mov_b32_e32 v68, v2
	v_mov_b32_e32 v69, v2
	v_mov_b32_e32 v70, v2
	v_mov_b32_e32 v71, v2
	v_mov_b32_e32 v72, v2
	v_mov_b32_e32 v73, v2
	v_mov_b32_e32 v82, v2
	v_mov_b32_e32 v83, v2
	v_mov_b32_e32 v84, v2
	v_mov_b32_e32 v85, v2
	v_mov_b32_e32 v86, v2
	v_mov_b32_e32 v87, v2
	v_mov_b32_e32 v88, v2
	v_mov_b32_e32 v89, v2
	v_mov_b32_e32 v98, v2
	v_mov_b32_e32 v99, v2
	v_mov_b32_e32 v100, v2
	v_mov_b32_e32 v101, v2
	v_mov_b32_e32 v102, v2
	v_mov_b32_e32 v103, v2
	v_mov_b32_e32 v104, v2
	v_mov_b32_e32 v105, v2
	v_mov_b32_e32 v114, v2
	v_mov_b32_e32 v115, v2
	v_mov_b32_e32 v116, v2
	v_mov_b32_e32 v117, v2
	v_mov_b32_e32 v118, v2
	v_mov_b32_e32 v119, v2
	v_mov_b32_e32 v120, v2
	v_mov_b32_e32 v121, v2
	v_mov_b32_e32 v74, v2
	v_mov_b32_e32 v75, v2
	v_mov_b32_e32 v76, v2
	v_mov_b32_e32 v77, v2
	v_mov_b32_e32 v78, v2
	v_mov_b32_e32 v79, v2
	v_mov_b32_e32 v80, v2
	v_mov_b32_e32 v81, v2
	v_mov_b32_e32 v90, v2
	v_mov_b32_e32 v91, v2
	v_mov_b32_e32 v92, v2
	v_mov_b32_e32 v93, v2
	v_mov_b32_e32 v94, v2
	v_mov_b32_e32 v95, v2
	v_mov_b32_e32 v96, v2
	v_mov_b32_e32 v97, v2
	v_mov_b32_e32 v106, v2
	v_mov_b32_e32 v107, v2
	v_mov_b32_e32 v108, v2
	v_mov_b32_e32 v109, v2
	v_mov_b32_e32 v110, v2
	v_mov_b32_e32 v111, v2
	v_mov_b32_e32 v112, v2
	v_mov_b32_e32 v113, v2
	v_mov_b32_e32 v122, v2
	v_mov_b32_e32 v123, v2
	v_mov_b32_e32 v124, v2
	v_mov_b32_e32 v125, v2
	v_mov_b32_e32 v126, v2
	v_mov_b32_e32 v127, v2
	v_mov_b32_e32 v128, v2
	v_mov_b32_e32 v129, v2

.LBB0_357:
	s_ashr_i32 s19, s18, 31
	s_lshl_b64 s[8:9], s[18:19], 20
	v_readlane_b32 s5, v243, 17
	s_add_u32 s28, s5, s8
	v_readlane_b32 s5, v243, 18
	s_addc_u32 s29, s5, s9
	s_and_b64 s[8:9], s[34:35], exec
	s_cselect_b32 s8, s29, s37
	s_cselect_b32 s9, s28, s36
	s_ashr_i32 s5, s4, 31
	s_lshl_b64 s[20:21], s[4:5], 20
	s_add_u32 s38, s30, s20
	v_readlane_b32 s5, v242, 4
	s_addc_u32 s39, s5, s21
	s_and_b64 s[20:21], s[34:35], exec
	s_cselect_b32 s5, s39, s43
	s_cselect_b32 s11, s38, s42
	s_add_u32 s36, s36, 0x80080
	s_addc_u32 s37, s37, 0
	s_add_u32 s13, s42, 0x100
	v_mov_b32_e32 v2, 0
	s_addc_u32 s19, s43, 0
	s_mov_b32 s20, -2
	v_mov_b32_e32 v3, v2
	v_mov_b32_e32 v4, v2
	v_mov_b32_e32 v5, v2
	v_mov_b32_e32 v6, v2
	v_mov_b32_e32 v7, v2
	v_mov_b32_e32 v8, v2
	v_mov_b32_e32 v9, v2
	s_waitcnt vmcnt(0)
	v_mov_b32_e32 v18, v2
	v_mov_b32_e32 v19, v2
	v_mov_b32_e32 v20, v2
	v_mov_b32_e32 v21, v2
	v_mov_b32_e32 v22, v2
	v_mov_b32_e32 v23, v2
	v_mov_b32_e32 v24, v2
	v_mov_b32_e32 v25, v2
	v_mov_b32_e32 v34, v2
	v_mov_b32_e32 v35, v2
	v_mov_b32_e32 v36, v2
	v_mov_b32_e32 v37, v2
	v_mov_b32_e32 v38, v2
	v_mov_b32_e32 v39, v2
	v_mov_b32_e32 v40, v2
	v_mov_b32_e32 v41, v2
	v_mov_b32_e32 v50, v2
	v_mov_b32_e32 v51, v2
	v_mov_b32_e32 v52, v2
	v_mov_b32_e32 v53, v2
	v_mov_b32_e32 v54, v2
	v_mov_b32_e32 v55, v2
	v_mov_b32_e32 v56, v2
	v_mov_b32_e32 v57, v2
	v_mov_b32_e32 v10, v2
	v_mov_b32_e32 v11, v2
	v_mov_b32_e32 v12, v2
	v_mov_b32_e32 v13, v2
	v_mov_b32_e32 v14, v2
	v_mov_b32_e32 v15, v2
	v_mov_b32_e32 v16, v2
	v_mov_b32_e32 v17, v2
	v_mov_b32_e32 v26, v2
	v_mov_b32_e32 v27, v2
	v_mov_b32_e32 v28, v2
	v_mov_b32_e32 v29, v2
	v_mov_b32_e32 v30, v2
	v_mov_b32_e32 v31, v2
	v_mov_b32_e32 v32, v2
	v_mov_b32_e32 v33, v2
	v_mov_b32_e32 v42, v2
	v_mov_b32_e32 v43, v2
	v_mov_b32_e32 v44, v2
	v_mov_b32_e32 v45, v2
	v_mov_b32_e32 v46, v2
	v_mov_b32_e32 v47, v2
	v_mov_b32_e32 v48, v2
	v_mov_b32_e32 v49, v2
	v_mov_b32_e32 v58, v2
	v_mov_b32_e32 v59, v2
	v_mov_b32_e32 v60, v2
	v_mov_b32_e32 v61, v2
	v_mov_b32_e32 v62, v2
	v_mov_b32_e32 v63, v2
	v_mov_b32_e32 v64, v2
	v_mov_b32_e32 v65, v2
	v_mov_b32_e32 v66, v2
	v_mov_b32_e32 v67, v2
	v_mov_b32_e32 v68, v2
	v_mov_b32_e32 v69, v2
	v_mov_b32_e32 v70, v2
	v_mov_b32_e32 v71, v2
	v_mov_b32_e32 v72, v2
	v_mov_b32_e32 v73, v2
	v_mov_b32_e32 v82, v2
	v_mov_b32_e32 v83, v2
	v_mov_b32_e32 v84, v2
	v_mov_b32_e32 v85, v2
	v_mov_b32_e32 v86, v2
	v_mov_b32_e32 v87, v2
	v_mov_b32_e32 v88, v2
	v_mov_b32_e32 v89, v2
	v_mov_b32_e32 v98, v2
	v_mov_b32_e32 v99, v2
	v_mov_b32_e32 v100, v2
	v_mov_b32_e32 v101, v2
	v_mov_b32_e32 v102, v2
	v_mov_b32_e32 v103, v2
	v_mov_b32_e32 v104, v2
	v_mov_b32_e32 v105, v2
	v_mov_b32_e32 v114, v2
	v_mov_b32_e32 v115, v2
	v_mov_b32_e32 v116, v2
	v_mov_b32_e32 v117, v2
	v_mov_b32_e32 v118, v2
	v_mov_b32_e32 v119, v2
	v_mov_b32_e32 v120, v2
	v_mov_b32_e32 v121, v2
	v_mov_b32_e32 v74, v2
	v_mov_b32_e32 v75, v2
	v_mov_b32_e32 v76, v2
	v_mov_b32_e32 v77, v2
	v_mov_b32_e32 v78, v2
	v_mov_b32_e32 v79, v2
	v_mov_b32_e32 v80, v2
	v_mov_b32_e32 v81, v2
	v_mov_b32_e32 v90, v2
	v_mov_b32_e32 v91, v2
	v_mov_b32_e32 v92, v2
	v_mov_b32_e32 v93, v2
	v_mov_b32_e32 v94, v2
	v_mov_b32_e32 v95, v2
	v_mov_b32_e32 v96, v2
	v_mov_b32_e32 v97, v2
	v_mov_b32_e32 v106, v2
	v_mov_b32_e32 v107, v2
	v_mov_b32_e32 v108, v2
	v_mov_b32_e32 v109, v2
	v_mov_b32_e32 v110, v2
	v_mov_b32_e32 v111, v2
	v_mov_b32_e32 v112, v2
	v_mov_b32_e32 v113, v2
	v_mov_b32_e32 v122, v2
	v_mov_b32_e32 v123, v2
	v_mov_b32_e32 v124, v2
	v_mov_b32_e32 v125, v2
	v_mov_b32_e32 v126, v2
	v_mov_b32_e32 v127, v2
	v_mov_b32_e32 v128, v2
	v_mov_b32_e32 v129, v2

.LBB0_645:
	v_add_u32_e32 v218, s11, v192
	v_add_u32_e32 v81, 1, v218
	v_mad_i64_i32 v[82:83], s[0:1], v81, s33, v[164:165]
	v_add_u32_e32 v86, 33, v218
	v_mad_i64_i32 v[84:85], s[0:1], v86, s33, v[164:165]
	global_load_dwordx4 v[146:149], v[82:83], off
	global_load_dwordx4 v[150:153], v[84:85], off
	v_mad_i64_i32 v[82:83], s[0:1], v81, s33, v[166:167]
	v_mad_i64_i32 v[84:85], s[0:1], v86, s33, v[166:167]
	global_load_dwordx4 v[154:157], v[82:83], off
	global_load_dwordx4 v[158:161], v[84:85], off
	ds_read_b128 v[228:231], v191 offset:49152
	ds_read_b128 v[232:235], v190 offset:49152
	ds_read_b128 v[236:239], v191 offset:57344
	ds_read_b128 v[248:251], v190 offset:57344
	ds_read_b128 v[252:255], v189 offset:49152
	s_waitcnt lgkmcnt(4)
	v_mfma_f32_32x32x16_bf16 v[98:113], v[228:231], v[142:145], 0
	ds_read_b128 v[228:231], v189 offset:57344
	s_waitcnt lgkmcnt(4)
	v_mfma_f32_32x32x16_bf16 v[98:113], v[232:235], v[138:141], v[98:113]
	ds_read_b128 v[232:235], v188 offset:49152
	s_waitcnt lgkmcnt(4)
	v_mfma_f32_32x32x16_bf16 v[82:97], v[236:239], v[142:145], 0
	ds_read_b128 v[236:239], v188 offset:57344
	s_waitcnt lgkmcnt(4)
	v_mfma_f32_32x32x16_bf16 v[82:97], v[248:251], v[138:141], v[82:97]
	ds_read_b128 v[248:251], v191 offset:49280
	s_waitcnt lgkmcnt(4)
	v_mfma_f32_32x32x16_bf16 v[98:113], v[252:255], v[134:137], v[98:113]
	ds_read_b128 v[252:255], v191 offset:57472
	s_waitcnt lgkmcnt(4)
	v_mfma_f32_32x32x16_bf16 v[82:97], v[228:231], v[134:137], v[82:97]
	ds_read_b128 v[228:231], v190 offset:49280
	s_waitcnt lgkmcnt(4)
	v_mfma_f32_32x32x16_bf16 v[98:113], v[232:235], v[130:133], v[98:113]
	ds_read_b128 v[232:235], v190 offset:57472
	s_waitcnt lgkmcnt(4)
	v_mfma_f32_32x32x16_bf16 v[82:97], v[236:239], v[130:133], v[82:97]
	ds_read_b128 v[236:239], v189 offset:49280
	s_waitcnt lgkmcnt(4)
	v_mfma_f32_32x32x16_bf16 v[98:113], v[248:251], v[126:129], v[98:113]
	ds_read_b128 v[248:251], v189 offset:57472
	s_waitcnt lgkmcnt(4)
	v_mfma_f32_32x32x16_bf16 v[82:97], v[252:255], v[126:129], v[82:97]
	ds_read_b128 v[252:255], v188 offset:49280
	s_waitcnt lgkmcnt(4)
	v_mfma_f32_32x32x16_bf16 v[98:113], v[228:231], v[122:125], v[98:113]
	ds_read_b128 v[228:231], v188 offset:57472
	s_waitcnt lgkmcnt(4)
	v_mfma_f32_32x32x16_bf16 v[82:97], v[232:235], v[122:125], v[82:97]
	s_waitcnt lgkmcnt(3)
	v_mfma_f32_32x32x16_bf16 v[98:113], v[236:239], v[118:121], v[98:113]
	s_waitcnt lgkmcnt(2)
	v_mfma_f32_32x32x16_bf16 v[82:97], v[248:251], v[118:121], v[82:97]
	s_waitcnt lgkmcnt(1)
	v_mfma_f32_32x32x16_bf16 v[98:113], v[252:255], v[114:117], v[98:113]
	s_waitcnt lgkmcnt(0)
	v_mfma_f32_32x32x16_bf16 v[82:97], v[228:231], v[114:117], v[82:97]
	v_exp_f32_e32 v226, v66
	v_add_f32_e32 v66, 0, v215
	v_add_f32_e32 v66, v217, v66
	v_add_f32_e32 v66, v213, v66
	v_add_f32_e32 v66, v216, v66
	v_add_f32_e32 v66, v211, v66
	v_add_f32_e32 v66, v214, v66
	v_add_f32_e32 v66, v210, v66
	v_add_f32_e32 v66, v212, v66
	v_add_f32_e32 v66, v207, v66
	v_add_f32_e32 v66, v209, v66
	v_add_f32_e32 v66, v205, v66
	v_add_f32_e32 v66, v208, v66
	v_exp_f32_e32 v80, v80
	v_add_f32_e32 v66, v203, v66
	v_exp_f32_e32 v1, v1
	v_add_f32_e32 v66, v206, v66
	v_exp_f32_e32 v78, v78
	v_add_f32_e32 v66, v202, v66
	v_exp_f32_e32 v79, v79
	v_add_f32_e32 v66, v204, v66
	v_exp_f32_e32 v76, v76
	v_add_f32_e32 v66, v80, v66
	v_exp_f32_e32 v77, v77
	v_add_f32_e32 v66, v1, v66
	v_exp_f32_e32 v81, v74
	v_add_f32_e32 v66, v78, v66
	v_exp_f32_e32 v219, v75
	v_add_f32_e32 v66, v79, v66
	v_exp_f32_e32 v220, v72
	v_add_f32_e32 v66, v76, v66
	v_exp_f32_e32 v221, v73
	v_add_f32_e32 v66, v77, v66
	v_exp_f32_e32 v222, v70
	v_add_f32_e32 v66, v81, v66
	v_exp_f32_e32 v223, v71
	v_add_f32_e32 v66, v219, v66
	v_exp_f32_e32 v224, v68
	v_add_f32_e32 v66, v220, v66
	v_exp_f32_e32 v225, v69
	v_add_f32_e32 v66, v221, v66
	v_add_f32_e32 v66, v222, v66
	v_exp_f32_e32 v227, v67
	v_add_f32_e32 v66, v223, v66
	v_add_f32_e32 v66, v224, v66
	v_add_f32_e32 v66, v225, v66
	v_add_f32_e32 v66, v226, v66
	v_add_f32_e32 v200, v227, v66
	v_mov_b32_e32 v201, v200
	v_cvt_pk_bf16_f32 v66, v215, v217
	v_cvt_pk_bf16_f32 v67, v213, v216
	v_cvt_pk_bf16_f32 v68, v211, v214
	v_cvt_pk_bf16_f32 v69, v210, v212
	v_cvt_pk_bf16_f32 v70, v207, v209
	v_cvt_pk_bf16_f32 v71, v205, v208
	v_cvt_pk_bf16_f32 v72, v203, v206
	v_cvt_pk_bf16_f32 v73, v202, v204
	v_cvt_pk_bf16_f32 v74, v80, v1
	v_cvt_pk_bf16_f32 v75, v78, v79
	v_cvt_pk_bf16_f32 v76, v76, v77
	v_cvt_pk_bf16_f32 v77, v81, v219
	v_cvt_pk_bf16_f32 v78, v220, v221
	v_cvt_pk_bf16_f32 v79, v222, v223
	v_cvt_pk_bf16_f32 v80, v224, v225
	v_cvt_pk_bf16_f32 v81, v226, v227
	s_nop 1
	v_permlane32_swap_b32_e32 v200, v201
	v_permlane32_swap_b32_e32 v66, v68
	v_permlane32_swap_b32_e32 v67, v69
	v_permlane32_swap_b32_e32 v70, v72
	v_permlane32_swap_b32_e32 v71, v73
	v_permlane32_swap_b32_e32 v74, v76
	v_permlane32_swap_b32_e32 v75, v77
	v_permlane32_swap_b32_e32 v78, v80
	v_permlane32_swap_b32_e32 v79, v81
	ds_read_b64_tr_b16 v[202:203], v183 offset:0
	ds_read_b64_tr_b16 v[204:205], v183 offset:0x800
	ds_read_b64_tr_b16 v[206:207], v183 offset:0x1000
	ds_read_b64_tr_b16 v[208:209], v183 offset:0x1800
	ds_read_b64_tr_b16 v[210:211], v183 offset:0x2000
	ds_read_b64_tr_b16 v[212:213], v183 offset:0x2800
	ds_read_b64_tr_b16 v[214:215], v183 offset:0x3000
	ds_read_b64_tr_b16 v[216:217], v183 offset:0x3800
	s_waitcnt lgkmcnt(0)
	s_nop 0
	v_mfma_f32_32x32x16_bf16 v[50:65], v[66:69], v[202:205], v[50:65]
	ds_read_b64_tr_b16 v[202:203], v183 offset:0x200
	ds_read_b64_tr_b16 v[204:205], v183 offset:0xa00
	v_mfma_f32_32x32x16_bf16 v[50:65], v[70:73], v[206:209], v[50:65]
	ds_read_b64_tr_b16 v[206:207], v183 offset:0x1200
	ds_read_b64_tr_b16 v[208:209], v183 offset:0x1a00
	v_mfma_f32_32x32x16_bf16 v[50:65], v[74:77], v[210:213], v[50:65]
	ds_read_b64_tr_b16 v[210:211], v183 offset:0x2200
	ds_read_b64_tr_b16 v[212:213], v183 offset:0x2a00
	v_mfma_f32_32x32x16_bf16 v[50:65], v[78:81], v[214:217], v[50:65]
	ds_read_b64_tr_b16 v[214:215], v183 offset:0x3200
	ds_read_b64_tr_b16 v[216:217], v183 offset:0x3a00
	s_waitcnt lgkmcnt(0)
	v_mfma_f32_32x32x16_bf16 v[34:49], v[66:69], v[202:205], v[34:49]
	ds_read_b64_tr_b16 v[202:203], v183 offset:0x400
	ds_read_b64_tr_b16 v[204:205], v183 offset:0xc00
	v_mfma_f32_32x32x16_bf16 v[34:49], v[70:73], v[206:209], v[34:49]
	ds_read_b64_tr_b16 v[206:207], v183 offset:0x1400
	ds_read_b64_tr_b16 v[208:209], v183 offset:0x1c00
	v_mfma_f32_32x32x16_bf16 v[34:49], v[74:77], v[210:213], v[34:49]
	ds_read_b64_tr_b16 v[210:211], v183 offset:0x2400
	ds_read_b64_tr_b16 v[212:213], v183 offset:0x2c00
	v_mfma_f32_32x32x16_bf16 v[34:49], v[78:81], v[214:217], v[34:49]
	ds_read_b64_tr_b16 v[214:215], v183 offset:0x3400
	ds_read_b64_tr_b16 v[216:217], v183 offset:0x3c00
	s_waitcnt lgkmcnt(0)
	v_mfma_f32_32x32x16_bf16 v[18:33], v[66:69], v[202:205], v[18:33]
	ds_read_b64_tr_b16 v[202:203], v183 offset:0x600
	ds_read_b64_tr_b16 v[204:205], v183 offset:0xe00
	v_mfma_f32_32x32x16_bf16 v[18:33], v[70:73], v[206:209], v[18:33]
	ds_read_b64_tr_b16 v[206:207], v183 offset:0x1600
	ds_read_b64_tr_b16 v[208:209], v183 offset:0x1e00
	v_mfma_f32_32x32x16_bf16 v[18:33], v[74:77], v[210:213], v[18:33]
	ds_read_b64_tr_b16 v[210:211], v183 offset:0x2600
	ds_read_b64_tr_b16 v[212:213], v183 offset:0x2e00
	v_mfma_f32_32x32x16_bf16 v[18:33], v[78:81], v[214:217], v[18:33]
	ds_read_b64_tr_b16 v[214:215], v183 offset:0x3600
	ds_read_b64_tr_b16 v[216:217], v183 offset:0x3e00
	s_waitcnt lgkmcnt(0)
	v_mfma_f32_32x32x16_bf16 v[2:17], v[66:69], v[202:205], v[2:17]
	v_mfma_f32_32x32x16_bf16 v[2:17], v[70:73], v[206:209], v[2:17]
	v_mfma_f32_32x32x16_bf16 v[2:17], v[74:77], v[210:213], v[2:17]
	v_mfma_f32_32x32x16_bf16 v[2:17], v[78:81], v[214:217], v[2:17]
	ds_read_b128 v[66:69], v198
	ds_read_b128 v[70:73], v198 offset:32
	ds_read_b128 v[202:205], v198 offset:128
	ds_read_b128 v[206:209], v198 offset:160
	ds_read_b128 v[76:79], v198 offset:64
	ds_read_b128 v[210:213], v198 offset:96
	ds_read_b128 v[214:217], v198 offset:192
	ds_read_b128 v[220:223], v198 offset:224
	s_waitcnt lgkmcnt(7)
	v_xor_b32_e32 v69, 0x80000000, v69
	s_waitcnt lgkmcnt(3)
	v_xor_b32_e32 v225, 0x80000000, v79
	v_xor_b32_e32 v224, 0x80000000, v78
	v_xor_b32_e32 v68, 0x80000000, v68
	v_xor_b32_e32 v73, 0x80000000, v73
	v_xor_b32_e32 v72, 0x80000000, v72
	s_waitcnt lgkmcnt(2)
	v_xor_b32_e32 v81, 0x80000000, v213
	v_xor_b32_e32 v80, 0x80000000, v212
	v_pk_fma_f32 v[74:75], v[110:111], s[12:13], v[210:211] op_sel_hi:[1,0,1] neg_lo:[0,0,1] neg_hi:[0,0,1]
	v_pk_fma_f32 v[78:79], v[106:107], s[12:13], v[76:77] op_sel_hi:[1,0,1] neg_lo:[0,0,1] neg_hi:[0,0,1]
	v_pk_fma_f32 v[102:103], v[102:103], s[12:13], v[70:71] op_sel_hi:[1,0,1] neg_lo:[0,0,1] neg_hi:[0,0,1]
	v_pk_fma_f32 v[106:107], v[108:109], s[12:13], v[224:225] op_sel_hi:[1,0,1]
	v_xor_b32_e32 v109, 0x80000000, v205
	v_xor_b32_e32 v108, 0x80000000, v204
	v_xor_b32_e32 v111, 0x80000000, v209
	v_xor_b32_e32 v110, 0x80000000, v208
	s_waitcnt lgkmcnt(1)
	v_xor_b32_e32 v77, 0x80000000, v217
	v_xor_b32_e32 v76, 0x80000000, v216
	s_waitcnt lgkmcnt(0)
	v_xor_b32_e32 v71, 0x80000000, v223
	v_xor_b32_e32 v70, 0x80000000, v222
	v_pk_fma_f32 v[80:81], v[112:113], s[12:13], v[80:81] op_sel_hi:[1,0,1]
	v_pk_fma_f32 v[104:105], v[104:105], s[12:13], v[72:73] op_sel_hi:[1,0,1]
	v_pk_fma_f32 v[100:101], v[100:101], s[12:13], v[68:69] op_sel_hi:[1,0,1]
	v_pk_fma_f32 v[98:99], v[98:99], s[12:13], v[66:67] op_sel_hi:[1,0,1] neg_lo:[0,0,1] neg_hi:[0,0,1]
	v_pk_fma_f32 v[66:67], v[94:95], s[12:13], v[220:221] op_sel_hi:[1,0,1] neg_lo:[0,0,1] neg_hi:[0,0,1]
	v_pk_fma_f32 v[68:69], v[90:91], s[12:13], v[214:215] op_sel_hi:[1,0,1] neg_lo:[0,0,1] neg_hi:[0,0,1]
	v_pk_fma_f32 v[72:73], v[86:87], s[12:13], v[206:207] op_sel_hi:[1,0,1] neg_lo:[0,0,1] neg_hi:[0,0,1]
	v_pk_fma_f32 v[70:71], v[96:97], s[12:13], v[70:71] op_sel_hi:[1,0,1]
	v_pk_fma_f32 v[76:77], v[92:93], s[12:13], v[76:77] op_sel_hi:[1,0,1]
	v_pk_fma_f32 v[86:87], v[88:89], s[12:13], v[110:111] op_sel_hi:[1,0,1]
	v_pk_fma_f32 v[84:85], v[84:85], s[12:13], v[108:109] op_sel_hi:[1,0,1]
	s_cmp_le_i32 s11, s27
	v_pk_fma_f32 v[82:83], v[82:83], s[12:13], v[202:203] op_sel_hi:[1,0,1] neg_lo:[0,0,1] neg_hi:[0,0,1]
	s_cbranch_scc1 .LBB0_647
	v_add_u32_e32 v1, 64, v199
	v_cmp_gt_i32_e64 s[92:93], 26, v1
	v_cmp_gt_i32_e64 s[94:95], 27, v1
	v_cmp_gt_i32_e64 s[90:91], 25, v1
	s_and_b64 s[92:93], s[94:95], s[92:93]
	v_cmp_gt_i32_e64 s[88:89], 24, v1
	s_and_b64 s[90:91], s[92:93], s[90:91]
	v_cmp_gt_i32_e64 s[86:87], 19, v1
	s_and_b64 s[88:89], s[90:91], s[88:89]
	v_cmp_gt_i32_e64 s[84:85], 18, v1
	s_and_b64 s[86:87], s[88:89], s[86:87]
	v_cmp_gt_i32_e64 s[82:83], 17, v1
	s_and_b64 s[84:85], s[86:87], s[84:85]
	v_cmp_gt_i32_e64 s[80:81], 16, v1
	s_and_b64 s[82:83], s[84:85], s[82:83]
	v_cmp_gt_i32_e64 s[78:79], 11, v1
	s_and_b64 s[80:81], s[82:83], s[80:81]
	v_cmp_gt_i32_e64 s[76:77], 10, v1
	s_and_b64 s[78:79], s[80:81], s[78:79]
	v_cmp_gt_i32_e64 s[74:75], 9, v1
	s_and_b64 s[76:77], s[78:79], s[76:77]
	v_cmp_gt_i32_e64 s[72:73], 8, v1
	s_and_b64 s[74:75], s[76:77], s[74:75]
	v_cmp_gt_i32_e64 s[70:71], 3, v1
	s_and_b64 s[72:73], s[74:75], s[72:73]
	v_cmp_gt_i32_e64 s[68:69], 2, v1
	s_and_b64 s[70:71], s[72:73], s[70:71]
	v_cmp_gt_i32_e64 s[2:3], 1, v1
	s_and_b64 s[68:69], s[70:71], s[68:69]
	v_cmp_gt_i32_e64 s[0:1], 0, v1
	s_and_b64 s[2:3], s[68:69], s[2:3]
	s_and_b64 s[0:1], s[2:3], s[0:1]
	v_cmp_gt_i32_e64 s[66:67], 58, v1
	v_cndmask_b32_e64 v98, v98, v175, s[0:1]
	v_cmp_gt_i32_e64 s[0:1], 59, v1
	v_cmp_gt_i32_e64 s[64:65], 57, v1
	v_cmp_gt_i32_e64 s[62:63], 56, v1
	v_cndmask_b32_e64 v71, v71, v175, s[0:1]
	s_and_b64 s[0:1], s[0:1], s[66:67]
	v_cndmask_b32_e64 v70, v70, v175, s[0:1]
	s_and_b64 s[0:1], s[0:1], s[64:65]
	v_cmp_gt_i32_e64 s[60:61], 51, v1
	v_cndmask_b32_e64 v67, v67, v175, s[0:1]
	s_and_b64 s[0:1], s[0:1], s[62:63]
	v_cmp_gt_i32_e64 s[58:59], 50, v1
	v_cndmask_b32_e64 v66, v66, v175, s[0:1]
	s_and_b64 s[0:1], s[0:1], s[60:61]
	v_cmp_gt_i32_e64 s[56:57], 49, v1
	v_cndmask_b32_e64 v77, v77, v175, s[0:1]
	s_and_b64 s[0:1], s[0:1], s[58:59]
	v_cmp_gt_i32_e64 s[54:55], 48, v1
	v_cndmask_b32_e64 v76, v76, v175, s[0:1]
	s_and_b64 s[0:1], s[0:1], s[56:57]
	v_cmp_gt_i32_e64 s[52:53], 43, v1
	v_cndmask_b32_e64 v69, v69, v175, s[0:1]
	s_and_b64 s[0:1], s[0:1], s[54:55]
	v_cmp_gt_i32_e64 s[50:51], 42, v1
	v_cndmask_b32_e64 v68, v68, v175, s[0:1]
	s_and_b64 s[0:1], s[0:1], s[52:53]
	v_cmp_gt_i32_e64 s[48:49], 41, v1
	v_cndmask_b32_e64 v87, v87, v175, s[0:1]
	s_and_b64 s[0:1], s[0:1], s[50:51]
	v_cmp_gt_i32_e64 s[46:47], 40, v1
	v_cndmask_b32_e64 v86, v86, v175, s[0:1]
	s_and_b64 s[0:1], s[0:1], s[48:49]
	v_cmp_gt_i32_e64 s[44:45], 35, v1
	v_cndmask_b32_e64 v73, v73, v175, s[0:1]
	s_and_b64 s[0:1], s[0:1], s[46:47]
	v_cmp_gt_i32_e64 s[42:43], 34, v1
	v_cndmask_b32_e64 v72, v72, v175, s[0:1]
	s_and_b64 s[0:1], s[0:1], s[44:45]
	v_cmp_gt_i32_e64 s[40:41], 33, v1
	v_cndmask_b32_e64 v85, v85, v175, s[0:1]
	s_and_b64 s[0:1], s[0:1], s[42:43]
	v_cmp_gt_i32_e32 vcc, 32, v1
	v_cndmask_b32_e64 v84, v84, v175, s[0:1]
	s_and_b64 s[0:1], s[0:1], s[40:41]
	v_cndmask_b32_e64 v74, v74, v175, s[88:89]
	v_readlane_b32 s88, v242, 2
	s_and_b64 vcc, s[0:1], vcc
	v_cndmask_b32_e64 v81, v81, v175, s[94:95]
	v_cndmask_b32_e64 v80, v80, v175, s[92:93]
	s_movk_i32 s93, 0x6018
	s_mov_b32 s92, 0xf800000
	v_cndmask_b32_e64 v75, v75, v175, s[90:91]
	s_mov_b64 s[90:91], s[16:17]
	v_readlane_b32 s89, v242, 3
	v_cndmask_b32_e64 v107, v107, v175, s[86:87]
	v_readlane_b32 s86, v242, 0
	v_cndmask_b32_e64 v106, v106, v175, s[84:85]
	v_cndmask_b32_e64 v79, v79, v175, s[82:83]
	s_movk_i32 s83, 0x6000
	v_cndmask_b32_e64 v78, v78, v175, s[80:81]
	v_cndmask_b32_e64 v105, v105, v175, s[78:79]
	v_cndmask_b32_e64 v104, v104, v175, s[76:77]
	v_cndmask_b32_e64 v103, v103, v175, s[74:75]
	v_cndmask_b32_e64 v102, v102, v175, s[72:73]
	v_cndmask_b32_e64 v101, v101, v175, s[70:71]
	v_cndmask_b32_e64 v100, v100, v175, s[68:69]
	v_cndmask_b32_e64 v99, v99, v175, s[2:3]
	s_mov_b32 s56, s30
	v_cndmask_b32_e64 v83, v83, v175, s[0:1]
	v_cndmask_b32_e32 v82, v82, v175, vcc
	v_readlane_b32 s87, v242, 1

.LBB0_653:
	v_sub_f32_e32 v104, v82, v1
	v_sub_f32_e32 v105, v83, v1
	v_sub_f32_e32 v208, v84, v1
	v_sub_f32_e32 v209, v85, v1
	v_sub_f32_e32 v210, v72, v1
	v_sub_f32_e32 v211, v73, v1
	v_sub_f32_e32 v212, v86, v1
	v_sub_f32_e32 v213, v87, v1
	v_sub_f32_e32 v214, v68, v1
	v_sub_f32_e32 v215, v69, v1
	v_sub_f32_e32 v216, v76, v1
	v_sub_f32_e32 v217, v77, v1
	v_sub_f32_e32 v218, v66, v1
	v_sub_f32_e32 v219, v67, v1
	v_sub_f32_e32 v220, v70, v1
	v_sub_f32_e32 v221, v71, v1
	ds_read_b128 v[228:231], v191 offset:32768
	ds_read_b128 v[232:235], v190 offset:32768
	ds_read_b128 v[236:239], v191 offset:40960
	ds_read_b128 v[248:251], v190 offset:40960
	ds_read_b128 v[252:255], v189 offset:32768
	s_waitcnt lgkmcnt(4)
	v_mfma_f32_32x32x16_bf16 v[82:97], v[228:231], v[142:145], 0
	ds_read_b128 v[228:231], v189 offset:40960
	s_waitcnt lgkmcnt(4)
	v_mfma_f32_32x32x16_bf16 v[82:97], v[232:235], v[138:141], v[82:97]
	ds_read_b128 v[232:235], v188 offset:32768
	s_waitcnt lgkmcnt(4)
	v_mfma_f32_32x32x16_bf16 v[66:81], v[236:239], v[142:145], 0
	ds_read_b128 v[236:239], v188 offset:40960
	s_waitcnt lgkmcnt(4)
	v_mfma_f32_32x32x16_bf16 v[66:81], v[248:251], v[138:141], v[66:81]
	ds_read_b128 v[248:251], v191 offset:32896
	s_waitcnt lgkmcnt(4)
	v_mfma_f32_32x32x16_bf16 v[82:97], v[252:255], v[134:137], v[82:97]
	ds_read_b128 v[252:255], v191 offset:41088
	s_waitcnt lgkmcnt(4)
	v_mfma_f32_32x32x16_bf16 v[66:81], v[228:231], v[134:137], v[66:81]
	ds_read_b128 v[228:231], v190 offset:32896
	s_waitcnt lgkmcnt(4)
	v_mfma_f32_32x32x16_bf16 v[82:97], v[232:235], v[130:133], v[82:97]
	ds_read_b128 v[232:235], v190 offset:41088
	s_waitcnt lgkmcnt(4)
	v_mfma_f32_32x32x16_bf16 v[66:81], v[236:239], v[130:133], v[66:81]
	ds_read_b128 v[236:239], v189 offset:32896
	s_waitcnt lgkmcnt(4)
	v_mfma_f32_32x32x16_bf16 v[82:97], v[248:251], v[126:129], v[82:97]
	ds_read_b128 v[248:251], v189 offset:41088
	s_waitcnt lgkmcnt(4)
	v_mfma_f32_32x32x16_bf16 v[66:81], v[252:255], v[126:129], v[66:81]
	ds_read_b128 v[252:255], v188 offset:32896
	s_waitcnt lgkmcnt(4)
	v_mfma_f32_32x32x16_bf16 v[82:97], v[228:231], v[122:125], v[82:97]
	ds_read_b128 v[228:231], v188 offset:41088
	s_waitcnt lgkmcnt(4)
	v_mfma_f32_32x32x16_bf16 v[66:81], v[232:235], v[122:125], v[66:81]
	s_waitcnt lgkmcnt(3)
	v_mfma_f32_32x32x16_bf16 v[82:97], v[236:239], v[118:121], v[82:97]
	s_waitcnt lgkmcnt(2)
	v_mfma_f32_32x32x16_bf16 v[66:81], v[248:251], v[118:121], v[66:81]
	s_waitcnt lgkmcnt(1)
	v_mfma_f32_32x32x16_bf16 v[82:97], v[252:255], v[114:117], v[82:97]
	s_waitcnt lgkmcnt(0)
	v_mfma_f32_32x32x16_bf16 v[66:81], v[228:231], v[114:117], v[66:81]
	v_exp_f32_e32 v222, v104
	v_add_f32_e32 v104, 0, v196
	v_add_f32_e32 v104, v203, v104
	v_add_f32_e32 v104, v112, v104
	v_add_f32_e32 v104, v202, v104
	v_add_f32_e32 v104, v110, v104
	v_add_f32_e32 v104, v113, v104
	v_add_f32_e32 v104, v109, v104
	v_add_f32_e32 v104, v111, v104
	v_add_f32_e32 v104, v103, v104
	v_add_f32_e32 v104, v107, v104
	v_add_f32_e32 v104, v101, v104
	v_add_f32_e32 v104, v106, v104
	v_add_f32_e32 v104, v99, v104
	v_exp_f32_e32 v223, v105
	v_add_f32_e32 v104, v102, v104
	v_exp_f32_e32 v208, v208
	v_add_f32_e32 v104, v98, v104
	v_exp_f32_e32 v209, v209
	v_add_f32_e32 v104, v100, v104
	v_exp_f32_e32 v210, v210
	v_add_f32_e32 v104, v222, v104
	v_exp_f32_e32 v211, v211
	v_add_f32_e32 v104, v223, v104
	v_exp_f32_e32 v212, v212
	v_add_f32_e32 v104, v208, v104
	v_exp_f32_e32 v213, v213
	v_add_f32_e32 v104, v209, v104
	v_exp_f32_e32 v214, v214
	v_add_f32_e32 v104, v210, v104
	v_exp_f32_e32 v215, v215
	v_add_f32_e32 v104, v211, v104
	v_exp_f32_e32 v216, v216
	v_add_f32_e32 v104, v212, v104
	v_exp_f32_e32 v217, v217
	v_add_f32_e32 v104, v213, v104
	v_exp_f32_e32 v218, v218
	v_add_f32_e32 v104, v214, v104
	v_exp_f32_e32 v219, v219
	v_add_f32_e32 v104, v215, v104
	v_exp_f32_e32 v220, v220
	v_add_f32_e32 v104, v216, v104
	v_exp_f32_e32 v221, v221
	v_add_f32_e32 v104, v217, v104
	v_add_f32_e32 v104, v218, v104
	v_add_f32_e32 v104, v219, v104
	v_add_f32_e32 v104, v220, v104
	v_add_f32_e32 v104, v221, v104
	v_mov_b32_e32 v105, v104
	v_cvt_pk_bf16_f32 v204, v196, v203
	v_cvt_pk_bf16_f32 v205, v112, v202
	v_cvt_pk_bf16_f32 v206, v110, v113
	v_cvt_pk_bf16_f32 v207, v109, v111
	v_cvt_pk_bf16_f32 v110, v103, v107
	v_cvt_pk_bf16_f32 v111, v101, v106
	v_cvt_pk_bf16_f32 v112, v99, v102
	v_cvt_pk_bf16_f32 v113, v98, v100
	v_cvt_pk_bf16_f32 v98, v222, v223
	v_cvt_pk_bf16_f32 v99, v208, v209
	v_cvt_pk_bf16_f32 v100, v210, v211
	v_cvt_pk_bf16_f32 v101, v212, v213
	s_nop 1
	v_permlane32_swap_b32_e32 v104, v105
	v_permlane32_swap_b32_e32 v98, v100
	v_permlane32_swap_b32_e32 v99, v101
	v_cvt_pk_bf16_f32 v208, v214, v215
	v_cvt_pk_bf16_f32 v209, v216, v217
	v_cvt_pk_bf16_f32 v210, v218, v219
	v_cvt_pk_bf16_f32 v211, v220, v221
	v_permlane32_swap_b32_e32 v204, v206
	v_permlane32_swap_b32_e32 v205, v207
	v_permlane32_swap_b32_e32 v110, v112
	v_permlane32_swap_b32_e32 v111, v113
	v_permlane32_swap_b32_e32 v208, v210
	v_permlane32_swap_b32_e32 v209, v211
	ds_read_b64_tr_b16 v[212:213], v183 offset:0x4000
	ds_read_b64_tr_b16 v[214:215], v183 offset:0x4800
	ds_read_b64_tr_b16 v[216:217], v183 offset:0x5000
	ds_read_b64_tr_b16 v[218:219], v183 offset:0x5800
	ds_read_b64_tr_b16 v[220:221], v183 offset:0x6000
	ds_read_b64_tr_b16 v[222:223], v183 offset:0x6800
	ds_read_b64_tr_b16 v[224:225], v183 offset:0x7000
	ds_read_b64_tr_b16 v[226:227], v183 offset:0x7800
	s_waitcnt lgkmcnt(0)
	s_nop 0
	v_mfma_f32_32x32x16_bf16 v[50:65], v[204:207], v[212:215], v[50:65]
	ds_read_b64_tr_b16 v[212:213], v183 offset:0x4200
	ds_read_b64_tr_b16 v[214:215], v183 offset:0x4a00
	v_mfma_f32_32x32x16_bf16 v[50:65], v[110:113], v[216:219], v[50:65]
	ds_read_b64_tr_b16 v[216:217], v183 offset:0x5200
	ds_read_b64_tr_b16 v[218:219], v183 offset:0x5a00
	v_mfma_f32_32x32x16_bf16 v[50:65], v[98:101], v[220:223], v[50:65]
	ds_read_b64_tr_b16 v[220:221], v183 offset:0x6200
	ds_read_b64_tr_b16 v[222:223], v183 offset:0x6a00
	v_mfma_f32_32x32x16_bf16 v[50:65], v[208:211], v[224:227], v[50:65]
	ds_read_b64_tr_b16 v[224:225], v183 offset:0x7200
	ds_read_b64_tr_b16 v[226:227], v183 offset:0x7a00
	s_waitcnt lgkmcnt(0)
	v_mfma_f32_32x32x16_bf16 v[34:49], v[204:207], v[212:215], v[34:49]
	ds_read_b64_tr_b16 v[212:213], v183 offset:0x4400
	ds_read_b64_tr_b16 v[214:215], v183 offset:0x4c00
	v_mfma_f32_32x32x16_bf16 v[34:49], v[110:113], v[216:219], v[34:49]
	ds_read_b64_tr_b16 v[216:217], v183 offset:0x5400
	ds_read_b64_tr_b16 v[218:219], v183 offset:0x5c00
	v_mfma_f32_32x32x16_bf16 v[34:49], v[98:101], v[220:223], v[34:49]
	ds_read_b64_tr_b16 v[220:221], v183 offset:0x6400
	ds_read_b64_tr_b16 v[222:223], v183 offset:0x6c00
	v_mfma_f32_32x32x16_bf16 v[34:49], v[208:211], v[224:227], v[34:49]
	ds_read_b64_tr_b16 v[224:225], v183 offset:0x7400
	ds_read_b64_tr_b16 v[226:227], v183 offset:0x7c00
	s_waitcnt lgkmcnt(0)
	v_mfma_f32_32x32x16_bf16 v[18:33], v[204:207], v[212:215], v[18:33]
	ds_read_b64_tr_b16 v[212:213], v183 offset:0x4600
	ds_read_b64_tr_b16 v[214:215], v183 offset:0x4e00
	v_mfma_f32_32x32x16_bf16 v[18:33], v[110:113], v[216:219], v[18:33]
	ds_read_b64_tr_b16 v[216:217], v183 offset:0x5600
	ds_read_b64_tr_b16 v[218:219], v183 offset:0x5e00
	v_mfma_f32_32x32x16_bf16 v[18:33], v[98:101], v[220:223], v[18:33]
	ds_read_b64_tr_b16 v[220:221], v183 offset:0x6600
	ds_read_b64_tr_b16 v[222:223], v183 offset:0x6e00
	v_mfma_f32_32x32x16_bf16 v[18:33], v[208:211], v[224:227], v[18:33]
	ds_read_b64_tr_b16 v[224:225], v183 offset:0x7600
	ds_read_b64_tr_b16 v[226:227], v183 offset:0x7e00
	s_waitcnt lgkmcnt(0)
	v_mfma_f32_32x32x16_bf16 v[2:17], v[204:207], v[212:215], v[2:17]
	v_mfma_f32_32x32x16_bf16 v[2:17], v[110:113], v[216:219], v[2:17]
	v_mfma_f32_32x32x16_bf16 v[2:17], v[98:101], v[220:223], v[2:17]
	v_mfma_f32_32x32x16_bf16 v[2:17], v[208:211], v[224:227], v[2:17]
	ds_read_b128 v[100:103], v198 offset:256
	ds_read_b128 v[110:113], v198 offset:288
	ds_read_b128 v[202:205], v198 offset:384
	ds_read_b128 v[206:209], v198 offset:416
	ds_read_b128 v[210:213], v198 offset:320
	ds_read_b128 v[214:217], v198 offset:352
	ds_read_b128 v[218:221], v198 offset:448
	ds_read_b128 v[222:225], v198 offset:480
	s_waitcnt lgkmcnt(7)
	v_xor_b32_e32 v103, 0x80000000, v103
	v_xor_b32_e32 v102, 0x80000000, v102
	s_waitcnt lgkmcnt(6)
	v_xor_b32_e32 v107, 0x80000000, v113
	v_xor_b32_e32 v106, 0x80000000, v112
	s_waitcnt lgkmcnt(3)
	v_xor_b32_e32 v113, 0x80000000, v213
	v_xor_b32_e32 v112, 0x80000000, v212
	s_waitcnt lgkmcnt(2)
	v_xor_b32_e32 v213, 0x80000000, v217
	v_xor_b32_e32 v212, 0x80000000, v216
	v_pk_fma_f32 v[98:99], v[86:87], s[12:13], v[110:111] op_sel_hi:[1,0,1] neg_lo:[0,0,1] neg_hi:[0,0,1]
	v_pk_fma_f32 v[86:87], v[96:97], s[12:13], v[212:213] op_sel_hi:[1,0,1]
	v_pk_fma_f32 v[88:89], v[88:89], s[12:13], v[106:107] op_sel_hi:[1,0,1]
	v_pk_fma_f32 v[84:85], v[84:85], s[12:13], v[102:103] op_sel_hi:[1,0,1]
	v_pk_fma_f32 v[96:97], v[82:83], s[12:13], v[100:101] op_sel_hi:[1,0,1] neg_lo:[0,0,1] neg_hi:[0,0,1]
	v_xor_b32_e32 v103, 0x80000000, v205
	v_xor_b32_e32 v102, 0x80000000, v204
	v_xor_b32_e32 v101, 0x80000000, v209
	v_xor_b32_e32 v100, 0x80000000, v208
	s_waitcnt lgkmcnt(1)
	v_xor_b32_e32 v107, 0x80000000, v221
	v_xor_b32_e32 v106, 0x80000000, v220
	s_waitcnt lgkmcnt(0)
	v_xor_b32_e32 v111, 0x80000000, v225
	v_xor_b32_e32 v110, 0x80000000, v224
	s_add_i32 s0, s11, 64
	v_pk_fma_f32 v[94:95], v[94:95], s[12:13], v[214:215] op_sel_hi:[1,0,1] neg_lo:[0,0,1] neg_hi:[0,0,1]
	v_pk_fma_f32 v[90:91], v[90:91], s[12:13], v[210:211] op_sel_hi:[1,0,1] neg_lo:[0,0,1] neg_hi:[0,0,1]
	v_pk_fma_f32 v[92:93], v[92:93], s[12:13], v[112:113] op_sel_hi:[1,0,1]
	v_pk_fma_f32 v[82:83], v[78:79], s[12:13], v[222:223] op_sel_hi:[1,0,1] neg_lo:[0,0,1] neg_hi:[0,0,1]
	v_pk_fma_f32 v[74:75], v[74:75], s[12:13], v[218:219] op_sel_hi:[1,0,1] neg_lo:[0,0,1] neg_hi:[0,0,1]
	v_pk_fma_f32 v[78:79], v[70:71], s[12:13], v[206:207] op_sel_hi:[1,0,1] neg_lo:[0,0,1] neg_hi:[0,0,1]
	v_pk_fma_f32 v[70:71], v[80:81], s[12:13], v[110:111] op_sel_hi:[1,0,1]
	v_pk_fma_f32 v[76:77], v[76:77], s[12:13], v[106:107] op_sel_hi:[1,0,1]
	v_pk_fma_f32 v[100:101], v[72:73], s[12:13], v[100:101] op_sel_hi:[1,0,1]
	v_pk_fma_f32 v[102:103], v[68:69], s[12:13], v[102:103] op_sel_hi:[1,0,1]
	s_cmp_le_i32 s0, s27
	v_pk_fma_f32 v[80:81], v[66:67], s[12:13], v[202:203] op_sel_hi:[1,0,1] neg_lo:[0,0,1] neg_hi:[0,0,1]
	s_cbranch_scc1 .LBB0_655
	v_cmp_gt_i32_e64 s[92:93], 26, v199
	v_cmp_gt_i32_e64 s[94:95], 27, v199
	v_cmp_gt_i32_e64 s[90:91], 25, v199
	s_and_b64 s[92:93], s[94:95], s[92:93]
	v_cmp_gt_i32_e64 s[88:89], 24, v199
	s_and_b64 s[90:91], s[92:93], s[90:91]
	v_cmp_gt_i32_e64 s[86:87], 19, v199
	s_and_b64 s[88:89], s[90:91], s[88:89]
	v_cmp_gt_i32_e64 s[84:85], 18, v199
	s_and_b64 s[86:87], s[88:89], s[86:87]
	v_cmp_gt_i32_e64 s[82:83], 17, v199
	s_and_b64 s[84:85], s[86:87], s[84:85]
	v_cmp_gt_i32_e64 s[80:81], 16, v199
	s_and_b64 s[82:83], s[84:85], s[82:83]
	v_cmp_gt_i32_e64 s[78:79], 11, v199
	s_and_b64 s[80:81], s[82:83], s[80:81]
	v_cmp_gt_i32_e64 s[76:77], 10, v199
	s_and_b64 s[78:79], s[80:81], s[78:79]
	v_cmp_gt_i32_e64 s[74:75], 9, v199
	s_and_b64 s[76:77], s[78:79], s[76:77]
	v_cmp_gt_i32_e64 s[72:73], 8, v199
	s_and_b64 s[74:75], s[76:77], s[74:75]
	v_cmp_gt_i32_e64 s[70:71], 3, v199
	s_and_b64 s[72:73], s[74:75], s[72:73]
	v_cmp_gt_i32_e64 s[68:69], 2, v199
	s_and_b64 s[70:71], s[72:73], s[70:71]
	v_cmp_gt_i32_e64 s[2:3], 1, v199
	s_and_b64 s[68:69], s[70:71], s[68:69]
	v_cmp_gt_i32_e64 s[0:1], 0, v199
	s_and_b64 s[2:3], s[68:69], s[2:3]
	s_and_b64 s[0:1], s[2:3], s[0:1]
	v_cmp_gt_i32_e64 s[66:67], 58, v199
	v_cndmask_b32_e64 v96, v96, v175, s[0:1]
	v_cmp_gt_i32_e64 s[0:1], 59, v199
	v_cmp_gt_i32_e64 s[64:65], 57, v199
	v_cmp_gt_i32_e64 s[62:63], 56, v199
	v_cndmask_b32_e64 v71, v71, v175, s[0:1]
	s_and_b64 s[0:1], s[0:1], s[66:67]
	v_cndmask_b32_e64 v70, v70, v175, s[0:1]
	s_and_b64 s[0:1], s[0:1], s[64:65]
	v_cmp_gt_i32_e64 s[60:61], 51, v199
	v_cndmask_b32_e64 v83, v83, v175, s[0:1]
	s_and_b64 s[0:1], s[0:1], s[62:63]
	v_cmp_gt_i32_e64 s[58:59], 50, v199
	v_cndmask_b32_e64 v82, v82, v175, s[0:1]
	s_and_b64 s[0:1], s[0:1], s[60:61]
	v_cmp_gt_i32_e64 s[56:57], 49, v199
	v_cndmask_b32_e64 v77, v77, v175, s[0:1]
	s_and_b64 s[0:1], s[0:1], s[58:59]
	v_cmp_gt_i32_e64 s[54:55], 48, v199
	v_cndmask_b32_e64 v76, v76, v175, s[0:1]
	s_and_b64 s[0:1], s[0:1], s[56:57]
	v_cmp_gt_i32_e64 s[52:53], 43, v199
	v_cndmask_b32_e64 v75, v75, v175, s[0:1]
	s_and_b64 s[0:1], s[0:1], s[54:55]
	v_cmp_gt_i32_e64 s[50:51], 42, v199
	v_cndmask_b32_e64 v74, v74, v175, s[0:1]
	s_and_b64 s[0:1], s[0:1], s[52:53]
	v_cmp_gt_i32_e64 s[48:49], 41, v199
	v_cndmask_b32_e64 v101, v101, v175, s[0:1]
	s_and_b64 s[0:1], s[0:1], s[50:51]
	v_cmp_gt_i32_e64 s[46:47], 40, v199
	v_cndmask_b32_e64 v100, v100, v175, s[0:1]
	s_and_b64 s[0:1], s[0:1], s[48:49]
	v_cmp_gt_i32_e64 s[44:45], 35, v199
	v_cndmask_b32_e64 v79, v79, v175, s[0:1]
	s_and_b64 s[0:1], s[0:1], s[46:47]
	v_cmp_gt_i32_e64 s[42:43], 34, v199
	v_cndmask_b32_e64 v78, v78, v175, s[0:1]
	s_and_b64 s[0:1], s[0:1], s[44:45]
	v_cmp_gt_i32_e64 s[40:41], 33, v199
	v_cndmask_b32_e64 v103, v103, v175, s[0:1]
	s_and_b64 s[0:1], s[0:1], s[42:43]
	v_cmp_gt_i32_e32 vcc, 32, v199
	v_cndmask_b32_e64 v102, v102, v175, s[0:1]
	s_and_b64 s[0:1], s[0:1], s[40:41]
	v_cndmask_b32_e64 v94, v94, v175, s[88:89]
	v_readlane_b32 s88, v242, 2
	s_and_b64 vcc, s[0:1], vcc
	v_cndmask_b32_e64 v87, v87, v175, s[94:95]
	v_cndmask_b32_e64 v86, v86, v175, s[92:93]
	s_movk_i32 s93, 0x6018
	s_mov_b32 s92, 0xf800000
	v_cndmask_b32_e64 v95, v95, v175, s[90:91]
	s_mov_b64 s[90:91], s[16:17]
	v_readlane_b32 s89, v242, 3
	v_cndmask_b32_e64 v93, v93, v175, s[86:87]
	v_readlane_b32 s86, v242, 0
	v_cndmask_b32_e64 v92, v92, v175, s[84:85]
	v_cndmask_b32_e64 v91, v91, v175, s[82:83]
	s_movk_i32 s83, 0x6000
	v_cndmask_b32_e64 v90, v90, v175, s[80:81]
	v_cndmask_b32_e64 v89, v89, v175, s[78:79]
	v_cndmask_b32_e64 v88, v88, v175, s[76:77]
	v_cndmask_b32_e64 v99, v99, v175, s[74:75]
	v_cndmask_b32_e64 v98, v98, v175, s[72:73]
	v_cndmask_b32_e64 v85, v85, v175, s[70:71]
	v_cndmask_b32_e64 v84, v84, v175, s[68:69]
	v_cndmask_b32_e64 v97, v97, v175, s[2:3]
	s_mov_b32 s56, s30
	v_cndmask_b32_e64 v81, v81, v175, s[0:1]
	v_cndmask_b32_e32 v80, v80, v175, vcc
	v_readlane_b32 s87, v242, 1

.LBB0_823:
	v_add_u32_e32 v182, s9, v158
	v_add_u32_e32 v66, 1, v182
	v_mad_i64_i32 v[66:67], s[0:1], v66, s33, v[130:131]
	v_add_u32_e32 v68, 33, v182
	v_mad_i64_i32 v[68:69], s[0:1], v68, s33, v[130:131]
	global_load_dwordx4 v[114:117], v[66:67], off offset:2048
	global_load_dwordx4 v[122:125], v[66:67], off offset:1024
	global_load_dwordx4 v[118:121], v[68:69], off offset:2048
	global_load_dwordx4 v[126:129], v[68:69], off offset:1024
	ds_read_b128 v[228:231], v159 offset:49152
	ds_read_b128 v[232:235], v160 offset:49152
	ds_read_b128 v[236:239], v159 offset:57344
	ds_read_b128 v[248:251], v160 offset:57344
	ds_read_b128 v[252:255], v161 offset:49152
	s_waitcnt lgkmcnt(4)
	v_mfma_f32_32x32x16_bf16 v[82:97], v[228:231], v[110:113], 0
	ds_read_b128 v[228:231], v161 offset:57344
	s_waitcnt lgkmcnt(4)
	v_mfma_f32_32x32x16_bf16 v[82:97], v[232:235], v[106:109], v[82:97]
	ds_read_b128 v[232:235], v162 offset:49152
	s_waitcnt lgkmcnt(4)
	v_mfma_f32_32x32x16_bf16 v[66:81], v[236:239], v[110:113], 0
	ds_read_b128 v[236:239], v162 offset:57344
	s_waitcnt lgkmcnt(4)
	v_mfma_f32_32x32x16_bf16 v[66:81], v[248:251], v[106:109], v[66:81]
	s_waitcnt lgkmcnt(3)
	v_mfma_f32_32x32x16_bf16 v[82:97], v[252:255], v[102:105], v[82:97]
	s_waitcnt lgkmcnt(2)
	v_mfma_f32_32x32x16_bf16 v[66:81], v[228:231], v[102:105], v[66:81]
	s_waitcnt lgkmcnt(1)
	v_mfma_f32_32x32x16_bf16 v[82:97], v[232:235], v[98:101], v[82:97]
	s_waitcnt lgkmcnt(0)
	v_mfma_f32_32x32x16_bf16 v[66:81], v[236:239], v[98:101], v[66:81]
	v_exp_f32_e32 v206, v132
	v_add_f32_e32 v132, 0, v197
	v_add_f32_e32 v132, v199, v132
	v_add_f32_e32 v132, v195, v132
	v_add_f32_e32 v132, v198, v132
	v_add_f32_e32 v132, v193, v132
	v_add_f32_e32 v132, v196, v132
	v_add_f32_e32 v132, v192, v132
	v_add_f32_e32 v132, v194, v132
	v_add_f32_e32 v132, v189, v132
	v_add_f32_e32 v132, v191, v132
	v_add_f32_e32 v132, v187, v132
	v_add_f32_e32 v132, v190, v132
	v_exp_f32_e32 v146, v146
	v_add_f32_e32 v132, v185, v132
	v_exp_f32_e32 v147, v147
	v_add_f32_e32 v132, v188, v132
	v_exp_f32_e32 v144, v144
	v_add_f32_e32 v132, v184, v132
	v_exp_f32_e32 v145, v145
	v_add_f32_e32 v132, v186, v132
	v_exp_f32_e32 v142, v142
	v_add_f32_e32 v132, v146, v132
	v_exp_f32_e32 v143, v143
	v_add_f32_e32 v132, v147, v132
	v_exp_f32_e32 v181, v140
	v_add_f32_e32 v132, v144, v132
	v_exp_f32_e32 v183, v141
	v_add_f32_e32 v132, v145, v132
	v_exp_f32_e32 v200, v138
	v_add_f32_e32 v132, v142, v132
	v_exp_f32_e32 v201, v139
	v_add_f32_e32 v132, v143, v132
	v_exp_f32_e32 v202, v136
	v_add_f32_e32 v132, v181, v132
	v_exp_f32_e32 v203, v137
	v_add_f32_e32 v132, v183, v132
	v_exp_f32_e32 v204, v134
	v_add_f32_e32 v132, v200, v132
	v_exp_f32_e32 v205, v135
	v_add_f32_e32 v132, v201, v132
	v_add_f32_e32 v132, v202, v132
	v_exp_f32_e32 v207, v133
	v_add_f32_e32 v132, v203, v132
	v_add_f32_e32 v132, v204, v132
	v_add_f32_e32 v132, v205, v132
	v_add_f32_e32 v132, v206, v132
	v_add_f32_e32 v179, v207, v132
	v_mov_b32_e32 v180, v179
	s_nop 1
	v_permlane32_swap_b32_e32 v179, v180
	v_cvt_pk_bf16_f32 v132, v197, v199
	v_cvt_pk_bf16_f32 v133, v195, v198
	v_cvt_pk_bf16_f32 v134, v193, v196
	v_cvt_pk_bf16_f32 v135, v192, v194
	v_cvt_pk_bf16_f32 v136, v189, v191
	v_cvt_pk_bf16_f32 v137, v187, v190
	v_cvt_pk_bf16_f32 v138, v185, v188
	v_cvt_pk_bf16_f32 v139, v184, v186
	v_cvt_pk_bf16_f32 v140, v146, v147
	v_cvt_pk_bf16_f32 v141, v144, v145
	v_cvt_pk_bf16_f32 v142, v142, v143
	v_cvt_pk_bf16_f32 v143, v181, v183
	v_cvt_pk_bf16_f32 v144, v200, v201
	v_cvt_pk_bf16_f32 v145, v202, v203
	v_cvt_pk_bf16_f32 v146, v204, v205
	v_cvt_pk_bf16_f32 v147, v206, v207
	s_nop 0
	v_permlane32_swap_b32_e32 v132, v134
	v_permlane32_swap_b32_e32 v133, v135
	v_permlane32_swap_b32_e32 v136, v138
	v_permlane32_swap_b32_e32 v137, v139
	v_permlane32_swap_b32_e32 v140, v142
	v_permlane32_swap_b32_e32 v141, v143
	v_permlane32_swap_b32_e32 v144, v146
	v_permlane32_swap_b32_e32 v145, v147
	ds_read_b64_tr_b16 v[184:185], v153 offset:0
	ds_read_b64_tr_b16 v[186:187], v153 offset:0x800
	ds_read_b64_tr_b16 v[188:189], v153 offset:0x1000
	ds_read_b64_tr_b16 v[190:191], v153 offset:0x1800
	ds_read_b64_tr_b16 v[192:193], v153 offset:0x2000
	ds_read_b64_tr_b16 v[194:195], v153 offset:0x2800
	ds_read_b64_tr_b16 v[196:197], v153 offset:0x3000
	ds_read_b64_tr_b16 v[198:199], v153 offset:0x3800
	s_waitcnt lgkmcnt(0)
	s_nop 0
	v_mfma_f32_32x32x16_bf16 v[50:65], v[132:135], v[184:187], v[50:65]
	ds_read_b64_tr_b16 v[184:185], v153 offset:0x200
	ds_read_b64_tr_b16 v[186:187], v153 offset:0xa00
	v_mfma_f32_32x32x16_bf16 v[50:65], v[136:139], v[188:191], v[50:65]
	ds_read_b64_tr_b16 v[188:189], v153 offset:0x1200
	ds_read_b64_tr_b16 v[190:191], v153 offset:0x1a00
	v_mfma_f32_32x32x16_bf16 v[50:65], v[140:143], v[192:195], v[50:65]
	ds_read_b64_tr_b16 v[192:193], v153 offset:0x2200
	ds_read_b64_tr_b16 v[194:195], v153 offset:0x2a00
	v_mfma_f32_32x32x16_bf16 v[50:65], v[144:147], v[196:199], v[50:65]
	ds_read_b64_tr_b16 v[196:197], v153 offset:0x3200
	ds_read_b64_tr_b16 v[198:199], v153 offset:0x3a00
	s_waitcnt lgkmcnt(0)
	v_mfma_f32_32x32x16_bf16 v[34:49], v[132:135], v[184:187], v[34:49]
	ds_read_b64_tr_b16 v[184:185], v153 offset:0x400
	ds_read_b64_tr_b16 v[186:187], v153 offset:0xc00
	v_mfma_f32_32x32x16_bf16 v[34:49], v[136:139], v[188:191], v[34:49]
	ds_read_b64_tr_b16 v[188:189], v153 offset:0x1400
	ds_read_b64_tr_b16 v[190:191], v153 offset:0x1c00
	v_mfma_f32_32x32x16_bf16 v[34:49], v[140:143], v[192:195], v[34:49]
	ds_read_b64_tr_b16 v[192:193], v153 offset:0x2400
	ds_read_b64_tr_b16 v[194:195], v153 offset:0x2c00
	v_mfma_f32_32x32x16_bf16 v[34:49], v[144:147], v[196:199], v[34:49]
	ds_read_b64_tr_b16 v[196:197], v153 offset:0x3400
	ds_read_b64_tr_b16 v[198:199], v153 offset:0x3c00
	s_waitcnt lgkmcnt(0)
	v_mfma_f32_32x32x16_bf16 v[18:33], v[132:135], v[184:187], v[18:33]
	ds_read_b64_tr_b16 v[184:185], v153 offset:0x600
	ds_read_b64_tr_b16 v[186:187], v153 offset:0xe00
	v_mfma_f32_32x32x16_bf16 v[18:33], v[136:139], v[188:191], v[18:33]
	ds_read_b64_tr_b16 v[188:189], v153 offset:0x1600
	ds_read_b64_tr_b16 v[190:191], v153 offset:0x1e00
	v_mfma_f32_32x32x16_bf16 v[18:33], v[140:143], v[192:195], v[18:33]
	ds_read_b64_tr_b16 v[192:193], v153 offset:0x2600
	ds_read_b64_tr_b16 v[194:195], v153 offset:0x2e00
	v_mfma_f32_32x32x16_bf16 v[18:33], v[144:147], v[196:199], v[18:33]
	ds_read_b64_tr_b16 v[196:197], v153 offset:0x3600
	ds_read_b64_tr_b16 v[198:199], v153 offset:0x3e00
	s_waitcnt lgkmcnt(0)
	v_mfma_f32_32x32x16_bf16 v[2:17], v[132:135], v[184:187], v[2:17]
	v_mfma_f32_32x32x16_bf16 v[2:17], v[136:139], v[188:191], v[2:17]
	v_mfma_f32_32x32x16_bf16 v[2:17], v[140:143], v[192:195], v[2:17]
	v_mfma_f32_32x32x16_bf16 v[2:17], v[144:147], v[196:199], v[2:17]
	s_cmp_le_i32 s9, s25
	s_cbranch_scc1 .LBB0_825
	v_add_u32_e32 v132, 64, v169
	v_cmp_gt_i32_e64 s[92:93], 26, v132
	v_cmp_gt_i32_e64 s[94:95], 27, v132
	v_cmp_gt_i32_e64 s[90:91], 25, v132
	s_and_b64 s[92:93], s[94:95], s[92:93]
	v_cmp_gt_i32_e64 s[88:89], 24, v132
	s_and_b64 s[90:91], s[92:93], s[90:91]
	v_cmp_gt_i32_e64 s[86:87], 19, v132
	s_and_b64 s[88:89], s[90:91], s[88:89]
	v_cmp_gt_i32_e64 s[84:85], 18, v132
	s_and_b64 s[86:87], s[88:89], s[86:87]
	v_cmp_gt_i32_e64 s[82:83], 17, v132
	s_and_b64 s[84:85], s[86:87], s[84:85]
	v_cmp_gt_i32_e64 s[80:81], 16, v132
	s_and_b64 s[82:83], s[84:85], s[82:83]
	v_cmp_gt_i32_e64 s[78:79], 11, v132
	s_and_b64 s[80:81], s[82:83], s[80:81]
	v_cmp_gt_i32_e64 s[76:77], 10, v132
	s_and_b64 s[78:79], s[80:81], s[78:79]
	v_cmp_gt_i32_e64 s[74:75], 9, v132
	s_and_b64 s[76:77], s[78:79], s[76:77]
	v_cmp_gt_i32_e64 s[72:73], 8, v132
	s_and_b64 s[74:75], s[76:77], s[74:75]
	v_cmp_gt_i32_e64 s[70:71], 3, v132
	s_and_b64 s[72:73], s[74:75], s[72:73]
	v_cmp_gt_i32_e64 s[68:69], 2, v132
	s_and_b64 s[70:71], s[72:73], s[70:71]
	v_cmp_gt_i32_e64 s[2:3], 1, v132
	s_and_b64 s[68:69], s[70:71], s[68:69]
	v_cmp_gt_i32_e64 s[0:1], 0, v132
	s_and_b64 s[2:3], s[68:69], s[2:3]
	s_and_b64 s[0:1], s[2:3], s[0:1]
	v_cmp_gt_i32_e64 s[66:67], 58, v132
	v_cndmask_b32_e64 v82, v82, v175, s[0:1]
	v_cmp_gt_i32_e64 s[0:1], 59, v132
	v_cmp_gt_i32_e64 s[64:65], 57, v132
	v_cmp_gt_i32_e64 s[62:63], 56, v132
	v_cndmask_b32_e64 v81, v81, v175, s[0:1]
	s_and_b64 s[0:1], s[0:1], s[66:67]
	v_cndmask_b32_e64 v80, v80, v175, s[0:1]
	s_and_b64 s[0:1], s[0:1], s[64:65]
	v_cmp_gt_i32_e64 s[60:61], 51, v132
	v_cndmask_b32_e64 v79, v79, v175, s[0:1]
	s_and_b64 s[0:1], s[0:1], s[62:63]
	v_cmp_gt_i32_e64 s[58:59], 50, v132
	v_cndmask_b32_e64 v78, v78, v175, s[0:1]
	s_and_b64 s[0:1], s[0:1], s[60:61]
	v_cmp_gt_i32_e64 s[56:57], 49, v132
	v_cndmask_b32_e64 v77, v77, v175, s[0:1]
	s_and_b64 s[0:1], s[0:1], s[58:59]
	v_cmp_gt_i32_e64 s[54:55], 48, v132
	v_cndmask_b32_e64 v76, v76, v175, s[0:1]
	s_and_b64 s[0:1], s[0:1], s[56:57]
	v_cmp_gt_i32_e64 s[52:53], 43, v132
	v_cndmask_b32_e64 v75, v75, v175, s[0:1]
	s_and_b64 s[0:1], s[0:1], s[54:55]
	v_cmp_gt_i32_e64 s[50:51], 42, v132
	v_cndmask_b32_e64 v74, v74, v175, s[0:1]
	s_and_b64 s[0:1], s[0:1], s[52:53]
	v_cmp_gt_i32_e64 s[48:49], 41, v132
	v_cndmask_b32_e64 v73, v73, v175, s[0:1]
	s_and_b64 s[0:1], s[0:1], s[50:51]
	v_cmp_gt_i32_e64 s[46:47], 40, v132
	v_cndmask_b32_e64 v72, v72, v175, s[0:1]
	s_and_b64 s[0:1], s[0:1], s[48:49]
	v_cmp_gt_i32_e64 s[44:45], 35, v132
	v_cndmask_b32_e64 v71, v71, v175, s[0:1]
	s_and_b64 s[0:1], s[0:1], s[46:47]
	v_cmp_gt_i32_e64 s[42:43], 34, v132
	v_cndmask_b32_e64 v70, v70, v175, s[0:1]
	s_and_b64 s[0:1], s[0:1], s[44:45]
	v_cmp_gt_i32_e64 s[40:41], 33, v132
	v_cndmask_b32_e64 v69, v69, v175, s[0:1]
	s_and_b64 s[0:1], s[0:1], s[42:43]
	v_cmp_gt_i32_e32 vcc, 32, v132
	v_cndmask_b32_e64 v68, v68, v175, s[0:1]
	s_and_b64 s[0:1], s[0:1], s[40:41]
	s_and_b64 vcc, s[0:1], vcc
	v_cndmask_b32_e64 v97, v97, v175, s[94:95]
	v_cndmask_b32_e64 v96, v96, v175, s[92:93]
	v_cndmask_b32_e64 v95, v95, v175, s[90:91]
	v_cndmask_b32_e64 v94, v94, v175, s[88:89]
	v_cndmask_b32_e64 v93, v93, v175, s[86:87]
	v_cndmask_b32_e64 v92, v92, v175, s[84:85]
	v_cndmask_b32_e64 v91, v91, v175, s[82:83]
	v_cndmask_b32_e64 v90, v90, v175, s[80:81]
	v_cndmask_b32_e64 v89, v89, v175, s[78:79]
	v_cndmask_b32_e64 v88, v88, v175, s[76:77]
	v_cndmask_b32_e64 v87, v87, v175, s[74:75]
	v_cndmask_b32_e64 v86, v86, v175, s[72:73]
	v_cndmask_b32_e64 v85, v85, v175, s[70:71]
	v_cndmask_b32_e64 v84, v84, v175, s[68:69]
	v_cndmask_b32_e64 v83, v83, v175, s[2:3]
	v_cndmask_b32_e64 v67, v67, v175, s[0:1]
	v_cndmask_b32_e32 v66, v66, v175, vcc

.LBB0_831:
	ds_read_b128 v[228:231], v159 offset:32768
	ds_read_b128 v[232:235], v160 offset:32768
	ds_read_b128 v[236:239], v159 offset:40960
	ds_read_b128 v[248:251], v160 offset:40960
	ds_read_b128 v[252:255], v161 offset:32768
	s_waitcnt lgkmcnt(4)
	v_mfma_f32_32x32x16_bf16 v[82:97], v[228:231], v[110:113], 0
	ds_read_b128 v[228:231], v161 offset:40960
	s_waitcnt lgkmcnt(4)
	v_mfma_f32_32x32x16_bf16 v[82:97], v[232:235], v[106:109], v[82:97]
	ds_read_b128 v[232:235], v162 offset:32768
	s_waitcnt lgkmcnt(4)
	v_mfma_f32_32x32x16_bf16 v[66:81], v[236:239], v[110:113], 0
	ds_read_b128 v[236:239], v162 offset:40960
	s_waitcnt lgkmcnt(4)
	v_mfma_f32_32x32x16_bf16 v[66:81], v[248:251], v[106:109], v[66:81]
	s_waitcnt lgkmcnt(3)
	v_mfma_f32_32x32x16_bf16 v[82:97], v[252:255], v[102:105], v[82:97]
	s_waitcnt lgkmcnt(2)
	v_mfma_f32_32x32x16_bf16 v[66:81], v[228:231], v[102:105], v[66:81]
	s_waitcnt lgkmcnt(1)
	v_mfma_f32_32x32x16_bf16 v[82:97], v[232:235], v[98:101], v[82:97]
	s_waitcnt lgkmcnt(0)
	v_mfma_f32_32x32x16_bf16 v[66:81], v[236:239], v[98:101], v[66:81]
	v_add_f32_e32 v182, 0, v146
	v_add_f32_e32 v182, v168, v182
	v_add_f32_e32 v182, v144, v182
	v_add_f32_e32 v182, v147, v182
	v_add_f32_e32 v182, v142, v182
	v_add_f32_e32 v182, v145, v182
	v_add_f32_e32 v182, v141, v182
	v_add_f32_e32 v182, v143, v182
	v_add_f32_e32 v182, v138, v182
	v_add_f32_e32 v182, v140, v182
	v_add_f32_e32 v182, v136, v182
	v_add_f32_e32 v182, v139, v182
	v_exp_f32_e32 v199, v184
	v_add_f32_e32 v182, v134, v182
	v_exp_f32_e32 v200, v185
	v_add_f32_e32 v182, v137, v182
	v_exp_f32_e32 v201, v186
	v_add_f32_e32 v182, v133, v182
	v_exp_f32_e32 v202, v187
	v_add_f32_e32 v182, v135, v182
	v_exp_f32_e32 v188, v188
	v_add_f32_e32 v182, v199, v182
	v_exp_f32_e32 v189, v189
	v_add_f32_e32 v182, v200, v182
	v_exp_f32_e32 v190, v190
	v_add_f32_e32 v182, v201, v182
	v_exp_f32_e32 v191, v191
	v_add_f32_e32 v182, v202, v182
	v_exp_f32_e32 v192, v192
	v_add_f32_e32 v182, v188, v182
	v_exp_f32_e32 v193, v193
	v_add_f32_e32 v182, v189, v182
	v_exp_f32_e32 v194, v194
	v_add_f32_e32 v182, v190, v182
	v_exp_f32_e32 v195, v195
	v_add_f32_e32 v182, v191, v182
	v_exp_f32_e32 v196, v196
	v_add_f32_e32 v182, v192, v182
	v_exp_f32_e32 v197, v197
	v_add_f32_e32 v182, v193, v182
	v_exp_f32_e32 v198, v198
	v_add_f32_e32 v182, v194, v182
	v_exp_f32_e32 v203, v183
	v_add_f32_e32 v182, v195, v182
	v_add_f32_e32 v182, v196, v182
	v_add_f32_e32 v182, v197, v182
	v_add_f32_e32 v182, v198, v182
	v_add_f32_e32 v182, v203, v182
	v_mov_b32_e32 v183, v182
	s_nop 1
	v_permlane32_swap_b32_e32 v182, v183
	v_cvt_pk_bf16_f32 v184, v146, v168
	v_cvt_pk_bf16_f32 v185, v144, v147
	v_cvt_pk_bf16_f32 v186, v142, v145
	v_cvt_pk_bf16_f32 v187, v141, v143
	v_cvt_pk_bf16_f32 v138, v138, v140
	v_cvt_pk_bf16_f32 v139, v136, v139
	v_cvt_pk_bf16_f32 v140, v134, v137
	v_cvt_pk_bf16_f32 v141, v133, v135
	v_cvt_pk_bf16_f32 v134, v199, v200
	v_cvt_pk_bf16_f32 v135, v201, v202
	v_cvt_pk_bf16_f32 v136, v188, v189
	v_cvt_pk_bf16_f32 v137, v190, v191
	v_cvt_pk_bf16_f32 v142, v192, v193
	v_cvt_pk_bf16_f32 v143, v194, v195
	v_cvt_pk_bf16_f32 v144, v196, v197
	v_cvt_pk_bf16_f32 v145, v198, v203
	s_nop 0
	v_permlane32_swap_b32_e32 v184, v186
	v_permlane32_swap_b32_e32 v185, v187
	v_permlane32_swap_b32_e32 v138, v140
	v_permlane32_swap_b32_e32 v139, v141
	v_permlane32_swap_b32_e32 v134, v136
	v_permlane32_swap_b32_e32 v135, v137
	v_permlane32_swap_b32_e32 v142, v144
	v_permlane32_swap_b32_e32 v143, v145
	ds_read_b64_tr_b16 v[188:189], v153 offset:0x4000
	ds_read_b64_tr_b16 v[190:191], v153 offset:0x4800
	ds_read_b64_tr_b16 v[192:193], v153 offset:0x5000
	ds_read_b64_tr_b16 v[194:195], v153 offset:0x5800
	ds_read_b64_tr_b16 v[196:197], v153 offset:0x6000
	ds_read_b64_tr_b16 v[198:199], v153 offset:0x6800
	ds_read_b64_tr_b16 v[200:201], v153 offset:0x7000
	ds_read_b64_tr_b16 v[202:203], v153 offset:0x7800
	s_waitcnt lgkmcnt(0)
	s_nop 0
	v_mfma_f32_32x32x16_bf16 v[50:65], v[184:187], v[188:191], v[50:65]
	ds_read_b64_tr_b16 v[188:189], v153 offset:0x4200
	ds_read_b64_tr_b16 v[190:191], v153 offset:0x4a00
	v_mfma_f32_32x32x16_bf16 v[50:65], v[138:141], v[192:195], v[50:65]
	ds_read_b64_tr_b16 v[192:193], v153 offset:0x5200
	ds_read_b64_tr_b16 v[194:195], v153 offset:0x5a00
	v_mfma_f32_32x32x16_bf16 v[50:65], v[134:137], v[196:199], v[50:65]
	ds_read_b64_tr_b16 v[196:197], v153 offset:0x6200
	ds_read_b64_tr_b16 v[198:199], v153 offset:0x6a00
	v_mfma_f32_32x32x16_bf16 v[50:65], v[142:145], v[200:203], v[50:65]
	ds_read_b64_tr_b16 v[200:201], v153 offset:0x7200
	ds_read_b64_tr_b16 v[202:203], v153 offset:0x7a00
	s_waitcnt lgkmcnt(0)
	v_mfma_f32_32x32x16_bf16 v[34:49], v[184:187], v[188:191], v[34:49]
	ds_read_b64_tr_b16 v[188:189], v153 offset:0x4400
	ds_read_b64_tr_b16 v[190:191], v153 offset:0x4c00
	v_mfma_f32_32x32x16_bf16 v[34:49], v[138:141], v[192:195], v[34:49]
	ds_read_b64_tr_b16 v[192:193], v153 offset:0x5400
	ds_read_b64_tr_b16 v[194:195], v153 offset:0x5c00
	v_mfma_f32_32x32x16_bf16 v[34:49], v[134:137], v[196:199], v[34:49]
	ds_read_b64_tr_b16 v[196:197], v153 offset:0x6400
	ds_read_b64_tr_b16 v[198:199], v153 offset:0x6c00
	v_mfma_f32_32x32x16_bf16 v[34:49], v[142:145], v[200:203], v[34:49]
	ds_read_b64_tr_b16 v[200:201], v153 offset:0x7400
	ds_read_b64_tr_b16 v[202:203], v153 offset:0x7c00
	s_waitcnt lgkmcnt(0)
	v_mfma_f32_32x32x16_bf16 v[18:33], v[184:187], v[188:191], v[18:33]
	ds_read_b64_tr_b16 v[188:189], v153 offset:0x4600
	ds_read_b64_tr_b16 v[190:191], v153 offset:0x4e00
	v_mfma_f32_32x32x16_bf16 v[18:33], v[138:141], v[192:195], v[18:33]
	ds_read_b64_tr_b16 v[192:193], v153 offset:0x5600
	ds_read_b64_tr_b16 v[194:195], v153 offset:0x5e00
	v_mfma_f32_32x32x16_bf16 v[18:33], v[134:137], v[196:199], v[18:33]
	ds_read_b64_tr_b16 v[196:197], v153 offset:0x6600
	ds_read_b64_tr_b16 v[198:199], v153 offset:0x6e00
	v_mfma_f32_32x32x16_bf16 v[18:33], v[142:145], v[200:203], v[18:33]
	ds_read_b64_tr_b16 v[200:201], v153 offset:0x7600
	ds_read_b64_tr_b16 v[202:203], v153 offset:0x7e00
	s_waitcnt lgkmcnt(0)
	v_mfma_f32_32x32x16_bf16 v[2:17], v[184:187], v[188:191], v[2:17]
	v_mfma_f32_32x32x16_bf16 v[2:17], v[138:141], v[192:195], v[2:17]
	v_mfma_f32_32x32x16_bf16 v[2:17], v[134:137], v[196:199], v[2:17]
	v_mfma_f32_32x32x16_bf16 v[2:17], v[142:145], v[200:203], v[2:17]
	s_add_i32 s0, s9, 64
	s_cmp_le_i32 s0, s25
	s_cbranch_scc1 .LBB0_833
	v_cmp_gt_i32_e64 s[92:93], 26, v169
	v_cmp_gt_i32_e64 s[94:95], 27, v169
	v_cmp_gt_i32_e64 s[90:91], 25, v169
	s_and_b64 s[92:93], s[94:95], s[92:93]
	v_cmp_gt_i32_e64 s[88:89], 24, v169
	s_and_b64 s[90:91], s[92:93], s[90:91]
	v_cmp_gt_i32_e64 s[86:87], 19, v169
	s_and_b64 s[88:89], s[90:91], s[88:89]
	v_cmp_gt_i32_e64 s[84:85], 18, v169
	s_and_b64 s[86:87], s[88:89], s[86:87]
	v_cmp_gt_i32_e64 s[82:83], 17, v169
	s_and_b64 s[84:85], s[86:87], s[84:85]
	v_cmp_gt_i32_e64 s[80:81], 16, v169
	s_and_b64 s[82:83], s[84:85], s[82:83]
	v_cmp_gt_i32_e64 s[78:79], 11, v169
	s_and_b64 s[80:81], s[82:83], s[80:81]
	v_cmp_gt_i32_e64 s[76:77], 10, v169
	s_and_b64 s[78:79], s[80:81], s[78:79]
	v_cmp_gt_i32_e64 s[74:75], 9, v169
	s_and_b64 s[76:77], s[78:79], s[76:77]
	v_cmp_gt_i32_e64 s[72:73], 8, v169
	s_and_b64 s[74:75], s[76:77], s[74:75]
	v_cmp_gt_i32_e64 s[70:71], 3, v169
	s_and_b64 s[72:73], s[74:75], s[72:73]
	v_cmp_gt_i32_e64 s[68:69], 2, v169
	s_and_b64 s[70:71], s[72:73], s[70:71]
	v_cmp_gt_i32_e64 s[2:3], 1, v169
	s_and_b64 s[68:69], s[70:71], s[68:69]
	v_cmp_gt_i32_e64 s[0:1], 0, v169
	s_and_b64 s[2:3], s[68:69], s[2:3]
	s_and_b64 s[0:1], s[2:3], s[0:1]
	v_cmp_gt_i32_e64 s[66:67], 58, v169
	v_cndmask_b32_e64 v82, v82, v175, s[0:1]
	v_cmp_gt_i32_e64 s[0:1], 59, v169
	v_cmp_gt_i32_e64 s[64:65], 57, v169
	v_cmp_gt_i32_e64 s[62:63], 56, v169
	v_cndmask_b32_e64 v81, v81, v175, s[0:1]
	s_and_b64 s[0:1], s[0:1], s[66:67]
	v_cndmask_b32_e64 v80, v80, v175, s[0:1]
	s_and_b64 s[0:1], s[0:1], s[64:65]
	v_cmp_gt_i32_e64 s[60:61], 51, v169
	v_cndmask_b32_e64 v79, v79, v175, s[0:1]
	s_and_b64 s[0:1], s[0:1], s[62:63]
	v_cmp_gt_i32_e64 s[58:59], 50, v169
	v_cndmask_b32_e64 v78, v78, v175, s[0:1]
	s_and_b64 s[0:1], s[0:1], s[60:61]
	v_cmp_gt_i32_e64 s[56:57], 49, v169
	v_cndmask_b32_e64 v77, v77, v175, s[0:1]
	s_and_b64 s[0:1], s[0:1], s[58:59]
	v_cmp_gt_i32_e64 s[54:55], 48, v169
	v_cndmask_b32_e64 v76, v76, v175, s[0:1]
	s_and_b64 s[0:1], s[0:1], s[56:57]
	v_cmp_gt_i32_e64 s[52:53], 43, v169
	v_cndmask_b32_e64 v75, v75, v175, s[0:1]
	s_and_b64 s[0:1], s[0:1], s[54:55]
	v_cmp_gt_i32_e64 s[50:51], 42, v169
	v_cndmask_b32_e64 v74, v74, v175, s[0:1]
	s_and_b64 s[0:1], s[0:1], s[52:53]
	v_cmp_gt_i32_e64 s[48:49], 41, v169
	v_cndmask_b32_e64 v73, v73, v175, s[0:1]
	s_and_b64 s[0:1], s[0:1], s[50:51]
	v_cmp_gt_i32_e64 s[46:47], 40, v169
	v_cndmask_b32_e64 v72, v72, v175, s[0:1]
	s_and_b64 s[0:1], s[0:1], s[48:49]
	v_cmp_gt_i32_e64 s[44:45], 35, v169
	v_cndmask_b32_e64 v71, v71, v175, s[0:1]
	s_and_b64 s[0:1], s[0:1], s[46:47]
	v_cmp_gt_i32_e64 s[42:43], 34, v169
	v_cndmask_b32_e64 v70, v70, v175, s[0:1]
	s_and_b64 s[0:1], s[0:1], s[44:45]
	v_cmp_gt_i32_e64 s[40:41], 33, v169
	v_cndmask_b32_e64 v69, v69, v175, s[0:1]
	s_and_b64 s[0:1], s[0:1], s[42:43]
	v_cmp_gt_i32_e32 vcc, 32, v169
	v_cndmask_b32_e64 v68, v68, v175, s[0:1]
	s_and_b64 s[0:1], s[0:1], s[40:41]
	s_and_b64 vcc, s[0:1], vcc
	v_cndmask_b32_e64 v97, v97, v175, s[94:95]
	v_cndmask_b32_e64 v96, v96, v175, s[92:93]
	v_cndmask_b32_e64 v95, v95, v175, s[90:91]
	v_cndmask_b32_e64 v94, v94, v175, s[88:89]
	v_cndmask_b32_e64 v93, v93, v175, s[86:87]
	v_cndmask_b32_e64 v92, v92, v175, s[84:85]
	v_cndmask_b32_e64 v91, v91, v175, s[82:83]
	v_cndmask_b32_e64 v90, v90, v175, s[80:81]
	v_cndmask_b32_e64 v89, v89, v175, s[78:79]
	v_cndmask_b32_e64 v88, v88, v175, s[76:77]
	v_cndmask_b32_e64 v87, v87, v175, s[74:75]
	v_cndmask_b32_e64 v86, v86, v175, s[72:73]
	v_cndmask_b32_e64 v85, v85, v175, s[70:71]
	v_cndmask_b32_e64 v84, v84, v175, s[68:69]
	v_cndmask_b32_e64 v83, v83, v175, s[2:3]
	v_cndmask_b32_e64 v67, v67, v175, s[0:1]
	v_cndmask_b32_e32 v66, v66, v175, vcc

.LBB0_1114:
	s_ashr_i32 s19, s18, 31
	s_lshl_b64 s[28:29], s[18:19], 20
	v_readlane_b32 s5, v245, 28
	s_add_u32 s28, s5, s28
	v_readlane_b32 s5, v245, 29
	s_addc_u32 s29, s5, s29
	s_and_b64 s[34:35], s[22:23], exec
	s_cselect_b32 s8, s29, s37
	s_cselect_b32 s19, s28, s36
	s_ashr_i32 s5, s4, 31
	s_lshl_b64 s[34:35], s[4:5], 20
	s_add_u32 s34, s11, s34
	s_addc_u32 s35, s13, s35
	s_and_b64 s[44:45], s[22:23], exec
	s_cselect_b32 s5, s35, s43
	s_cselect_b32 s21, s34, s42
	s_add_u32 s36, s36, 0x80080
	s_addc_u32 s37, s37, 0
	s_add_u32 s41, s42, 0x100
	v_mov_b32_e32 v2, 0
	s_addc_u32 s48, s43, 0
	s_mov_b32 s49, -2
	v_mov_b32_e32 v3, v2
	v_mov_b32_e32 v4, v2
	v_mov_b32_e32 v5, v2
	v_mov_b32_e32 v6, v2
	v_mov_b32_e32 v7, v2
	v_mov_b32_e32 v8, v2
	v_mov_b32_e32 v9, v2
	s_waitcnt vmcnt(0) lgkmcnt(0)
	v_mov_b32_e32 v18, v2
	v_mov_b32_e32 v19, v2
	v_mov_b32_e32 v20, v2
	v_mov_b32_e32 v21, v2
	v_mov_b32_e32 v22, v2
	v_mov_b32_e32 v23, v2
	v_mov_b32_e32 v24, v2
	v_mov_b32_e32 v25, v2
	v_mov_b32_e32 v34, v2
	v_mov_b32_e32 v35, v2
	v_mov_b32_e32 v36, v2
	v_mov_b32_e32 v37, v2
	v_mov_b32_e32 v38, v2
	v_mov_b32_e32 v39, v2
	v_mov_b32_e32 v40, v2
	v_mov_b32_e32 v41, v2
	v_mov_b32_e32 v50, v2
	v_mov_b32_e32 v51, v2
	v_mov_b32_e32 v52, v2
	v_mov_b32_e32 v53, v2
	v_mov_b32_e32 v54, v2
	v_mov_b32_e32 v55, v2
	v_mov_b32_e32 v56, v2
	v_mov_b32_e32 v57, v2
	v_mov_b32_e32 v10, v2
	v_mov_b32_e32 v11, v2
	v_mov_b32_e32 v12, v2
	v_mov_b32_e32 v13, v2
	v_mov_b32_e32 v14, v2
	v_mov_b32_e32 v15, v2
	v_mov_b32_e32 v16, v2
	v_mov_b32_e32 v17, v2
	v_mov_b32_e32 v26, v2
	v_mov_b32_e32 v27, v2
	v_mov_b32_e32 v28, v2
	v_mov_b32_e32 v29, v2
	v_mov_b32_e32 v30, v2
	v_mov_b32_e32 v31, v2
	v_mov_b32_e32 v32, v2
	v_mov_b32_e32 v33, v2
	v_mov_b32_e32 v42, v2
	v_mov_b32_e32 v43, v2
	v_mov_b32_e32 v44, v2
	v_mov_b32_e32 v45, v2
	v_mov_b32_e32 v46, v2
	v_mov_b32_e32 v47, v2
	v_mov_b32_e32 v48, v2
	v_mov_b32_e32 v49, v2
	v_mov_b32_e32 v58, v2
	v_mov_b32_e32 v59, v2
	v_mov_b32_e32 v60, v2
	v_mov_b32_e32 v61, v2
	v_mov_b32_e32 v62, v2
	v_mov_b32_e32 v63, v2
	v_mov_b32_e32 v64, v2
	v_mov_b32_e32 v65, v2
	v_mov_b32_e32 v66, v2
	v_mov_b32_e32 v67, v2
	v_mov_b32_e32 v68, v2
	v_mov_b32_e32 v69, v2
	v_mov_b32_e32 v70, v2
	v_mov_b32_e32 v71, v2
	v_mov_b32_e32 v72, v2
	v_mov_b32_e32 v73, v2
	v_mov_b32_e32 v82, v2
	v_mov_b32_e32 v83, v2
	v_mov_b32_e32 v84, v2
	v_mov_b32_e32 v85, v2
	v_mov_b32_e32 v86, v2
	v_mov_b32_e32 v87, v2
	v_mov_b32_e32 v88, v2
	v_mov_b32_e32 v89, v2
	v_mov_b32_e32 v98, v2
	v_mov_b32_e32 v99, v2
	v_mov_b32_e32 v100, v2
	v_mov_b32_e32 v101, v2
	v_mov_b32_e32 v102, v2
	v_mov_b32_e32 v103, v2
	v_mov_b32_e32 v104, v2
	v_mov_b32_e32 v105, v2
	v_mov_b32_e32 v114, v2
	v_mov_b32_e32 v115, v2
	v_mov_b32_e32 v116, v2
	v_mov_b32_e32 v117, v2
	v_mov_b32_e32 v118, v2
	v_mov_b32_e32 v119, v2
	v_mov_b32_e32 v120, v2
	v_mov_b32_e32 v121, v2
	v_mov_b32_e32 v74, v2
	v_mov_b32_e32 v75, v2
	v_mov_b32_e32 v76, v2
	v_mov_b32_e32 v77, v2
	v_mov_b32_e32 v78, v2
	v_mov_b32_e32 v79, v2
	v_mov_b32_e32 v80, v2
	v_mov_b32_e32 v81, v2
	v_mov_b32_e32 v90, v2
	v_mov_b32_e32 v91, v2
	v_mov_b32_e32 v92, v2
	v_mov_b32_e32 v93, v2
	v_mov_b32_e32 v94, v2
	v_mov_b32_e32 v95, v2
	v_mov_b32_e32 v96, v2
	v_mov_b32_e32 v97, v2
	v_mov_b32_e32 v106, v2
	v_mov_b32_e32 v107, v2
	v_mov_b32_e32 v108, v2
	v_mov_b32_e32 v109, v2
	v_mov_b32_e32 v110, v2
	v_mov_b32_e32 v111, v2
	v_mov_b32_e32 v112, v2
	v_mov_b32_e32 v113, v2
	v_mov_b32_e32 v122, v2
	v_mov_b32_e32 v123, v2
	v_mov_b32_e32 v124, v2
	v_mov_b32_e32 v125, v2
	v_mov_b32_e32 v126, v2
	v_mov_b32_e32 v127, v2
	v_mov_b32_e32 v128, v2
	v_mov_b32_e32 v129, v2

.LBB0_1293:
	s_ashr_i32 s19, s18, 31
	s_lshl_b64 s[8:9], s[18:19], 20
	v_readlane_b32 s5, v243, 17
	s_add_u32 s28, s5, s8
	v_readlane_b32 s5, v243, 18
	s_addc_u32 s29, s5, s9
	s_and_b64 s[8:9], s[34:35], exec
	s_cselect_b32 s8, s29, s37
	s_cselect_b32 s9, s28, s36
	s_ashr_i32 s5, s4, 31
	s_lshl_b64 s[20:21], s[4:5], 20
	s_add_u32 s38, s25, s20
	s_addc_u32 s39, s27, s21
	s_and_b64 s[20:21], s[34:35], exec
	s_cselect_b32 s5, s39, s43
	s_cselect_b32 s11, s38, s42
	s_add_u32 s36, s36, 0x80080
	s_addc_u32 s37, s37, 0
	s_add_u32 s13, s42, 0x100
	v_mov_b32_e32 v2, 0
	s_addc_u32 s19, s43, 0
	s_mov_b32 s20, -2
	v_mov_b32_e32 v3, v2
	v_mov_b32_e32 v4, v2
	v_mov_b32_e32 v5, v2
	v_mov_b32_e32 v6, v2
	v_mov_b32_e32 v7, v2
	v_mov_b32_e32 v8, v2
	v_mov_b32_e32 v9, v2
	s_waitcnt vmcnt(0) lgkmcnt(0)
	v_mov_b32_e32 v18, v2
	v_mov_b32_e32 v19, v2
	v_mov_b32_e32 v20, v2
	v_mov_b32_e32 v21, v2
	v_mov_b32_e32 v22, v2
	v_mov_b32_e32 v23, v2
	v_mov_b32_e32 v24, v2
	v_mov_b32_e32 v25, v2
	v_mov_b32_e32 v34, v2
	v_mov_b32_e32 v35, v2
	v_mov_b32_e32 v36, v2
	v_mov_b32_e32 v37, v2
	v_mov_b32_e32 v38, v2
	v_mov_b32_e32 v39, v2
	v_mov_b32_e32 v40, v2
	v_mov_b32_e32 v41, v2
	v_mov_b32_e32 v50, v2
	v_mov_b32_e32 v51, v2
	v_mov_b32_e32 v52, v2
	v_mov_b32_e32 v53, v2
	v_mov_b32_e32 v54, v2
	v_mov_b32_e32 v55, v2
	v_mov_b32_e32 v56, v2
	v_mov_b32_e32 v57, v2
	v_mov_b32_e32 v10, v2
	v_mov_b32_e32 v11, v2
	v_mov_b32_e32 v12, v2
	v_mov_b32_e32 v13, v2
	v_mov_b32_e32 v14, v2
	v_mov_b32_e32 v15, v2
	v_mov_b32_e32 v16, v2
	v_mov_b32_e32 v17, v2
	v_mov_b32_e32 v26, v2
	v_mov_b32_e32 v27, v2
	v_mov_b32_e32 v28, v2
	v_mov_b32_e32 v29, v2
	v_mov_b32_e32 v30, v2
	v_mov_b32_e32 v31, v2
	v_mov_b32_e32 v32, v2
	v_mov_b32_e32 v33, v2
	v_mov_b32_e32 v42, v2
	v_mov_b32_e32 v43, v2
	v_mov_b32_e32 v44, v2
	v_mov_b32_e32 v45, v2
	v_mov_b32_e32 v46, v2
	v_mov_b32_e32 v47, v2
	v_mov_b32_e32 v48, v2
	v_mov_b32_e32 v49, v2
	v_mov_b32_e32 v58, v2
	v_mov_b32_e32 v59, v2
	v_mov_b32_e32 v60, v2
	v_mov_b32_e32 v61, v2
	v_mov_b32_e32 v62, v2
	v_mov_b32_e32 v63, v2
	v_mov_b32_e32 v64, v2
	v_mov_b32_e32 v65, v2
	v_mov_b32_e32 v66, v2
	v_mov_b32_e32 v67, v2
	v_mov_b32_e32 v68, v2
	v_mov_b32_e32 v69, v2
	v_mov_b32_e32 v70, v2
	v_mov_b32_e32 v71, v2
	v_mov_b32_e32 v72, v2
	v_mov_b32_e32 v73, v2
	v_mov_b32_e32 v82, v2
	v_mov_b32_e32 v83, v2
	v_mov_b32_e32 v84, v2
	v_mov_b32_e32 v85, v2
	v_mov_b32_e32 v86, v2
	v_mov_b32_e32 v87, v2
	v_mov_b32_e32 v88, v2
	v_mov_b32_e32 v89, v2
	v_mov_b32_e32 v98, v2
	v_mov_b32_e32 v99, v2
	v_mov_b32_e32 v100, v2
	v_mov_b32_e32 v101, v2
	v_mov_b32_e32 v102, v2
	v_mov_b32_e32 v103, v2
	v_mov_b32_e32 v104, v2
	v_mov_b32_e32 v105, v2
	v_mov_b32_e32 v114, v2
	v_mov_b32_e32 v115, v2
	v_mov_b32_e32 v116, v2
	v_mov_b32_e32 v117, v2
	v_mov_b32_e32 v118, v2
	v_mov_b32_e32 v119, v2
	v_mov_b32_e32 v120, v2
	v_mov_b32_e32 v121, v2
	v_mov_b32_e32 v74, v2
	v_mov_b32_e32 v75, v2
	v_mov_b32_e32 v76, v2
	v_mov_b32_e32 v77, v2
	v_mov_b32_e32 v78, v2
	v_mov_b32_e32 v79, v2
	v_mov_b32_e32 v80, v2
	v_mov_b32_e32 v81, v2
	v_mov_b32_e32 v90, v2
	v_mov_b32_e32 v91, v2
	v_mov_b32_e32 v92, v2
	v_mov_b32_e32 v93, v2
	v_mov_b32_e32 v94, v2
	v_mov_b32_e32 v95, v2
	v_mov_b32_e32 v96, v2
	v_mov_b32_e32 v97, v2
	v_mov_b32_e32 v106, v2
	v_mov_b32_e32 v107, v2
	v_mov_b32_e32 v108, v2
	v_mov_b32_e32 v109, v2
	v_mov_b32_e32 v110, v2
	v_mov_b32_e32 v111, v2
	v_mov_b32_e32 v112, v2
	v_mov_b32_e32 v113, v2
	v_mov_b32_e32 v122, v2
	v_mov_b32_e32 v123, v2
	v_mov_b32_e32 v124, v2
	v_mov_b32_e32 v125, v2
	v_mov_b32_e32 v126, v2
	v_mov_b32_e32 v127, v2
	v_mov_b32_e32 v128, v2
	v_mov_b32_e32 v129, v2

.LBB0_1414:
	s_ashr_i32 s4, s34, 5
	v_readlane_b32 s0, v243, 52
	s_add_i32 s0, s4, s0
	s_ashr_i32 s1, s0, 31
	s_and_b32 s2, s29, 0xe0000
	s_lshl_b64 s[0:1], s[0:1], 20
	s_or_b32 s0, s0, s2
	s_lshl_b64 s[0:1], s[0:1], 1
	v_readlane_b32 s2, v245, 20
	s_add_u32 s2, s2, s0
	v_readlane_b32 s3, v245, 23
	s_addc_u32 s5, s3, s1
	s_and_b32 s3, s28, 0x180
	s_waitcnt vmcnt(0)
	v_mov_b32_e32 v155, v0
	s_lshl_b32 s3, s3, 1
	s_add_u32 s18, s2, s3
	v_ashrrev_i32_e32 v146, 4, v155
	v_lshlrev_b32_e32 v2, 3, v155
	v_and_b32_e32 v4, 0xfffff0, v146
	v_lshlrev_b32_e32 v5, 1, v146
	s_addc_u32 s19, s5, 0
	s_ashr_i32 s5, s4, 31
	v_and_b32_e32 v3, 0x78, v2
	v_and_or_b32 v4, v5, 8, v4
	v_lshrrev_b32_e32 v5, 1, v146
	v_and_b32_e32 v6, 3, v146
	v_add_u32_e32 v8, 32, v146
	s_lshl_b64 s[4:5], s[4:5], 19
	v_and_or_b32 v5, v5, 4, v6
	s_waitcnt vmcnt(0) lgkmcnt(0)
	v_lshlrev_b32_e32 v50, 1, v3
	v_and_b32_e32 v3, 0xfffff0, v8
	v_lshlrev_b32_e32 v6, 1, v8
	s_add_u32 s2, s22, s4
	v_and_or_b32 v3, v6, 8, v3
	s_addc_u32 s5, s23, s5
	v_lshrrev_b32_e32 v4, 1, v4
	v_bfe_u32 v2, v2, 5, 2
	v_lshrrev_b32_e32 v3, 1, v3
	s_add_u32 s4, s2, s3
	v_readfirstlane_b32 s2, v155
	v_or_b32_e32 v4, v4, v2
	v_or_b32_e32 v2, v3, v2
	s_addc_u32 s5, s5, 0
	s_ashr_i32 s35, s2, 6
	v_and_b32_e32 v1, 63, v155
	s_and_b32 s2, s2, 0x3fffffc0
	v_lshlrev_b32_e32 v6, 9, v2
	v_lshlrev_b32_e32 v2, 8, v146
	v_and_b32_e32 v3, 0x70, v155
	v_lshlrev_b32_e32 v154, 4, v155
	s_lshl_b32 s2, s2, 2
	v_bitop3_b32 v20, v50, v2, v3 bitop3:0xde
	v_lshlrev_b32_e32 v2, 3, v1
	v_and_b32_e32 v3, 0xc0, v154
	v_lshlrev_b32_e32 v7, 1, v155
	v_and_b32_e32 v156, 31, v155
	s_add_i32 s42, s2, 0
	v_and_or_b32 v3, v2, 24, v3
	v_and_b32_e32 v7, 32, v7
	v_and_b32_e32 v2, 0x100, v2
	s_lshl_b32 s2, s35, 5
	v_or3_b32 v7, v3, v7, v2
	v_or_b32_e32 v2, s2, v156
	v_ashrrev_i32_e32 v3, 31, v2
	v_bfe_u32 v157, v155, 5, 1
	v_lshlrev_b64 v[2:3], 10, v[2:3]
	v_lshl_add_u64 v[2:3], s[18:19], 0, v[2:3]
	v_lshlrev_b32_e32 v162, 4, v157
	v_lshl_add_u64 v[2:3], v[2:3], 0, v[162:163]
	v_ashrrev_i32_e32 v147, 31, v146
	v_ashrrev_i32_e32 v9, 31, v8
	v_lshlrev_b32_e32 v4, 9, v4
	v_lshlrev_b32_e32 v5, 6, v5
	global_load_dwordx4 v[126:129], v[2:3], off
	global_load_dwordx4 v[122:125], v[2:3], off offset:32
	global_load_dwordx4 v[118:121], v[2:3], off offset:64
	global_load_dwordx4 v[114:117], v[2:3], off offset:96
	global_load_dwordx4 v[110:113], v[2:3], off offset:128
	global_load_dwordx4 v[106:109], v[2:3], off offset:160
	global_load_dwordx4 v[102:105], v[2:3], off offset:192
	global_load_dwordx4 v[98:101], v[2:3], off offset:224
	v_and_b32_e32 v2, 48, v50
	v_lshlrev_b64 v[52:53], 11, v[146:147]
	v_lshlrev_b64 v[8:9], 11, v[8:9]
	v_or3_b32 v21, v4, v5, v2
	v_or3_b32 v22, v6, v5, v2
	v_mov_b32_e32 v51, v163
	v_lshl_add_u64 v[2:3], s[4:5], 0, v[52:53]
	v_lshl_add_u64 v[8:9], s[4:5], 0, v[8:9]
	v_lshl_add_u64 v[2:3], v[2:3], 0, v[50:51]
	v_lshl_add_u64 v[16:17], v[8:9], 0, v[50:51]
	v_add_u32_e32 v158, 0, v7
	global_load_dwordx4 v[4:7], v[2:3], off offset:1024
	global_load_dwordx4 v[8:11], v[16:17], off offset:1024
	global_load_dwordx4 v[12:15], v[2:3], off
	s_nop 0
	global_load_dwordx4 v[16:19], v[16:17], off
	v_add_u32_e32 v165, 0, v20
	v_add_u32_e32 v166, 0, v21
	s_mov_b64 s[8:9], 0x20000
	v_add_u32_e32 v167, 0, v22
	s_add_i32 s42, s42, 0x10000
	s_waitcnt vmcnt(1)
	ds_write_b128 v165, v[12:15] offset:32768
	s_waitcnt vmcnt(0)
	ds_write_b128 v165, v[16:19] offset:40960
	ds_write_b128 v166, v[4:7]
	v_lshl_add_u64 v[4:5], v[2:3], 0, s[8:9]
	s_mov_b64 s[8:9], 0x30000
	ds_write_b128 v167, v[8:11]
	s_waitcnt lgkmcnt(0)
	s_barrier
	global_load_dwordx4 v[34:37], v[4:5], off offset:1024
	v_lshl_add_u64 v[4:5], v[2:3], 0, s[8:9]
	s_mov_b32 s8, 0x20000
	global_load_dwordx4 v[38:41], v[4:5], off offset:1024
	v_add_co_u32_e32 v4, vcc, s8, v2
	s_mov_b32 s8, 0x30000
	s_nop 0
	v_addc_co_u32_e32 v5, vcc, 0, v3, vcc
	v_add_co_u32_e32 v2, vcc, s8, v2
	global_load_dwordx4 v[42:45], v[4:5], off
	s_nop 0
	v_addc_co_u32_e32 v3, vcc, 0, v3, vcc
	global_load_dwordx4 v[46:49], v[2:3], off
	s_movk_i32 s8, 0x70
	v_and_b32_e32 v2, 0x70, v154
	v_lshl_add_u32 v3, v156, 8, 0
	v_bitop3_b32 v4, v162, v154, s8 bitop3:0x78
	v_add_u32_e32 v168, v3, v4
	v_bitop3_b32 v4, v162, v2, 32 bitop3:0x36
	s_movk_i32 s8, 0x60
	v_add_u32_e32 v164, v3, v4
	v_bitop3_b32 v4, v162, v2, 64 bitop3:0x36
	v_bitop3_b32 v2, v162, v2, s8 bitop3:0x36
	v_add_u32_e32 v161, v3, v4
	v_add_u32_e32 v160, v3, v2
	ds_read_b128 v[2:5], v168 offset:32768
	ds_read_b128 v[18:21], v168 offset:40960
	s_waitcnt lgkmcnt(1)
	v_mfma_f32_32x32x16_bf16 v[2:17], v[2:5], v[126:129], 0
	ds_read_b128 v[54:57], v164 offset:32768
	ds_read_b128 v[58:61], v164 offset:40960
	v_lshl_add_u64 v[148:149], s[4:5], 0, v[50:51]
	s_mov_b64 s[4:5], 0x40000
	v_cmp_gt_u32_e64 s[38:39], 32, v1
	v_lshl_add_u32 v159, v156, 2, s42
	s_waitcnt lgkmcnt(2)
	v_mfma_f32_32x32x16_bf16 v[18:33], v[18:21], v[126:129], 0
	s_waitcnt lgkmcnt(1)
	v_mfma_f32_32x32x16_bf16 v[2:17], v[54:57], v[122:125], v[2:17]
	s_waitcnt lgkmcnt(0)
	v_mfma_f32_32x32x16_bf16 v[18:33], v[58:61], v[122:125], v[18:33]
	ds_read_b128 v[54:57], v161 offset:32768
	ds_read_b128 v[58:61], v161 offset:40960
	s_waitcnt lgkmcnt(1)
	v_mfma_f32_32x32x16_bf16 v[2:17], v[54:57], v[118:121], v[2:17]
	s_waitcnt lgkmcnt(0)
	v_mfma_f32_32x32x16_bf16 v[18:33], v[58:61], v[118:121], v[18:33]
	ds_read_b128 v[54:57], v160 offset:32768
	ds_read_b128 v[58:61], v160 offset:40960
	s_waitcnt lgkmcnt(1)
	v_mfma_f32_32x32x16_bf16 v[2:17], v[54:57], v[114:117], v[2:17]
	s_waitcnt lgkmcnt(0)
	v_mfma_f32_32x32x16_bf16 v[18:33], v[58:61], v[114:117], v[18:33]
	ds_read_b128 v[54:57], v168 offset:32896
	ds_read_b128 v[58:61], v168 offset:41088
	s_waitcnt lgkmcnt(1)
	v_mfma_f32_32x32x16_bf16 v[2:17], v[54:57], v[110:113], v[2:17]
	s_waitcnt lgkmcnt(0)
	v_mfma_f32_32x32x16_bf16 v[18:33], v[58:61], v[110:113], v[18:33]
	ds_read_b128 v[54:57], v164 offset:32896
	ds_read_b128 v[58:61], v164 offset:41088
	s_waitcnt lgkmcnt(1)
	v_mfma_f32_32x32x16_bf16 v[2:17], v[54:57], v[106:109], v[2:17]
	s_waitcnt lgkmcnt(0)
	v_mfma_f32_32x32x16_bf16 v[18:33], v[58:61], v[106:109], v[18:33]
	ds_read_b128 v[54:57], v161 offset:32896
	ds_read_b128 v[58:61], v161 offset:41088
	s_waitcnt lgkmcnt(1)
	v_mfma_f32_32x32x16_bf16 v[2:17], v[54:57], v[102:105], v[2:17]
	s_waitcnt lgkmcnt(0)
	v_mfma_f32_32x32x16_bf16 v[18:33], v[58:61], v[102:105], v[18:33]
	ds_read_b128 v[54:57], v160 offset:32896
	ds_read_b128 v[58:61], v160 offset:41088
	s_waitcnt vmcnt(1)
	ds_write_b128 v165, v[42:45] offset:49152
	s_waitcnt vmcnt(0)
	ds_write_b128 v165, v[46:49] offset:57344
	ds_write_b128 v166, v[34:37] offset:16384
	ds_write_b128 v167, v[38:41] offset:16384
	v_lshl_add_u64 v[34:35], v[148:149], 0, v[52:53]
	v_lshl_add_u64 v[36:37], v[34:35], 0, s[4:5]
	s_mov_b64 s[4:5], 0x50000
	s_waitcnt lgkmcnt(0)
	s_barrier
	v_mfma_f32_32x32x16_bf16 v[2:17], v[54:57], v[98:101], v[2:17]
	global_load_dwordx4 v[130:133], v[36:37], off offset:1024
	v_lshl_add_u64 v[36:37], v[34:35], 0, s[4:5]
	s_mov_b32 s4, 0x40000
	global_load_dwordx4 v[134:137], v[36:37], off offset:1024
	s_nop 7
	v_max_f32_e32 v54, v3, v3
	v_max_f32_e32 v55, v2, v2
	v_mfma_f32_32x32x16_bf16 v[18:33], v[58:61], v[98:101], v[18:33]
	v_max_f32_e32 v54, v55, v54
	v_max3_f32 v54, v54, v4, v5
	v_max3_f32 v54, v54, v6, v7
	v_max3_f32 v54, v54, v8, v9
	v_max3_f32 v54, v54, v10, v11
	v_max3_f32 v54, v54, v12, v13
	v_max3_f32 v54, v54, v14, v15
	v_max3_f32 v54, v54, v16, v17
	s_nop 3
	v_max3_f32 v54, v54, v18, v19
	v_max3_f32 v54, v54, v20, v21
	v_max3_f32 v54, v54, v22, v23
	v_max3_f32 v54, v54, v24, v25
	v_max3_f32 v54, v54, v26, v27
	v_max3_f32 v54, v54, v28, v29
	v_max3_f32 v54, v54, v30, v31
	v_max3_f32 v54, v54, v32, v33
	v_mov_b32_e32 v55, v54
	s_nop 1
	v_permlane32_swap_b32_e32 v54, v55
	v_max_f32_e32 v55, v55, v55
	v_max_f32_e32 v54, v54, v54
	v_max_f32_e32 v54, v54, v55
	v_add_f32_e32 v55, 0x7149f2ca, v54
	v_mul_f32_e32 v55, 0x3e0293ee, v55
	v_cmp_ge_f32_e32 vcc, s24, v55
	s_cmp_eq_u64 vcc, exec
	v_add_co_u32_e32 v36, vcc, s4, v34
	s_mov_b32 s4, 0x50000
	s_nop 0
	v_addc_co_u32_e32 v37, vcc, 0, v35, vcc
	v_add_co_u32_e32 v34, vcc, s4, v34
	global_load_dwordx4 v[138:141], v[36:37], off
	s_nop 0
	v_addc_co_u32_e32 v35, vcc, 0, v35, vcc
	global_load_dwordx4 v[142:145], v[34:35], off
	s_cselect_b64 s[36:37], -1, 0
	v_max_f32_e32 v151, 0xf149f2ca, v54
	v_cndmask_b32_e64 v150, v151, v177, s[36:37]
	v_mul_f32_e32 v54, 0xbe0293ee, v150
	v_fmamk_f32 v2, v2, 0x3e0293ee, v54
	v_fmamk_f32 v3, v3, 0x3e0293ee, v54
	v_fmamk_f32 v4, v4, 0x3e0293ee, v54
	v_fmamk_f32 v5, v5, 0x3e0293ee, v54
	v_fmamk_f32 v6, v6, 0x3e0293ee, v54
	v_fmamk_f32 v7, v7, 0x3e0293ee, v54
	v_fmamk_f32 v8, v8, 0x3e0293ee, v54
	v_fmamk_f32 v9, v9, 0x3e0293ee, v54
	v_fmamk_f32 v55, v10, 0x3e0293ee, v54
	v_fmamk_f32 v56, v11, 0x3e0293ee, v54
	v_fmamk_f32 v57, v12, 0x3e0293ee, v54
	v_fmamk_f32 v58, v13, 0x3e0293ee, v54
	v_fmamk_f32 v59, v14, 0x3e0293ee, v54
	v_fmamk_f32 v60, v15, 0x3e0293ee, v54
	v_fmamk_f32 v61, v16, 0x3e0293ee, v54
	v_fmamk_f32 v62, v17, 0x3e0293ee, v54
	v_exp_f32_e32 v10, v2
	v_exp_f32_e32 v11, v3
	v_exp_f32_e32 v12, v4
	v_exp_f32_e32 v13, v5
	v_exp_f32_e32 v14, v6
	v_exp_f32_e32 v15, v7
	v_exp_f32_e32 v16, v8
	v_exp_f32_e32 v17, v9
	v_exp_f32_e32 v2, v55
	v_exp_f32_e32 v3, v56
	v_exp_f32_e32 v4, v57
	v_exp_f32_e32 v5, v58
	v_exp_f32_e32 v6, v59
	v_exp_f32_e32 v7, v60
	v_exp_f32_e32 v8, v61
	v_exp_f32_e32 v9, v62
	v_fmamk_f32 v18, v18, 0x3e0293ee, v54
	v_fmamk_f32 v19, v19, 0x3e0293ee, v54
	v_fmamk_f32 v20, v20, 0x3e0293ee, v54
	v_fmamk_f32 v21, v21, 0x3e0293ee, v54
	v_fmamk_f32 v22, v22, 0x3e0293ee, v54
	v_fmamk_f32 v23, v23, 0x3e0293ee, v54
	v_fmamk_f32 v24, v24, 0x3e0293ee, v54
	v_fmamk_f32 v25, v25, 0x3e0293ee, v54
	v_fmamk_f32 v26, v26, 0x3e0293ee, v54
	v_fmamk_f32 v27, v27, 0x3e0293ee, v54
	v_fmamk_f32 v28, v28, 0x3e0293ee, v54
	v_fmamk_f32 v29, v29, 0x3e0293ee, v54
	v_fmamk_f32 v30, v30, 0x3e0293ee, v54
	v_fmamk_f32 v31, v31, 0x3e0293ee, v54
	v_fmamk_f32 v32, v32, 0x3e0293ee, v54
	v_fmac_f32_e32 v54, 0x3e0293ee, v33
	ds_read_b128 v[228:231], v168 offset:49152
	ds_read_b128 v[232:235], v168 offset:57344
	ds_read_b128 v[236:239], v164 offset:49152
	ds_read_b128 v[248:251], v164 offset:57344
	ds_read_b128 v[252:255], v161 offset:49152
	s_waitcnt lgkmcnt(4)
	v_mfma_f32_32x32x16_bf16 v[82:97], v[228:231], v[126:129], 0
	ds_read_b128 v[228:231], v161 offset:57344
	s_waitcnt lgkmcnt(4)
	v_mfma_f32_32x32x16_bf16 v[66:81], v[232:235], v[126:129], 0
	ds_read_b128 v[232:235], v160 offset:49152
	s_waitcnt lgkmcnt(4)
	v_mfma_f32_32x32x16_bf16 v[82:97], v[236:239], v[122:125], v[82:97]
	ds_read_b128 v[236:239], v160 offset:57344
	s_waitcnt lgkmcnt(4)
	v_mfma_f32_32x32x16_bf16 v[66:81], v[248:251], v[122:125], v[66:81]
	ds_read_b128 v[248:251], v168 offset:49280
	s_waitcnt lgkmcnt(4)
	v_mfma_f32_32x32x16_bf16 v[82:97], v[252:255], v[118:121], v[82:97]
	ds_read_b128 v[252:255], v168 offset:57472
	s_waitcnt lgkmcnt(4)
	v_mfma_f32_32x32x16_bf16 v[66:81], v[228:231], v[118:121], v[66:81]
	ds_read_b128 v[228:231], v164 offset:49280
	s_waitcnt lgkmcnt(4)
	v_mfma_f32_32x32x16_bf16 v[82:97], v[232:235], v[114:117], v[82:97]
	ds_read_b128 v[232:235], v164 offset:57472
	s_waitcnt lgkmcnt(4)
	v_mfma_f32_32x32x16_bf16 v[66:81], v[236:239], v[114:117], v[66:81]
	ds_read_b128 v[236:239], v161 offset:49280
	s_waitcnt lgkmcnt(4)
	v_mfma_f32_32x32x16_bf16 v[82:97], v[248:251], v[110:113], v[82:97]
	ds_read_b128 v[248:251], v161 offset:57472
	s_waitcnt lgkmcnt(4)
	v_mfma_f32_32x32x16_bf16 v[66:81], v[252:255], v[110:113], v[66:81]
	ds_read_b128 v[252:255], v160 offset:49280
	s_waitcnt lgkmcnt(4)
	v_mfma_f32_32x32x16_bf16 v[82:97], v[228:231], v[106:109], v[82:97]
	ds_read_b128 v[228:231], v160 offset:57472
	s_waitcnt lgkmcnt(4)
	v_mfma_f32_32x32x16_bf16 v[66:81], v[232:235], v[106:109], v[66:81]
	s_waitcnt lgkmcnt(3)
	v_mfma_f32_32x32x16_bf16 v[82:97], v[236:239], v[102:105], v[82:97]
	s_waitcnt lgkmcnt(2)
	v_mfma_f32_32x32x16_bf16 v[66:81], v[248:251], v[102:105], v[66:81]
	s_waitcnt lgkmcnt(1)
	v_mfma_f32_32x32x16_bf16 v[82:97], v[252:255], v[98:101], v[82:97]
	s_waitcnt lgkmcnt(0)
	v_mfma_f32_32x32x16_bf16 v[66:81], v[228:231], v[98:101], v[66:81]
	v_add_f32_e32 v34, 0, v10
	v_add_f32_e32 v34, v11, v34
	v_add_f32_e32 v34, v12, v34
	v_add_f32_e32 v34, v13, v34
	v_add_f32_e32 v34, v14, v34
	v_add_f32_e32 v34, v15, v34
	v_add_f32_e32 v34, v16, v34
	v_add_f32_e32 v34, v17, v34
	v_add_f32_e32 v34, v2, v34
	v_add_f32_e32 v34, v3, v34
	v_add_f32_e32 v34, v4, v34
	v_add_f32_e32 v34, v5, v34
	v_exp_f32_e32 v18, v18
	v_add_f32_e32 v34, v6, v34
	v_exp_f32_e32 v19, v19
	v_add_f32_e32 v34, v7, v34
	v_exp_f32_e32 v20, v20
	v_add_f32_e32 v34, v8, v34
	v_exp_f32_e32 v21, v21
	v_add_f32_e32 v34, v9, v34
	v_exp_f32_e32 v22, v22
	v_add_f32_e32 v34, v18, v34
	v_exp_f32_e32 v23, v23
	v_add_f32_e32 v34, v19, v34
	v_exp_f32_e32 v24, v24
	v_add_f32_e32 v34, v20, v34
	v_exp_f32_e32 v25, v25
	v_add_f32_e32 v34, v21, v34
	v_exp_f32_e32 v26, v26
	v_add_f32_e32 v34, v22, v34
	v_exp_f32_e32 v27, v27
	v_add_f32_e32 v34, v23, v34
	v_exp_f32_e32 v28, v28
	v_add_f32_e32 v34, v24, v34
	v_exp_f32_e32 v29, v29
	v_add_f32_e32 v34, v25, v34
	v_exp_f32_e32 v30, v30
	v_add_f32_e32 v34, v26, v34
	v_exp_f32_e32 v31, v31
	v_add_f32_e32 v34, v27, v34
	v_exp_f32_e32 v32, v32
	v_add_f32_e32 v34, v28, v34
	v_exp_f32_e32 v33, v54
	v_add_f32_e32 v34, v29, v34
	v_add_f32_e32 v34, v30, v34
	v_add_f32_e32 v34, v31, v34
	v_add_f32_e32 v34, v32, v34
	v_add_f32_e32 v169, v33, v34
	v_mov_b32_e32 v179, v169
	v_cvt_pk_bf16_f32 v50, v10, v11
	v_cvt_pk_bf16_f32 v51, v12, v13
	v_cvt_pk_bf16_f32 v52, v14, v15
	v_cvt_pk_bf16_f32 v53, v16, v17
	v_cvt_pk_bf16_f32 v180, v2, v3
	v_cvt_pk_bf16_f32 v181, v4, v5
	v_cvt_pk_bf16_f32 v182, v6, v7
	s_nop 1
	v_permlane32_swap_b32_e32 v169, v179
	v_permlane32_swap_b32_e32 v50, v52
	v_permlane32_swap_b32_e32 v51, v53
	v_cvt_pk_bf16_f32 v183, v8, v9
	v_permlane32_swap_b32_e32 v180, v182
	v_cvt_pk_bf16_f32 v184, v18, v19
	v_cvt_pk_bf16_f32 v185, v20, v21
	v_cvt_pk_bf16_f32 v186, v22, v23
	v_cvt_pk_bf16_f32 v187, v24, v25
	v_cvt_pk_bf16_f32 v188, v26, v27
	v_cvt_pk_bf16_f32 v189, v28, v29
	v_cvt_pk_bf16_f32 v190, v30, v31
	v_cvt_pk_bf16_f32 v191, v32, v33
	v_permlane32_swap_b32_e32 v181, v183
	v_permlane32_swap_b32_e32 v184, v186
	v_permlane32_swap_b32_e32 v185, v187
	v_permlane32_swap_b32_e32 v188, v190
	v_permlane32_swap_b32_e32 v189, v191
	ds_read_b64_tr_b16 v[2:3], v158 offset:0
	ds_read_b64_tr_b16 v[4:5], v158 offset:0x800
	ds_read_b64_tr_b16 v[18:19], v158 offset:0x1000
	ds_read_b64_tr_b16 v[20:21], v158 offset:0x1800
	ds_read_b64_tr_b16 v[22:23], v158 offset:0x2000
	ds_read_b64_tr_b16 v[24:25], v158 offset:0x2800
	ds_read_b64_tr_b16 v[26:27], v158 offset:0x3000
	ds_read_b64_tr_b16 v[28:29], v158 offset:0x3800
	s_waitcnt lgkmcnt(0)
	s_nop 0
	v_mfma_f32_32x32x16_bf16 v[2:17], v[50:53], v[2:5], 0
	v_mfma_f32_32x32x16_bf16 v[2:17], v[180:183], v[18:21], v[2:17]
	ds_read_b64_tr_b16 v[18:19], v158 offset:0x200
	ds_read_b64_tr_b16 v[20:21], v158 offset:0xa00
	ds_read_b64_tr_b16 v[34:35], v158 offset:0x1200
	ds_read_b64_tr_b16 v[36:37], v158 offset:0x1a00
	ds_read_b64_tr_b16 v[38:39], v158 offset:0x2200
	ds_read_b64_tr_b16 v[40:41], v158 offset:0x2a00
	ds_read_b64_tr_b16 v[42:43], v158 offset:0x3200
	v_mfma_f32_32x32x16_bf16 v[2:17], v[184:187], v[22:25], v[2:17]
	ds_read_b64_tr_b16 v[44:45], v158 offset:0x3a00
	s_waitcnt lgkmcnt(0)
	v_mfma_f32_32x32x16_bf16 v[2:17], v[188:191], v[26:29], v[2:17]
	v_mfma_f32_32x32x16_bf16 v[18:33], v[50:53], v[18:21], 0
	v_mfma_f32_32x32x16_bf16 v[18:33], v[180:183], v[34:37], v[18:33]
	ds_read_b64_tr_b16 v[34:35], v158 offset:0x400
	ds_read_b64_tr_b16 v[36:37], v158 offset:0xc00
	ds_read_b64_tr_b16 v[54:55], v158 offset:0x1400
	ds_read_b64_tr_b16 v[56:57], v158 offset:0x1c00
	ds_read_b64_tr_b16 v[58:59], v158 offset:0x2400
	ds_read_b64_tr_b16 v[60:61], v158 offset:0x2c00
	ds_read_b64_tr_b16 v[62:63], v158 offset:0x3400
	v_mfma_f32_32x32x16_bf16 v[18:33], v[184:187], v[38:41], v[18:33]
	ds_read_b64_tr_b16 v[64:65], v158 offset:0x3c00
	s_waitcnt lgkmcnt(0)
	v_mfma_f32_32x32x16_bf16 v[18:33], v[188:191], v[42:45], v[18:33]
	v_mfma_f32_32x32x16_bf16 v[34:49], v[50:53], v[34:37], 0
	v_mfma_f32_32x32x16_bf16 v[34:49], v[180:183], v[54:57], v[34:49]
	ds_read_b64_tr_b16 v[54:55], v158 offset:0x600
	ds_read_b64_tr_b16 v[56:57], v158 offset:0xe00
	ds_read_b64_tr_b16 v[192:193], v158 offset:0x1600
	ds_read_b64_tr_b16 v[194:195], v158 offset:0x1e00
	ds_read_b64_tr_b16 v[196:197], v158 offset:0x2600
	ds_read_b64_tr_b16 v[198:199], v158 offset:0x2e00
	ds_read_b64_tr_b16 v[200:201], v158 offset:0x3600
	v_mfma_f32_32x32x16_bf16 v[34:49], v[184:187], v[58:61], v[34:49]
	ds_read_b64_tr_b16 v[202:203], v158 offset:0x3e00
	s_waitcnt lgkmcnt(0)
	v_mfma_f32_32x32x16_bf16 v[34:49], v[188:191], v[62:65], v[34:49]
	v_mfma_f32_32x32x16_bf16 v[50:65], v[50:53], v[54:57], 0
	v_mfma_f32_32x32x16_bf16 v[50:65], v[180:183], v[192:195], v[50:65]
	v_mfma_f32_32x32x16_bf16 v[50:65], v[184:187], v[196:199], v[50:65]
	v_mfma_f32_32x32x16_bf16 v[50:65], v[188:191], v[200:203], v[50:65]
	v_max_f32_e32 v152, v83, v83
	v_max_f32_e32 v153, v82, v82
	v_max_f32_e32 v152, v153, v152
	v_max3_f32 v152, v152, v84, v85
	v_max3_f32 v152, v152, v86, v87
	v_max3_f32 v152, v152, v88, v89
	v_max3_f32 v152, v152, v90, v91
	v_max3_f32 v152, v152, v92, v93
	v_max3_f32 v152, v152, v94, v95
	v_max3_f32 v152, v152, v96, v97
	v_max3_f32 v152, v152, v66, v67
	v_max3_f32 v152, v152, v68, v69
	v_max3_f32 v152, v152, v70, v71
	v_max3_f32 v152, v152, v72, v73
	v_max3_f32 v152, v152, v74, v75
	v_max3_f32 v152, v152, v76, v77
	v_max3_f32 v152, v152, v78, v79
	v_max3_f32 v152, v152, v80, v81
	v_mov_b32_e32 v153, v152
	s_nop 1
	v_permlane32_swap_b32_e32 v152, v153
	v_max_f32_e32 v153, v153, v153
	v_max_f32_e32 v152, v152, v152
	v_max_f32_e32 v152, v152, v153
	v_sub_f32_e32 v153, v152, v150
	v_mul_f32_e32 v153, 0x3e0293ee, v153
	v_max_f32_e32 v152, v150, v152
	v_cmp_ge_f32_e32 vcc, s24, v153
	v_sub_f32_e32 v153, v150, v152
	v_mul_f32_e32 v153, 0x3e0293ee, v153
	v_exp_f32_e32 v153, v153
	s_cmp_eq_u64 vcc, exec
	s_cselect_b64 s[40:41], -1, 0
	v_cndmask_b32_e64 v180, v153, 1.0, s[40:41]
	v_cmp_gt_f32_e32 vcc, 1.0, v180
	s_barrier
	s_waitcnt vmcnt(1)
	ds_write_b128 v165, v[138:141] offset:32768
	s_waitcnt vmcnt(0)
	ds_write_b128 v165, v[142:145] offset:40960
	ds_write_b128 v166, v[130:133]
	ds_write_b128 v167, v[134:137]
	s_cbranch_vccz .LBB0_1418
	s_and_saveexec_b64 s[4:5], s[38:39]
	ds_write_b32 v159, v180 offset:128
	s_or_b64 exec, exec, s[4:5]
	s_waitcnt lgkmcnt(0)
	v_add_u32_e32 v142, s42, v162
	ds_read_b128 v[130:133], v142 offset:224
	ds_read_b128 v[134:137], v142 offset:192
	ds_read_b128 v[138:141], v142 offset:160
	ds_read_b128 v[142:145], v142 offset:128
	s_waitcnt lgkmcnt(3)
	v_pk_mul_f32 v[14:15], v[14:15], v[130:131]
	s_waitcnt lgkmcnt(2)
	v_pk_mul_f32 v[10:11], v[10:11], v[134:135]
	s_waitcnt lgkmcnt(1)
	v_pk_mul_f32 v[6:7], v[6:7], v[138:139]
	v_pk_mul_f32 v[16:17], v[16:17], v[132:133]
	v_pk_mul_f32 v[12:13], v[12:13], v[136:137]
	v_pk_mul_f32 v[8:9], v[8:9], v[140:141]
	s_waitcnt lgkmcnt(0)
	v_pk_mul_f32 v[4:5], v[4:5], v[144:145]
	v_pk_mul_f32 v[2:3], v[2:3], v[142:143]
	v_pk_mul_f32 v[30:31], v[30:31], v[130:131]
	v_pk_mul_f32 v[26:27], v[26:27], v[134:135]
	v_pk_mul_f32 v[22:23], v[22:23], v[138:139]
	v_pk_mul_f32 v[32:33], v[32:33], v[132:133]
	v_pk_mul_f32 v[28:29], v[28:29], v[136:137]
	v_pk_mul_f32 v[24:25], v[24:25], v[140:141]
	v_pk_mul_f32 v[20:21], v[20:21], v[144:145]
	v_pk_mul_f32 v[18:19], v[18:19], v[142:143]
	v_pk_mul_f32 v[46:47], v[46:47], v[130:131]
	v_pk_mul_f32 v[42:43], v[42:43], v[134:135]
	v_pk_mul_f32 v[38:39], v[38:39], v[138:139]
	v_pk_mul_f32 v[48:49], v[48:49], v[132:133]
	v_pk_mul_f32 v[44:45], v[44:45], v[136:137]
	v_pk_mul_f32 v[40:41], v[40:41], v[140:141]
	v_pk_mul_f32 v[36:37], v[36:37], v[144:145]
	v_pk_mul_f32 v[34:35], v[34:35], v[142:143]
	v_pk_mul_f32 v[62:63], v[62:63], v[130:131]
	v_pk_mul_f32 v[58:59], v[58:59], v[134:135]
	v_pk_mul_f32 v[54:55], v[54:55], v[138:139]
	v_pk_mul_f32 v[64:65], v[64:65], v[132:133]
	v_pk_mul_f32 v[60:61], v[60:61], v[136:137]
	v_pk_mul_f32 v[56:57], v[56:57], v[140:141]
	v_pk_mul_f32 v[52:53], v[52:53], v[144:145]
	v_pk_mul_f32 v[50:51], v[50:51], v[142:143]
.LBB0_1418:
	v_cndmask_b32_e64 v184, v152, v150, s[40:41]
	v_mul_f32_e32 v182, 0xbe0293ee, v184
	v_fmamk_f32 v183, v66, 0x3e0293ee, v182
	v_fmamk_f32 v66, v83, 0x3e0293ee, v182
	v_fmamk_f32 v197, v67, 0x3e0293ee, v182
	v_fmamk_f32 v67, v84, 0x3e0293ee, v182
	v_exp_f32_e32 v196, v66
	v_exp_f32_e32 v192, v67
	v_lshlrev_b64 v[66:67], 11, v[146:147]
	v_sub_f32_e32 v130, 0xf149f2ca, v151
	v_fmamk_f32 v198, v68, 0x3e0293ee, v182
	v_fmamk_f32 v68, v85, 0x3e0293ee, v182
	v_fmamk_f32 v199, v69, 0x3e0293ee, v182
	v_fmamk_f32 v69, v86, 0x3e0293ee, v182
	v_lshl_add_u64 v[66:67], v[148:149], 0, v[66:67]
	s_mov_b64 s[4:5], 0x60000
	v_mul_f32_e32 v130, 0x3e0293ee, v130
	v_fmamk_f32 v200, v70, 0x3e0293ee, v182
	v_fmamk_f32 v70, v87, 0x3e0293ee, v182
	v_fmamk_f32 v201, v71, 0x3e0293ee, v182
	v_fmamk_f32 v71, v88, 0x3e0293ee, v182
	v_exp_f32_e32 v195, v68
	v_exp_f32_e32 v190, v69
	v_lshl_add_u64 v[68:69], v[66:67], 0, s[4:5]
	s_mov_b64 s[4:5], 0x70000
	v_exp_f32_e32 v181, v130
	v_exp_f32_e32 v193, v70
	v_exp_f32_e32 v189, v71
	s_waitcnt lgkmcnt(0)
	s_barrier
	v_lshl_add_u64 v[70:71], v[66:67], 0, s[4:5]
	global_load_dwordx4 v[130:133], v[68:69], off offset:1024
	global_load_dwordx4 v[134:137], v[70:71], off offset:1024
	v_add_co_u32_e32 v68, vcc, 0x60000, v66
	s_mov_b32 s4, 0x70000
	s_nop 0
	v_addc_co_u32_e32 v69, vcc, 0, v67, vcc
	v_add_co_u32_e32 v66, vcc, s4, v66
	v_fmamk_f32 v82, v82, 0x3e0293ee, v182
	s_nop 0
	v_addc_co_u32_e32 v67, vcc, 0, v67, vcc
	global_load_dwordx4 v[138:141], v[68:69], off
	global_load_dwordx4 v[142:145], v[66:67], off
	v_fmamk_f32 v202, v72, 0x3e0293ee, v182
	v_fmamk_f32 v72, v89, 0x3e0293ee, v182
	v_fmamk_f32 v203, v73, 0x3e0293ee, v182
	v_fmamk_f32 v73, v90, 0x3e0293ee, v182
	v_fmamk_f32 v204, v74, 0x3e0293ee, v182
	v_fmamk_f32 v74, v91, 0x3e0293ee, v182
	v_fmamk_f32 v205, v75, 0x3e0293ee, v182
	v_fmamk_f32 v75, v92, 0x3e0293ee, v182
	v_fmamk_f32 v206, v76, 0x3e0293ee, v182
	v_fmamk_f32 v76, v93, 0x3e0293ee, v182
	v_fmamk_f32 v207, v77, 0x3e0293ee, v182
	v_fmamk_f32 v77, v94, 0x3e0293ee, v182
	v_fmamk_f32 v208, v78, 0x3e0293ee, v182
	v_fmamk_f32 v78, v95, 0x3e0293ee, v182
	v_fmamk_f32 v83, v96, 0x3e0293ee, v182
	v_fmamk_f32 v84, v97, 0x3e0293ee, v182
	v_fmamk_f32 v209, v79, 0x3e0293ee, v182
	v_fmamk_f32 v210, v80, 0x3e0293ee, v182
	v_fmac_f32_e32 v182, 0x3e0293ee, v81
	v_exp_f32_e32 v194, v82
	v_exp_f32_e32 v191, v72
	v_exp_f32_e32 v150, v73
	v_exp_f32_e32 v188, v74
	v_exp_f32_e32 v151, v75
	v_exp_f32_e32 v187, v76
	v_exp_f32_e32 v152, v77
	v_exp_f32_e32 v186, v78
	v_exp_f32_e32 v153, v83
	v_exp_f32_e32 v185, v84
	ds_read_b128 v[228:231], v168 offset:32768
	ds_read_b128 v[232:235], v164 offset:32768
	ds_read_b128 v[236:239], v168 offset:40960
	ds_read_b128 v[248:251], v164 offset:40960
	ds_read_b128 v[252:255], v161 offset:32768
	s_waitcnt lgkmcnt(4)
	v_mfma_f32_32x32x16_bf16 v[82:97], v[228:231], v[126:129], 0
	ds_read_b128 v[228:231], v161 offset:40960
	s_waitcnt lgkmcnt(4)
	v_mfma_f32_32x32x16_bf16 v[82:97], v[232:235], v[122:125], v[82:97]
	ds_read_b128 v[232:235], v160 offset:32768
	s_waitcnt lgkmcnt(4)
	v_mfma_f32_32x32x16_bf16 v[66:81], v[236:239], v[126:129], 0
	ds_read_b128 v[236:239], v160 offset:40960
	s_waitcnt lgkmcnt(4)
	v_mfma_f32_32x32x16_bf16 v[66:81], v[248:251], v[122:125], v[66:81]
	ds_read_b128 v[248:251], v168 offset:32896
	s_waitcnt lgkmcnt(4)
	v_mfma_f32_32x32x16_bf16 v[82:97], v[252:255], v[118:121], v[82:97]
	ds_read_b128 v[252:255], v168 offset:41088
	s_waitcnt lgkmcnt(4)
	v_mfma_f32_32x32x16_bf16 v[66:81], v[228:231], v[118:121], v[66:81]
	ds_read_b128 v[228:231], v164 offset:32896
	s_waitcnt lgkmcnt(4)
	v_mfma_f32_32x32x16_bf16 v[82:97], v[232:235], v[114:117], v[82:97]
	ds_read_b128 v[232:235], v164 offset:41088
	s_waitcnt lgkmcnt(4)
	v_mfma_f32_32x32x16_bf16 v[66:81], v[236:239], v[114:117], v[66:81]
	ds_read_b128 v[236:239], v161 offset:32896
	s_waitcnt lgkmcnt(4)
	v_mfma_f32_32x32x16_bf16 v[82:97], v[248:251], v[110:113], v[82:97]
	ds_read_b128 v[248:251], v161 offset:41088
	s_waitcnt lgkmcnt(4)
	v_mfma_f32_32x32x16_bf16 v[66:81], v[252:255], v[110:113], v[66:81]
	ds_read_b128 v[252:255], v160 offset:32896
	s_waitcnt lgkmcnt(4)
	v_mfma_f32_32x32x16_bf16 v[82:97], v[228:231], v[106:109], v[82:97]
	ds_read_b128 v[228:231], v160 offset:41088
	s_waitcnt lgkmcnt(4)
	v_mfma_f32_32x32x16_bf16 v[66:81], v[232:235], v[106:109], v[66:81]
	s_waitcnt lgkmcnt(3)
	v_mfma_f32_32x32x16_bf16 v[82:97], v[236:239], v[102:105], v[82:97]
	s_waitcnt lgkmcnt(2)
	v_mfma_f32_32x32x16_bf16 v[66:81], v[248:251], v[102:105], v[66:81]
	s_waitcnt lgkmcnt(1)
	v_mfma_f32_32x32x16_bf16 v[82:97], v[252:255], v[98:101], v[82:97]
	s_waitcnt lgkmcnt(0)
	v_mfma_f32_32x32x16_bf16 v[66:81], v[228:231], v[98:101], v[66:81]
	v_add_f32_e32 v146, 0, v194
	v_add_f32_e32 v146, v196, v146
	v_add_f32_e32 v146, v192, v146
	v_add_f32_e32 v146, v195, v146
	v_add_f32_e32 v146, v190, v146
	v_add_f32_e32 v146, v193, v146
	v_add_f32_e32 v146, v189, v146
	v_add_f32_e32 v146, v191, v146
	v_add_f32_e32 v146, v150, v146
	v_add_f32_e32 v146, v188, v146
	v_add_f32_e32 v146, v151, v146
	v_add_f32_e32 v146, v187, v146
	v_exp_f32_e32 v211, v183
	v_add_f32_e32 v146, v152, v146
	v_exp_f32_e32 v197, v197
	v_add_f32_e32 v146, v186, v146
	v_exp_f32_e32 v198, v198
	v_add_f32_e32 v146, v153, v146
	v_exp_f32_e32 v199, v199
	v_add_f32_e32 v146, v185, v146
	v_exp_f32_e32 v200, v200
	v_add_f32_e32 v146, v211, v146
	v_exp_f32_e32 v201, v201
	v_add_f32_e32 v146, v197, v146
	v_exp_f32_e32 v202, v202
	v_add_f32_e32 v146, v198, v146
	v_exp_f32_e32 v203, v203
	v_add_f32_e32 v146, v199, v146
	v_exp_f32_e32 v204, v204
	v_add_f32_e32 v146, v200, v146
	v_exp_f32_e32 v205, v205
	v_add_f32_e32 v146, v201, v146
	v_exp_f32_e32 v206, v206
	v_add_f32_e32 v146, v202, v146
	v_exp_f32_e32 v207, v207
	v_add_f32_e32 v146, v203, v146
	v_exp_f32_e32 v208, v208
	v_add_f32_e32 v146, v204, v146
	v_exp_f32_e32 v209, v209
	v_add_f32_e32 v146, v205, v146
	v_exp_f32_e32 v210, v210
	v_add_f32_e32 v146, v206, v146
	v_exp_f32_e32 v212, v182
	v_add_f32_e32 v146, v207, v146
	v_add_f32_e32 v146, v208, v146
	v_add_f32_e32 v146, v209, v146
	v_add_f32_e32 v146, v210, v146
	v_add_f32_e32 v182, v212, v146
	v_mov_b32_e32 v183, v182
	v_cvt_pk_bf16_f32 v146, v194, v196
	v_cvt_pk_bf16_f32 v147, v192, v195
	v_cvt_pk_bf16_f32 v148, v190, v193
	v_cvt_pk_bf16_f32 v149, v189, v191
	s_nop 1
	v_permlane32_swap_b32_e32 v182, v183
	v_permlane32_swap_b32_e32 v146, v148
	v_permlane32_swap_b32_e32 v147, v149
	v_cvt_pk_bf16_f32 v150, v150, v188
	v_cvt_pk_bf16_f32 v151, v151, v187
	v_cvt_pk_bf16_f32 v152, v152, v186
	v_cvt_pk_bf16_f32 v153, v153, v185
	v_cvt_pk_bf16_f32 v186, v211, v197
	v_cvt_pk_bf16_f32 v187, v198, v199
	v_cvt_pk_bf16_f32 v188, v200, v201
	v_cvt_pk_bf16_f32 v189, v202, v203
	v_cvt_pk_bf16_f32 v190, v204, v205
	v_cvt_pk_bf16_f32 v191, v206, v207
	v_cvt_pk_bf16_f32 v192, v208, v209
	v_cvt_pk_bf16_f32 v193, v210, v212
	s_nop 0
	v_permlane32_swap_b32_e32 v150, v152
	v_permlane32_swap_b32_e32 v151, v153
	v_permlane32_swap_b32_e32 v186, v188
	v_permlane32_swap_b32_e32 v187, v189
	v_permlane32_swap_b32_e32 v190, v192
	v_permlane32_swap_b32_e32 v191, v193
	ds_read_b64_tr_b16 v[194:195], v158 offset:0x4000
	ds_read_b64_tr_b16 v[196:197], v158 offset:0x4800
	ds_read_b64_tr_b16 v[198:199], v158 offset:0x5000
	ds_read_b64_tr_b16 v[200:201], v158 offset:0x5800
	ds_read_b64_tr_b16 v[202:203], v158 offset:0x6000
	ds_read_b64_tr_b16 v[204:205], v158 offset:0x6800
	ds_read_b64_tr_b16 v[206:207], v158 offset:0x7000
	ds_read_b64_tr_b16 v[208:209], v158 offset:0x7800
	s_waitcnt lgkmcnt(0)
	s_nop 0
	v_mfma_f32_32x32x16_bf16 v[2:17], v[146:149], v[194:197], v[2:17]
	ds_read_b64_tr_b16 v[194:195], v158 offset:0x4200
	ds_read_b64_tr_b16 v[196:197], v158 offset:0x4a00
	v_mfma_f32_32x32x16_bf16 v[2:17], v[150:153], v[198:201], v[2:17]
	ds_read_b64_tr_b16 v[198:199], v158 offset:0x5200
	ds_read_b64_tr_b16 v[200:201], v158 offset:0x5a00
	v_mfma_f32_32x32x16_bf16 v[2:17], v[186:189], v[202:205], v[2:17]
	ds_read_b64_tr_b16 v[202:203], v158 offset:0x6200
	ds_read_b64_tr_b16 v[204:205], v158 offset:0x6a00
	v_mfma_f32_32x32x16_bf16 v[2:17], v[190:193], v[206:209], v[2:17]
	ds_read_b64_tr_b16 v[206:207], v158 offset:0x7200
	ds_read_b64_tr_b16 v[208:209], v158 offset:0x7a00
	s_waitcnt lgkmcnt(0)
	v_mfma_f32_32x32x16_bf16 v[18:33], v[146:149], v[194:197], v[18:33]
	ds_read_b64_tr_b16 v[194:195], v158 offset:0x4400
	ds_read_b64_tr_b16 v[196:197], v158 offset:0x4c00
	v_mfma_f32_32x32x16_bf16 v[18:33], v[150:153], v[198:201], v[18:33]
	ds_read_b64_tr_b16 v[198:199], v158 offset:0x5400
	ds_read_b64_tr_b16 v[200:201], v158 offset:0x5c00
	v_mfma_f32_32x32x16_bf16 v[18:33], v[186:189], v[202:205], v[18:33]
	ds_read_b64_tr_b16 v[202:203], v158 offset:0x6400
	ds_read_b64_tr_b16 v[204:205], v158 offset:0x6c00
	v_mfma_f32_32x32x16_bf16 v[18:33], v[190:193], v[206:209], v[18:33]
	ds_read_b64_tr_b16 v[206:207], v158 offset:0x7400
	ds_read_b64_tr_b16 v[208:209], v158 offset:0x7c00
	s_waitcnt lgkmcnt(0)
	v_mfma_f32_32x32x16_bf16 v[34:49], v[146:149], v[194:197], v[34:49]
	ds_read_b64_tr_b16 v[194:195], v158 offset:0x4600
	ds_read_b64_tr_b16 v[196:197], v158 offset:0x4e00
	v_mfma_f32_32x32x16_bf16 v[34:49], v[150:153], v[198:201], v[34:49]
	ds_read_b64_tr_b16 v[198:199], v158 offset:0x5600
	ds_read_b64_tr_b16 v[200:201], v158 offset:0x5e00
	v_mfma_f32_32x32x16_bf16 v[34:49], v[186:189], v[202:205], v[34:49]
	ds_read_b64_tr_b16 v[202:203], v158 offset:0x6600
	ds_read_b64_tr_b16 v[204:205], v158 offset:0x6e00
	v_mfma_f32_32x32x16_bf16 v[34:49], v[190:193], v[206:209], v[34:49]
	ds_read_b64_tr_b16 v[206:207], v158 offset:0x7600
	ds_read_b64_tr_b16 v[208:209], v158 offset:0x7e00
	s_waitcnt lgkmcnt(0)
	v_mfma_f32_32x32x16_bf16 v[50:65], v[146:149], v[194:197], v[50:65]
	v_mfma_f32_32x32x16_bf16 v[50:65], v[150:153], v[198:201], v[50:65]
	v_mfma_f32_32x32x16_bf16 v[50:65], v[186:189], v[202:205], v[50:65]
	v_mfma_f32_32x32x16_bf16 v[50:65], v[190:193], v[206:209], v[50:65]
	v_max_f32_e32 v146, v83, v83
	v_max_f32_e32 v147, v82, v82
	v_max_f32_e32 v146, v147, v146
	v_max3_f32 v146, v146, v84, v85
	v_max3_f32 v146, v146, v86, v87
	v_max3_f32 v146, v146, v88, v89
	v_max3_f32 v146, v146, v90, v91
	v_max3_f32 v146, v146, v92, v93
	v_max3_f32 v146, v146, v94, v95
	v_max3_f32 v146, v146, v96, v97
	v_max3_f32 v146, v146, v66, v67
	v_max3_f32 v146, v146, v68, v69
	v_max3_f32 v146, v146, v70, v71
	v_max3_f32 v146, v146, v72, v73
	v_max3_f32 v146, v146, v74, v75
	v_max3_f32 v146, v146, v76, v77
	v_max3_f32 v146, v146, v78, v79
	v_max3_f32 v146, v146, v80, v81
	v_mov_b32_e32 v147, v146
	s_nop 1
	v_permlane32_swap_b32_e32 v146, v147
	v_max_f32_e32 v147, v147, v147
	v_max_f32_e32 v146, v146, v146
	v_max_f32_e32 v146, v146, v147
	v_sub_f32_e32 v147, v146, v184
	v_mul_f32_e32 v147, 0x3e0293ee, v147
	v_cmp_ge_f32_e32 vcc, s24, v147
	v_max_f32_e32 v147, v184, v184
	v_max_f32_e32 v147, v147, v146
	v_sub_f32_e32 v146, v184, v147
	v_mul_f32_e32 v146, 0x3e0293ee, v146
	v_exp_f32_e32 v146, v146
	s_cmp_eq_u64 vcc, exec
	s_cselect_b64 s[40:41], -1, 0
	v_cndmask_b32_e64 v146, v146, 1.0, s[40:41]
	v_cmp_gt_f32_e32 vcc, 1.0, v146
	s_barrier
	s_waitcnt vmcnt(1)
	ds_write_b128 v165, v[138:141] offset:49152
	s_waitcnt vmcnt(0)
	ds_write_b128 v165, v[142:145] offset:57344
	ds_write_b128 v166, v[130:133] offset:16384
	ds_write_b128 v167, v[134:137] offset:16384
	s_cbranch_vccz .LBB0_1422
	s_and_saveexec_b64 s[4:5], s[38:39]
	ds_write_b32 v159, v146 offset:128
	s_or_b64 exec, exec, s[4:5]
	s_waitcnt lgkmcnt(0)
	v_add_u32_e32 v142, s42, v162
	ds_read_b128 v[130:133], v142 offset:224
	ds_read_b128 v[134:137], v142 offset:192
	ds_read_b128 v[138:141], v142 offset:160
	ds_read_b128 v[142:145], v142 offset:128
	s_waitcnt lgkmcnt(3)
	v_pk_mul_f32 v[14:15], v[14:15], v[130:131]
	s_waitcnt lgkmcnt(2)
	v_pk_mul_f32 v[10:11], v[10:11], v[134:135]
	s_waitcnt lgkmcnt(1)
	v_pk_mul_f32 v[6:7], v[6:7], v[138:139]
	v_pk_mul_f32 v[16:17], v[16:17], v[132:133]
	v_pk_mul_f32 v[12:13], v[12:13], v[136:137]
	v_pk_mul_f32 v[8:9], v[8:9], v[140:141]
	s_waitcnt lgkmcnt(0)
	v_pk_mul_f32 v[4:5], v[4:5], v[144:145]
	v_pk_mul_f32 v[2:3], v[2:3], v[142:143]
	v_pk_mul_f32 v[30:31], v[30:31], v[130:131]
	v_pk_mul_f32 v[26:27], v[26:27], v[134:135]
	v_pk_mul_f32 v[22:23], v[22:23], v[138:139]
	v_pk_mul_f32 v[32:33], v[32:33], v[132:133]
	v_pk_mul_f32 v[28:29], v[28:29], v[136:137]
	v_pk_mul_f32 v[24:25], v[24:25], v[140:141]
	v_pk_mul_f32 v[20:21], v[20:21], v[144:145]
	v_pk_mul_f32 v[18:19], v[18:19], v[142:143]
	v_pk_mul_f32 v[46:47], v[46:47], v[130:131]
	v_pk_mul_f32 v[42:43], v[42:43], v[134:135]
	v_pk_mul_f32 v[38:39], v[38:39], v[138:139]
	v_pk_mul_f32 v[48:49], v[48:49], v[132:133]
	v_pk_mul_f32 v[44:45], v[44:45], v[136:137]
	v_pk_mul_f32 v[40:41], v[40:41], v[140:141]
	v_pk_mul_f32 v[36:37], v[36:37], v[144:145]
	v_pk_mul_f32 v[34:35], v[34:35], v[142:143]
	v_pk_mul_f32 v[62:63], v[62:63], v[130:131]
	v_pk_mul_f32 v[58:59], v[58:59], v[134:135]
	v_pk_mul_f32 v[54:55], v[54:55], v[138:139]
	v_pk_mul_f32 v[64:65], v[64:65], v[132:133]
	v_pk_mul_f32 v[60:61], v[60:61], v[136:137]
	v_pk_mul_f32 v[56:57], v[56:57], v[140:141]
	v_pk_mul_f32 v[52:53], v[52:53], v[144:145]
	v_pk_mul_f32 v[50:51], v[50:51], v[142:143]
.LBB0_1422:
	v_cndmask_b32_e64 v130, v147, v184, s[40:41]
	v_mul_f32_e32 v148, 0xbe0293ee, v130
	v_fmamk_f32 v82, v82, 0x3e0293ee, v148
	v_fmamk_f32 v149, v66, 0x3e0293ee, v148
	v_fmamk_f32 v66, v83, 0x3e0293ee, v148
	v_fmamk_f32 v150, v67, 0x3e0293ee, v148
	v_fmamk_f32 v67, v84, 0x3e0293ee, v148
	v_fmamk_f32 v151, v68, 0x3e0293ee, v148
	v_fmamk_f32 v68, v85, 0x3e0293ee, v148
	v_fmamk_f32 v152, v69, 0x3e0293ee, v148
	v_fmamk_f32 v69, v86, 0x3e0293ee, v148
	v_fmamk_f32 v153, v70, 0x3e0293ee, v148
	v_fmamk_f32 v70, v87, 0x3e0293ee, v148
	v_fmamk_f32 v165, v71, 0x3e0293ee, v148
	v_fmamk_f32 v71, v88, 0x3e0293ee, v148
	v_fmamk_f32 v166, v72, 0x3e0293ee, v148
	v_fmamk_f32 v72, v89, 0x3e0293ee, v148
	v_fmamk_f32 v167, v73, 0x3e0293ee, v148
	v_fmamk_f32 v73, v90, 0x3e0293ee, v148
	v_fmamk_f32 v184, v74, 0x3e0293ee, v148
	v_fmamk_f32 v74, v91, 0x3e0293ee, v148
	v_fmamk_f32 v185, v75, 0x3e0293ee, v148
	v_fmamk_f32 v75, v92, 0x3e0293ee, v148
	v_fmamk_f32 v186, v76, 0x3e0293ee, v148
	v_fmamk_f32 v76, v93, 0x3e0293ee, v148
	v_fmamk_f32 v187, v77, 0x3e0293ee, v148
	v_fmamk_f32 v77, v94, 0x3e0293ee, v148
	v_fmamk_f32 v188, v78, 0x3e0293ee, v148
	v_fmamk_f32 v78, v95, 0x3e0293ee, v148
	v_fmamk_f32 v83, v96, 0x3e0293ee, v148
	v_fmamk_f32 v84, v97, 0x3e0293ee, v148
	v_exp_f32_e32 v144, v82
	v_exp_f32_e32 v147, v66
	v_exp_f32_e32 v142, v67
	v_exp_f32_e32 v145, v68
	v_exp_f32_e32 v140, v69
	v_exp_f32_e32 v143, v70
	v_exp_f32_e32 v139, v71
	v_exp_f32_e32 v141, v72
	v_exp_f32_e32 v136, v73
	v_exp_f32_e32 v138, v74
	v_exp_f32_e32 v134, v75
	v_exp_f32_e32 v137, v76
	v_exp_f32_e32 v132, v77
	v_exp_f32_e32 v135, v78
	v_exp_f32_e32 v131, v83
	v_exp_f32_e32 v133, v84
	v_fmamk_f32 v189, v79, 0x3e0293ee, v148
	v_fmamk_f32 v190, v80, 0x3e0293ee, v148
	v_fmac_f32_e32 v148, 0x3e0293ee, v81
	s_waitcnt lgkmcnt(0)
	s_barrier
	ds_read_b128 v[228:231], v168 offset:49152
	ds_read_b128 v[232:235], v168 offset:57344
	ds_read_b128 v[236:239], v164 offset:49152
	ds_read_b128 v[248:251], v164 offset:57344
	ds_read_b128 v[252:255], v161 offset:49152
	s_waitcnt lgkmcnt(4)
	v_mfma_f32_32x32x16_bf16 v[82:97], v[228:231], v[126:129], 0
	ds_read_b128 v[228:231], v161 offset:57344
	s_waitcnt lgkmcnt(4)
	v_mfma_f32_32x32x16_bf16 v[66:81], v[232:235], v[126:129], 0
	ds_read_b128 v[232:235], v160 offset:49152
	s_waitcnt lgkmcnt(4)
	v_mfma_f32_32x32x16_bf16 v[82:97], v[236:239], v[122:125], v[82:97]
	ds_read_b128 v[236:239], v160 offset:57344
	s_waitcnt lgkmcnt(4)
	v_mfma_f32_32x32x16_bf16 v[66:81], v[248:251], v[122:125], v[66:81]
	ds_read_b128 v[248:251], v168 offset:49280
	s_waitcnt lgkmcnt(4)
	v_mfma_f32_32x32x16_bf16 v[82:97], v[252:255], v[118:121], v[82:97]
	ds_read_b128 v[252:255], v168 offset:57472
	s_waitcnt lgkmcnt(4)
	v_mfma_f32_32x32x16_bf16 v[66:81], v[228:231], v[118:121], v[66:81]
	ds_read_b128 v[228:231], v164 offset:49280
	s_waitcnt lgkmcnt(4)
	v_mfma_f32_32x32x16_bf16 v[82:97], v[232:235], v[114:117], v[82:97]
	ds_read_b128 v[232:235], v164 offset:57472
	s_waitcnt lgkmcnt(4)
	v_mfma_f32_32x32x16_bf16 v[66:81], v[236:239], v[114:117], v[66:81]
	ds_read_b128 v[236:239], v161 offset:49280
	s_waitcnt lgkmcnt(4)
	v_mfma_f32_32x32x16_bf16 v[82:97], v[248:251], v[110:113], v[82:97]
	ds_read_b128 v[248:251], v161 offset:57472
	s_waitcnt lgkmcnt(4)
	v_mfma_f32_32x32x16_bf16 v[66:81], v[252:255], v[110:113], v[66:81]
	ds_read_b128 v[252:255], v160 offset:49280
	s_waitcnt lgkmcnt(4)
	v_mfma_f32_32x32x16_bf16 v[82:97], v[228:231], v[106:109], v[82:97]
	ds_read_b128 v[228:231], v160 offset:57472
	s_waitcnt lgkmcnt(4)
	v_mfma_f32_32x32x16_bf16 v[66:81], v[232:235], v[106:109], v[66:81]
	s_waitcnt lgkmcnt(3)
	v_mfma_f32_32x32x16_bf16 v[82:97], v[236:239], v[102:105], v[82:97]
	s_waitcnt lgkmcnt(2)
	v_mfma_f32_32x32x16_bf16 v[66:81], v[248:251], v[102:105], v[66:81]
	s_waitcnt lgkmcnt(1)
	v_mfma_f32_32x32x16_bf16 v[82:97], v[252:255], v[98:101], v[82:97]
	s_waitcnt lgkmcnt(0)
	v_mfma_f32_32x32x16_bf16 v[66:81], v[228:231], v[98:101], v[66:81]
	v_add_f32_e32 v98, 0, v144
	v_add_f32_e32 v98, v147, v98
	v_add_f32_e32 v98, v142, v98
	v_add_f32_e32 v98, v145, v98
	v_add_f32_e32 v98, v140, v98
	v_add_f32_e32 v98, v143, v98
	v_add_f32_e32 v98, v139, v98
	v_add_f32_e32 v98, v141, v98
	v_add_f32_e32 v98, v136, v98
	v_add_f32_e32 v98, v138, v98
	v_add_f32_e32 v98, v134, v98
	v_add_f32_e32 v98, v137, v98
	v_exp_f32_e32 v108, v149
	v_add_f32_e32 v98, v132, v98
	v_exp_f32_e32 v109, v150
	v_add_f32_e32 v98, v135, v98
	v_exp_f32_e32 v110, v151
	v_add_f32_e32 v98, v131, v98
	v_exp_f32_e32 v111, v152
	v_add_f32_e32 v98, v133, v98
	v_exp_f32_e32 v112, v153
	v_add_f32_e32 v98, v108, v98
	v_exp_f32_e32 v113, v165
	v_add_f32_e32 v98, v109, v98
	v_exp_f32_e32 v114, v166
	v_add_f32_e32 v98, v110, v98
	v_exp_f32_e32 v115, v167
	v_add_f32_e32 v98, v111, v98
	v_exp_f32_e32 v116, v184
	v_add_f32_e32 v98, v112, v98
	v_exp_f32_e32 v117, v185
	v_add_f32_e32 v98, v113, v98
	v_exp_f32_e32 v118, v186
	v_add_f32_e32 v98, v114, v98
	v_exp_f32_e32 v119, v187
	v_add_f32_e32 v98, v115, v98
	v_exp_f32_e32 v120, v188
	v_add_f32_e32 v98, v116, v98
	v_exp_f32_e32 v121, v189
	v_add_f32_e32 v98, v117, v98
	v_exp_f32_e32 v122, v190
	v_add_f32_e32 v98, v118, v98
	v_exp_f32_e32 v123, v148
	v_add_f32_e32 v98, v119, v98
	v_add_f32_e32 v98, v120, v98
	v_add_f32_e32 v98, v121, v98
	v_add_f32_e32 v98, v122, v98
	v_add_f32_e32 v102, v123, v98
	v_mov_b32_e32 v103, v102
	v_cvt_pk_bf16_f32 v98, v144, v147
	v_cvt_pk_bf16_f32 v99, v142, v145
	v_cvt_pk_bf16_f32 v100, v140, v143
	v_cvt_pk_bf16_f32 v101, v139, v141
	s_nop 1
	v_permlane32_swap_b32_e32 v102, v103
	v_permlane32_swap_b32_e32 v98, v100
	v_permlane32_swap_b32_e32 v99, v101
	v_cvt_pk_bf16_f32 v104, v136, v138
	v_cvt_pk_bf16_f32 v105, v134, v137
	v_cvt_pk_bf16_f32 v106, v132, v135
	v_cvt_pk_bf16_f32 v107, v131, v133
	v_cvt_pk_bf16_f32 v108, v108, v109
	v_cvt_pk_bf16_f32 v109, v110, v111
	v_cvt_pk_bf16_f32 v110, v112, v113
	v_cvt_pk_bf16_f32 v111, v114, v115
	v_cvt_pk_bf16_f32 v112, v116, v117
	v_cvt_pk_bf16_f32 v113, v118, v119
	v_cvt_pk_bf16_f32 v114, v120, v121
	v_cvt_pk_bf16_f32 v115, v122, v123
	s_nop 0
	v_permlane32_swap_b32_e32 v104, v106
	v_permlane32_swap_b32_e32 v105, v107
	v_permlane32_swap_b32_e32 v108, v110
	v_permlane32_swap_b32_e32 v109, v111
	v_permlane32_swap_b32_e32 v112, v114
	v_permlane32_swap_b32_e32 v113, v115
	ds_read_b64_tr_b16 v[116:117], v158 offset:0
	ds_read_b64_tr_b16 v[118:119], v158 offset:0x800
	ds_read_b64_tr_b16 v[120:121], v158 offset:0x1000
	ds_read_b64_tr_b16 v[122:123], v158 offset:0x1800
	ds_read_b64_tr_b16 v[124:125], v158 offset:0x2000
	ds_read_b64_tr_b16 v[126:127], v158 offset:0x2800
	ds_read_b64_tr_b16 v[132:133], v158 offset:0x3000
	ds_read_b64_tr_b16 v[134:135], v158 offset:0x3800
	s_waitcnt lgkmcnt(0)
	s_nop 0
	v_mfma_f32_32x32x16_bf16 v[2:17], v[98:101], v[116:119], v[2:17]
	ds_read_b64_tr_b16 v[116:117], v158 offset:0x200
	ds_read_b64_tr_b16 v[118:119], v158 offset:0xa00
	v_mfma_f32_32x32x16_bf16 v[2:17], v[104:107], v[120:123], v[2:17]
	ds_read_b64_tr_b16 v[120:121], v158 offset:0x1200
	ds_read_b64_tr_b16 v[122:123], v158 offset:0x1a00
	v_mfma_f32_32x32x16_bf16 v[2:17], v[108:111], v[124:127], v[2:17]
	ds_read_b64_tr_b16 v[124:125], v158 offset:0x2200
	ds_read_b64_tr_b16 v[126:127], v158 offset:0x2a00
	v_mfma_f32_32x32x16_bf16 v[2:17], v[112:115], v[132:135], v[2:17]
	ds_read_b64_tr_b16 v[132:133], v158 offset:0x3200
	ds_read_b64_tr_b16 v[134:135], v158 offset:0x3a00
	s_waitcnt lgkmcnt(0)
	v_mfma_f32_32x32x16_bf16 v[18:33], v[98:101], v[116:119], v[18:33]
	ds_read_b64_tr_b16 v[116:117], v158 offset:0x400
	ds_read_b64_tr_b16 v[118:119], v158 offset:0xc00
	v_mfma_f32_32x32x16_bf16 v[18:33], v[104:107], v[120:123], v[18:33]
	ds_read_b64_tr_b16 v[120:121], v158 offset:0x1400
	ds_read_b64_tr_b16 v[122:123], v158 offset:0x1c00
	v_mfma_f32_32x32x16_bf16 v[18:33], v[108:111], v[124:127], v[18:33]
	ds_read_b64_tr_b16 v[124:125], v158 offset:0x2400
	ds_read_b64_tr_b16 v[126:127], v158 offset:0x2c00
	v_mfma_f32_32x32x16_bf16 v[18:33], v[112:115], v[132:135], v[18:33]
	ds_read_b64_tr_b16 v[132:133], v158 offset:0x3400
	ds_read_b64_tr_b16 v[134:135], v158 offset:0x3c00
	s_waitcnt lgkmcnt(0)
	v_mfma_f32_32x32x16_bf16 v[34:49], v[98:101], v[116:119], v[34:49]
	ds_read_b64_tr_b16 v[116:117], v158 offset:0x600
	ds_read_b64_tr_b16 v[118:119], v158 offset:0xe00
	v_mfma_f32_32x32x16_bf16 v[34:49], v[104:107], v[120:123], v[34:49]
	ds_read_b64_tr_b16 v[120:121], v158 offset:0x1600
	ds_read_b64_tr_b16 v[122:123], v158 offset:0x1e00
	v_mfma_f32_32x32x16_bf16 v[34:49], v[108:111], v[124:127], v[34:49]
	ds_read_b64_tr_b16 v[124:125], v158 offset:0x2600
	ds_read_b64_tr_b16 v[126:127], v158 offset:0x2e00
	v_mfma_f32_32x32x16_bf16 v[34:49], v[112:115], v[132:135], v[34:49]
	ds_read_b64_tr_b16 v[132:133], v158 offset:0x3600
	ds_read_b64_tr_b16 v[134:135], v158 offset:0x3e00
	s_waitcnt lgkmcnt(0)
	v_mfma_f32_32x32x16_bf16 v[50:65], v[98:101], v[116:119], v[50:65]
	v_max_f32_e32 v98, v83, v83
	v_max_f32_e32 v99, v82, v82
	v_max_f32_e32 v98, v99, v98
	v_max3_f32 v98, v98, v84, v85
	v_max3_f32 v98, v98, v86, v87
	v_max3_f32 v98, v98, v88, v89
	v_max3_f32 v98, v98, v90, v91
	v_max3_f32 v98, v98, v92, v93
	v_max3_f32 v98, v98, v94, v95
	v_max3_f32 v98, v98, v96, v97
	v_mfma_f32_32x32x16_bf16 v[50:65], v[104:107], v[120:123], v[50:65]
	v_max3_f32 v98, v98, v66, v67
	v_max3_f32 v98, v98, v68, v69
	v_max3_f32 v98, v98, v70, v71
	v_max3_f32 v98, v98, v72, v73
	v_max3_f32 v98, v98, v74, v75
	v_max3_f32 v98, v98, v76, v77
	v_max3_f32 v98, v98, v78, v79
	v_max3_f32 v98, v98, v80, v81
	v_mfma_f32_32x32x16_bf16 v[50:65], v[108:111], v[124:127], v[50:65]
	v_mov_b32_e32 v99, v98
	s_nop 1
	v_permlane32_swap_b32_e32 v98, v99
	v_max_f32_e32 v99, v99, v99
	v_max_f32_e32 v98, v98, v98
	v_max_f32_e32 v98, v98, v99
	v_sub_f32_e32 v99, v98, v130
	v_mul_f32_e32 v99, 0x3e0293ee, v99
	v_cmp_ge_f32_e32 vcc, s24, v99
	v_max_f32_e32 v99, v130, v130
	v_max_f32_e32 v99, v99, v98
	v_mfma_f32_32x32x16_bf16 v[50:65], v[112:115], v[132:135], v[50:65]
	v_sub_f32_e32 v98, v130, v99
	v_mul_f32_e32 v98, 0x3e0293ee, v98
	v_exp_f32_e32 v98, v98
	s_cmp_eq_u64 vcc, exec
	s_cselect_b64 s[40:41], -1, 0
	v_cndmask_b32_e64 v98, v98, 1.0, s[40:41]
	v_cmp_gt_f32_e32 vcc, 1.0, v98
	s_cbranch_vccz .LBB0_1426
	s_and_saveexec_b64 s[4:5], s[38:39]
	ds_write_b32 v159, v98 offset:128
	s_or_b64 exec, exec, s[4:5]
	s_waitcnt lgkmcnt(0)
	v_add_u32_e32 v100, s42, v162
	ds_read_b128 v[104:107], v100 offset:224
	ds_read_b128 v[108:111], v100 offset:192
	ds_read_b128 v[112:115], v100 offset:160
	ds_read_b128 v[116:119], v100 offset:128
	s_waitcnt lgkmcnt(3)
	v_pk_mul_f32 v[14:15], v[14:15], v[104:105]
	s_waitcnt lgkmcnt(2)
	v_pk_mul_f32 v[10:11], v[10:11], v[108:109]
	s_waitcnt lgkmcnt(1)
	v_pk_mul_f32 v[6:7], v[6:7], v[112:113]
	v_pk_mul_f32 v[16:17], v[16:17], v[106:107]
	v_pk_mul_f32 v[12:13], v[12:13], v[110:111]
	v_pk_mul_f32 v[8:9], v[8:9], v[114:115]
	s_waitcnt lgkmcnt(0)
	v_pk_mul_f32 v[4:5], v[4:5], v[118:119]
	v_pk_mul_f32 v[2:3], v[2:3], v[116:117]
	v_pk_mul_f32 v[30:31], v[30:31], v[104:105]
	v_pk_mul_f32 v[26:27], v[26:27], v[108:109]
	v_pk_mul_f32 v[22:23], v[22:23], v[112:113]
	v_pk_mul_f32 v[32:33], v[32:33], v[106:107]
	v_pk_mul_f32 v[28:29], v[28:29], v[110:111]
	v_pk_mul_f32 v[24:25], v[24:25], v[114:115]
	v_pk_mul_f32 v[20:21], v[20:21], v[118:119]
	v_pk_mul_f32 v[18:19], v[18:19], v[116:117]
	v_pk_mul_f32 v[46:47], v[46:47], v[104:105]
	v_pk_mul_f32 v[42:43], v[42:43], v[108:109]
	v_pk_mul_f32 v[38:39], v[38:39], v[112:113]
	v_pk_mul_f32 v[48:49], v[48:49], v[106:107]
	v_pk_mul_f32 v[44:45], v[44:45], v[110:111]
	v_pk_mul_f32 v[40:41], v[40:41], v[114:115]
	v_pk_mul_f32 v[36:37], v[36:37], v[118:119]
	v_pk_mul_f32 v[34:35], v[34:35], v[116:117]
	v_pk_mul_f32 v[62:63], v[62:63], v[104:105]
	v_pk_mul_f32 v[58:59], v[58:59], v[108:109]
	v_pk_mul_f32 v[54:55], v[54:55], v[112:113]
	v_pk_mul_f32 v[64:65], v[64:65], v[106:107]
	v_pk_mul_f32 v[60:61], v[60:61], v[110:111]
	v_pk_mul_f32 v[56:57], v[56:57], v[114:115]
	v_pk_mul_f32 v[52:53], v[52:53], v[118:119]
	v_pk_mul_f32 v[50:51], v[50:51], v[116:117]

.LBB0_1620:
	s_ashr_i32 s19, s18, 31
	s_lshl_b64 s[28:29], s[18:19], 18
	v_readlane_b32 s5, v245, 24
	s_add_u32 s28, s5, s28
	v_readlane_b32 s5, v245, 26
	s_addc_u32 s29, s5, s29
	s_and_b64 s[34:35], s[22:23], exec
	s_cselect_b32 s8, s29, s43
	s_cselect_b32 s19, s28, s42
	s_ashr_i32 s5, s4, 31
	s_lshl_b64 s[34:35], s[4:5], 18
	s_add_u32 s34, s11, s34
	s_addc_u32 s35, s13, s35
	s_and_b64 s[46:47], s[22:23], exec
	s_cselect_b32 s5, s35, s45
	s_cselect_b32 s21, s34, s44
	s_add_u32 s42, s42, 0x20080
	s_addc_u32 s43, s43, 0
	s_add_u32 s39, s44, 0x100
	v_mov_b32_e32 v2, 0
	s_addc_u32 s50, s45, 0
	s_mov_b32 s51, -2
	v_mov_b32_e32 v3, v2
	v_mov_b32_e32 v4, v2
	v_mov_b32_e32 v5, v2
	v_mov_b32_e32 v6, v2
	v_mov_b32_e32 v7, v2
	v_mov_b32_e32 v8, v2
	v_mov_b32_e32 v9, v2
	s_waitcnt vmcnt(0) lgkmcnt(0)
	v_mov_b32_e32 v18, v2
	v_mov_b32_e32 v19, v2
	v_mov_b32_e32 v20, v2
	v_mov_b32_e32 v21, v2
	v_mov_b32_e32 v22, v2
	v_mov_b32_e32 v23, v2
	v_mov_b32_e32 v24, v2
	v_mov_b32_e32 v25, v2
	v_mov_b32_e32 v34, v2
	v_mov_b32_e32 v35, v2
	v_mov_b32_e32 v36, v2
	v_mov_b32_e32 v37, v2
	v_mov_b32_e32 v38, v2
	v_mov_b32_e32 v39, v2
	v_mov_b32_e32 v40, v2
	v_mov_b32_e32 v41, v2
	v_mov_b32_e32 v50, v2
	v_mov_b32_e32 v51, v2
	v_mov_b32_e32 v52, v2
	v_mov_b32_e32 v53, v2
	v_mov_b32_e32 v54, v2
	v_mov_b32_e32 v55, v2
	v_mov_b32_e32 v56, v2
	v_mov_b32_e32 v57, v2
	v_mov_b32_e32 v10, v2
	v_mov_b32_e32 v11, v2
	v_mov_b32_e32 v12, v2
	v_mov_b32_e32 v13, v2
	v_mov_b32_e32 v14, v2
	v_mov_b32_e32 v15, v2
	v_mov_b32_e32 v16, v2
	v_mov_b32_e32 v17, v2
	v_mov_b32_e32 v26, v2
	v_mov_b32_e32 v27, v2
	v_mov_b32_e32 v28, v2
	v_mov_b32_e32 v29, v2
	v_mov_b32_e32 v30, v2
	v_mov_b32_e32 v31, v2
	v_mov_b32_e32 v32, v2
	v_mov_b32_e32 v33, v2
	v_mov_b32_e32 v42, v2
	v_mov_b32_e32 v43, v2
	v_mov_b32_e32 v44, v2
	v_mov_b32_e32 v45, v2
	v_mov_b32_e32 v46, v2
	v_mov_b32_e32 v47, v2
	v_mov_b32_e32 v48, v2
	v_mov_b32_e32 v49, v2
	v_mov_b32_e32 v58, v2
	v_mov_b32_e32 v59, v2
	v_mov_b32_e32 v60, v2
	v_mov_b32_e32 v61, v2
	v_mov_b32_e32 v62, v2
	v_mov_b32_e32 v63, v2
	v_mov_b32_e32 v64, v2
	v_mov_b32_e32 v65, v2
	v_mov_b32_e32 v66, v2
	v_mov_b32_e32 v67, v2
	v_mov_b32_e32 v68, v2
	v_mov_b32_e32 v69, v2
	v_mov_b32_e32 v70, v2
	v_mov_b32_e32 v71, v2
	v_mov_b32_e32 v72, v2
	v_mov_b32_e32 v73, v2
	v_mov_b32_e32 v82, v2
	v_mov_b32_e32 v83, v2
	v_mov_b32_e32 v84, v2
	v_mov_b32_e32 v85, v2
	v_mov_b32_e32 v86, v2
	v_mov_b32_e32 v87, v2
	v_mov_b32_e32 v88, v2
	v_mov_b32_e32 v89, v2
	v_mov_b32_e32 v98, v2
	v_mov_b32_e32 v99, v2
	v_mov_b32_e32 v100, v2
	v_mov_b32_e32 v101, v2
	v_mov_b32_e32 v102, v2
	v_mov_b32_e32 v103, v2
	v_mov_b32_e32 v104, v2
	v_mov_b32_e32 v105, v2
	v_mov_b32_e32 v114, v2
	v_mov_b32_e32 v115, v2
	v_mov_b32_e32 v116, v2
	v_mov_b32_e32 v117, v2
	v_mov_b32_e32 v118, v2
	v_mov_b32_e32 v119, v2
	v_mov_b32_e32 v120, v2
	v_mov_b32_e32 v121, v2
	v_mov_b32_e32 v74, v2
	v_mov_b32_e32 v75, v2
	v_mov_b32_e32 v76, v2
	v_mov_b32_e32 v77, v2
	v_mov_b32_e32 v78, v2
	v_mov_b32_e32 v79, v2
	v_mov_b32_e32 v80, v2
	v_mov_b32_e32 v81, v2
	v_mov_b32_e32 v90, v2
	v_mov_b32_e32 v91, v2
	v_mov_b32_e32 v92, v2
	v_mov_b32_e32 v93, v2
	v_mov_b32_e32 v94, v2
	v_mov_b32_e32 v95, v2
	v_mov_b32_e32 v96, v2
	v_mov_b32_e32 v97, v2
	v_mov_b32_e32 v106, v2
	v_mov_b32_e32 v107, v2
	v_mov_b32_e32 v108, v2
	v_mov_b32_e32 v109, v2
	v_mov_b32_e32 v110, v2
	v_mov_b32_e32 v111, v2
	v_mov_b32_e32 v112, v2
	v_mov_b32_e32 v113, v2
	v_mov_b32_e32 v122, v2
	v_mov_b32_e32 v123, v2
	v_mov_b32_e32 v124, v2
	v_mov_b32_e32 v125, v2
	v_mov_b32_e32 v126, v2
	v_mov_b32_e32 v127, v2
	v_mov_b32_e32 v128, v2
	v_mov_b32_e32 v129, v2

.LBB0_1797:
	s_ashr_i32 s19, s18, 31
	s_lshl_b64 s[20:21], s[18:19], 20
	v_readlane_b32 s5, v243, 17
	s_add_u32 s28, s5, s20
	v_readlane_b32 s5, v243, 18
	s_addc_u32 s29, s5, s21
	s_and_b64 s[20:21], s[34:35], exec
	s_cselect_b32 s11, s29, s23
	s_cselect_b32 s13, s28, s22
	s_ashr_i32 s5, s4, 31
	s_lshl_b64 s[20:21], s[4:5], 20
	s_add_u32 s38, s25, s20
	s_addc_u32 s39, s27, s21
	s_and_b64 s[20:21], s[34:35], exec
	s_cselect_b32 s5, s39, s41
	s_cselect_b32 s19, s38, s40
	s_add_u32 s22, s22, 0x80080
	s_addc_u32 s23, s23, 0
	s_add_u32 s20, s40, 0x100
	v_mov_b32_e32 v2, 0
	s_addc_u32 s21, s41, 0
	s_mov_b32 s26, -2
	v_mov_b32_e32 v3, v2
	v_mov_b32_e32 v4, v2
	v_mov_b32_e32 v5, v2
	v_mov_b32_e32 v6, v2
	v_mov_b32_e32 v7, v2
	v_mov_b32_e32 v8, v2
	v_mov_b32_e32 v9, v2
	v_mov_b32_e32 v18, v2
	v_mov_b32_e32 v19, v2
	v_mov_b32_e32 v20, v2
	v_mov_b32_e32 v21, v2
	v_mov_b32_e32 v22, v2
	v_mov_b32_e32 v23, v2
	v_mov_b32_e32 v24, v2
	v_mov_b32_e32 v25, v2
	v_mov_b32_e32 v34, v2
	v_mov_b32_e32 v35, v2
	v_mov_b32_e32 v36, v2
	v_mov_b32_e32 v37, v2
	v_mov_b32_e32 v38, v2
	v_mov_b32_e32 v39, v2
	v_mov_b32_e32 v40, v2
	v_mov_b32_e32 v41, v2
	v_mov_b32_e32 v50, v2
	v_mov_b32_e32 v51, v2
	v_mov_b32_e32 v52, v2
	v_mov_b32_e32 v53, v2
	v_mov_b32_e32 v54, v2
	v_mov_b32_e32 v55, v2
	v_mov_b32_e32 v56, v2
	v_mov_b32_e32 v57, v2
	v_mov_b32_e32 v10, v2
	v_mov_b32_e32 v11, v2
	v_mov_b32_e32 v12, v2
	v_mov_b32_e32 v13, v2
	v_mov_b32_e32 v14, v2
	v_mov_b32_e32 v15, v2
	v_mov_b32_e32 v16, v2
	v_mov_b32_e32 v17, v2
	v_mov_b32_e32 v26, v2
	v_mov_b32_e32 v27, v2
	v_mov_b32_e32 v28, v2
	v_mov_b32_e32 v29, v2
	v_mov_b32_e32 v30, v2
	v_mov_b32_e32 v31, v2
	v_mov_b32_e32 v32, v2
	v_mov_b32_e32 v33, v2
	v_mov_b32_e32 v42, v2
	v_mov_b32_e32 v43, v2
	v_mov_b32_e32 v44, v2
	v_mov_b32_e32 v45, v2
	v_mov_b32_e32 v46, v2
	v_mov_b32_e32 v47, v2
	v_mov_b32_e32 v48, v2
	v_mov_b32_e32 v49, v2
	v_mov_b32_e32 v58, v2
	v_mov_b32_e32 v59, v2
	v_mov_b32_e32 v60, v2
	v_mov_b32_e32 v61, v2
	v_mov_b32_e32 v62, v2
	v_mov_b32_e32 v63, v2
	v_mov_b32_e32 v64, v2
	v_mov_b32_e32 v65, v2
	v_mov_b32_e32 v66, v2
	v_mov_b32_e32 v67, v2
	v_mov_b32_e32 v68, v2
	v_mov_b32_e32 v69, v2
	v_mov_b32_e32 v70, v2
	v_mov_b32_e32 v71, v2
	v_mov_b32_e32 v72, v2
	v_mov_b32_e32 v73, v2
	v_mov_b32_e32 v82, v2
	v_mov_b32_e32 v83, v2
	v_mov_b32_e32 v84, v2
	v_mov_b32_e32 v85, v2
	v_mov_b32_e32 v86, v2
	v_mov_b32_e32 v87, v2
	v_mov_b32_e32 v88, v2
	v_mov_b32_e32 v89, v2
	v_mov_b32_e32 v98, v2
	v_mov_b32_e32 v99, v2
	v_mov_b32_e32 v100, v2
	v_mov_b32_e32 v101, v2
	v_mov_b32_e32 v102, v2
	v_mov_b32_e32 v103, v2
	v_mov_b32_e32 v104, v2
	v_mov_b32_e32 v105, v2
	v_mov_b32_e32 v114, v2
	v_mov_b32_e32 v115, v2
	v_mov_b32_e32 v116, v2
	v_mov_b32_e32 v117, v2
	v_mov_b32_e32 v118, v2
	v_mov_b32_e32 v119, v2
	v_mov_b32_e32 v120, v2
	v_mov_b32_e32 v121, v2
	v_mov_b32_e32 v74, v2
	v_mov_b32_e32 v75, v2
	v_mov_b32_e32 v76, v2
	v_mov_b32_e32 v77, v2
	v_mov_b32_e32 v78, v2
	v_mov_b32_e32 v79, v2
	v_mov_b32_e32 v80, v2
	v_mov_b32_e32 v81, v2
	v_mov_b32_e32 v90, v2
	v_mov_b32_e32 v91, v2
	v_mov_b32_e32 v92, v2
	v_mov_b32_e32 v93, v2
	v_mov_b32_e32 v94, v2
	v_mov_b32_e32 v95, v2
	v_mov_b32_e32 v96, v2
	v_mov_b32_e32 v97, v2
	v_mov_b32_e32 v106, v2
	v_mov_b32_e32 v107, v2
	v_mov_b32_e32 v108, v2
	v_mov_b32_e32 v109, v2
	v_mov_b32_e32 v110, v2
	v_mov_b32_e32 v111, v2
	v_mov_b32_e32 v112, v2
	v_mov_b32_e32 v113, v2
	v_mov_b32_e32 v122, v2
	v_mov_b32_e32 v123, v2
	v_mov_b32_e32 v124, v2
	v_mov_b32_e32 v125, v2
	v_mov_b32_e32 v126, v2
	v_mov_b32_e32 v127, v2
	v_mov_b32_e32 v128, v2
	v_mov_b32_e32 v129, v2

.LBB0_1873:
	s_add_u32 s45, s28, 0x100
	v_mov_b32_e32 v2, 0
	s_addc_u32 s46, s29, 0
	s_mov_b32 s47, -2
	v_mov_b32_e32 v3, v2
	v_mov_b32_e32 v4, v2
	v_mov_b32_e32 v5, v2
	v_mov_b32_e32 v6, v2
	v_mov_b32_e32 v7, v2
	v_mov_b32_e32 v8, v2
	v_mov_b32_e32 v9, v2
	s_waitcnt vmcnt(0) lgkmcnt(0)
	v_mov_b32_e32 v18, v2
	v_mov_b32_e32 v19, v2
	v_mov_b32_e32 v20, v2
	v_mov_b32_e32 v21, v2
	v_mov_b32_e32 v22, v2
	v_mov_b32_e32 v23, v2
	v_mov_b32_e32 v24, v2
	v_mov_b32_e32 v25, v2
	v_mov_b32_e32 v34, v2
	v_mov_b32_e32 v35, v2
	v_mov_b32_e32 v36, v2
	v_mov_b32_e32 v37, v2
	v_mov_b32_e32 v38, v2
	v_mov_b32_e32 v39, v2
	v_mov_b32_e32 v40, v2
	v_mov_b32_e32 v41, v2
	v_mov_b32_e32 v50, v2
	v_mov_b32_e32 v51, v2
	v_mov_b32_e32 v52, v2
	v_mov_b32_e32 v53, v2
	v_mov_b32_e32 v54, v2
	v_mov_b32_e32 v55, v2
	v_mov_b32_e32 v56, v2
	v_mov_b32_e32 v57, v2
	v_mov_b32_e32 v10, v2
	v_mov_b32_e32 v11, v2
	v_mov_b32_e32 v12, v2
	v_mov_b32_e32 v13, v2
	v_mov_b32_e32 v14, v2
	v_mov_b32_e32 v15, v2
	v_mov_b32_e32 v16, v2
	v_mov_b32_e32 v17, v2
	v_mov_b32_e32 v26, v2
	v_mov_b32_e32 v27, v2
	v_mov_b32_e32 v28, v2
	v_mov_b32_e32 v29, v2
	v_mov_b32_e32 v30, v2
	v_mov_b32_e32 v31, v2
	v_mov_b32_e32 v32, v2
	v_mov_b32_e32 v33, v2
	v_mov_b32_e32 v42, v2
	v_mov_b32_e32 v43, v2
	v_mov_b32_e32 v44, v2
	v_mov_b32_e32 v45, v2
	v_mov_b32_e32 v46, v2
	v_mov_b32_e32 v47, v2
	v_mov_b32_e32 v48, v2
	v_mov_b32_e32 v49, v2
	v_mov_b32_e32 v58, v2
	v_mov_b32_e32 v59, v2
	v_mov_b32_e32 v60, v2
	v_mov_b32_e32 v61, v2
	v_mov_b32_e32 v62, v2
	v_mov_b32_e32 v63, v2
	v_mov_b32_e32 v64, v2
	v_mov_b32_e32 v65, v2
	v_mov_b32_e32 v66, v2
	v_mov_b32_e32 v67, v2
	v_mov_b32_e32 v68, v2
	v_mov_b32_e32 v69, v2
	v_mov_b32_e32 v70, v2
	v_mov_b32_e32 v71, v2
	v_mov_b32_e32 v72, v2
	v_mov_b32_e32 v73, v2
	v_mov_b32_e32 v82, v2
	v_mov_b32_e32 v83, v2
	v_mov_b32_e32 v84, v2
	v_mov_b32_e32 v85, v2
	v_mov_b32_e32 v86, v2
	v_mov_b32_e32 v87, v2
	v_mov_b32_e32 v88, v2
	v_mov_b32_e32 v89, v2
	v_mov_b32_e32 v98, v2
	v_mov_b32_e32 v99, v2
	v_mov_b32_e32 v100, v2
	v_mov_b32_e32 v101, v2
	v_mov_b32_e32 v102, v2
	v_mov_b32_e32 v103, v2
	v_mov_b32_e32 v104, v2
	v_mov_b32_e32 v105, v2
	v_mov_b32_e32 v114, v2
	v_mov_b32_e32 v115, v2
	v_mov_b32_e32 v116, v2
	v_mov_b32_e32 v117, v2
	v_mov_b32_e32 v118, v2
	v_mov_b32_e32 v119, v2
	v_mov_b32_e32 v120, v2
	v_mov_b32_e32 v121, v2
	v_mov_b32_e32 v74, v2
	v_mov_b32_e32 v75, v2
	v_mov_b32_e32 v76, v2
	v_mov_b32_e32 v77, v2
	v_mov_b32_e32 v78, v2
	v_mov_b32_e32 v79, v2
	v_mov_b32_e32 v80, v2
	v_mov_b32_e32 v81, v2
	v_mov_b32_e32 v90, v2
	v_mov_b32_e32 v91, v2
	v_mov_b32_e32 v92, v2
	v_mov_b32_e32 v93, v2
	v_mov_b32_e32 v94, v2
	v_mov_b32_e32 v95, v2
	v_mov_b32_e32 v96, v2
	v_mov_b32_e32 v97, v2
	v_mov_b32_e32 v106, v2
	v_mov_b32_e32 v107, v2
	v_mov_b32_e32 v108, v2
	v_mov_b32_e32 v109, v2
	v_mov_b32_e32 v110, v2
	v_mov_b32_e32 v111, v2
	v_mov_b32_e32 v112, v2
	v_mov_b32_e32 v113, v2
	v_mov_b32_e32 v122, v2
	v_mov_b32_e32 v123, v2
	v_mov_b32_e32 v124, v2
	v_mov_b32_e32 v125, v2
	v_mov_b32_e32 v126, v2
	v_mov_b32_e32 v127, v2
	v_mov_b32_e32 v128, v2
	v_mov_b32_e32 v129, v2

	.amdhsa_kernel _Z9trunk_fwd4Args
		.amdhsa_group_segment_fixed_size 0
		.amdhsa_private_segment_fixed_size 0
		.amdhsa_kernarg_size 496
		.amdhsa_user_sgpr_count 2
		.amdhsa_user_sgpr_dispatch_ptr 0
		.amdhsa_user_sgpr_queue_ptr 0
		.amdhsa_user_sgpr_kernarg_segment_ptr 1
		.amdhsa_user_sgpr_dispatch_id 0
		.amdhsa_user_sgpr_kernarg_preload_length 0
		.amdhsa_user_sgpr_kernarg_preload_offset 0
		.amdhsa_user_sgpr_private_segment_size 0
		.amdhsa_uses_dynamic_stack 0
		.amdhsa_enable_private_segment 0
		.amdhsa_system_sgpr_workgroup_id_x 1
		.amdhsa_system_sgpr_workgroup_id_y 0
		.amdhsa_system_sgpr_workgroup_id_z 0
		.amdhsa_system_sgpr_workgroup_info 0
		.amdhsa_system_vgpr_workitem_id 0
		.amdhsa_next_free_vgpr 256
		.amdhsa_next_free_sgpr 100
		.amdhsa_accum_offset 256
		.amdhsa_reserve_vcc 1
		.amdhsa_float_round_mode_32 0
		.amdhsa_float_round_mode_16_64 0
		.amdhsa_float_denorm_mode_32 3
		.amdhsa_float_denorm_mode_16_64 3
		.amdhsa_dx10_clamp 1
		.amdhsa_ieee_mode 1
		.amdhsa_fp16_overflow 0
		.amdhsa_tg_split 0
		.amdhsa_exception_fp_ieee_invalid_op 0
		.amdhsa_exception_fp_denorm_src 0
		.amdhsa_exception_fp_ieee_div_zero 0
		.amdhsa_exception_fp_ieee_overflow 0
		.amdhsa_exception_fp_ieee_underflow 0
		.amdhsa_exception_fp_ieee_inexact 0
		.amdhsa_exception_int_div_zero 0
	.end_amdhsa_kernel

amdhsa.kernels:
  - .agpr_count:     0
    .args:
      - .offset:         0
        .size:           240
        .value_kind:     by_value
      - .offset:         240
        .size:           4
        .value_kind:     hidden_block_count_x
      - .offset:         244
        .size:           4
        .value_kind:     hidden_block_count_y
      - .offset:         248
        .size:           4
        .value_kind:     hidden_block_count_z
      - .offset:         252
        .size:           2
        .value_kind:     hidden_group_size_x
      - .offset:         254
        .size:           2
        .value_kind:     hidden_group_size_y
      - .offset:         256
        .size:           2
        .value_kind:     hidden_group_size_z
      - .offset:         258
        .size:           2
        .value_kind:     hidden_remainder_x
      - .offset:         260
        .size:           2
        .value_kind:     hidden_remainder_y
      - .offset:         262
        .size:           2
        .value_kind:     hidden_remainder_z
      - .offset:         280
        .size:           8
        .value_kind:     hidden_global_offset_x
      - .offset:         288
        .size:           8
        .value_kind:     hidden_global_offset_y
      - .offset:         296
        .size:           8
        .value_kind:     hidden_global_offset_z
      - .offset:         304
        .size:           2
        .value_kind:     hidden_grid_dims
      - .offset:         360
        .size:           4
        .value_kind:     hidden_dynamic_lds_size
    .group_segment_fixed_size: 0
    .kernarg_segment_align: 8
    .kernarg_segment_size: 496
    .language:       OpenCL C
    .language_version:
      - 2
      - 0
    .max_flat_workgroup_size: 512
    .name:           _Z9trunk_fwd4Args
    .private_segment_fixed_size: 0
    .sgpr_count:     106
    .sgpr_spill_count: 289
    .symbol:         _Z9trunk_fwd4Args.kd
    .uniform_work_group_size: 1
    .uses_dynamic_stack: false
    .vgpr_count:     256
    .vgpr_spill_count: 0
    .wavefront_size: 64
